# wave_sum butterflies: ds_bpermute hops (one LDS round trip + lgkmcnt(0) each) replaced by DPP quad_perm/row_half_mirror/row_mirror and v_permlane16/32_swap adds (275 of 308 sites, gMLP LayerNorm stats
# speedup vs baseline: 1.0090x; 1.0032x over previous
; __device__ __forceinline__ unsigned pk2(float lo, float hi) { return f2bf(lo) | (f2bf(hi) << 16); }
; __device__ __forceinline__ float wave_sum(float v) {
; #pragma unroll
;     for (int o = 1; o < 64; o <<= 1) v += __shfl_xor(v, o);
;     return v;
; __global__ void __launch_bounds__(512, 2) mega(Params p) {
;     ...
;               const float4* xr = (const float4*)(l == 0 ? (row < TL ? p.in[0] + (size_t)row * DM : p.in[2] + (size_t)(row - TL) * DM) : X + (size_t)row * DM) + lane; float4 v[8]; float ss = 0.f;
; #pragma unroll
;               for (int j = 0; j < 8; ++j) { v[j] = xr[64 * j]; ss += v[j].x * v[j].x + v[j].y * v[j].y + v[j].z * v[j].z + v[j].w * v[j].w; }
;               const float r = rsqrtf(wave_sum(ss) * (1.f / DM) + EPS);
;               const float* md = mod + (row >= TL ? 6144 : 0);
;               uint2* hp = (uint2*)(H + (size_t)row * DM) + lane;
; #pragma unroll
;               for (int j = 0; j < 8; ++j) { const int col = 4 * (lane + 64 * j); const float4 w4 = *(const float4*)(nw + col), sc = *(const float4*)(md + 2048 + col), sh = *(const float4*)(md + col);
;                   uint2 o; o.x = pk2(v[j].x * r * w4.x * (1.f + sc.x) + sh.x, v[j].y * r * w4.y * (1.f + sc.y) + sh.y);
;                   o.y = pk2(v[j].z * r * w4.z * (1.f + sc.z) + sh.z, v[j].w * r * w4.w * (1.f + sc.w) + sh.w); hp[64 * j] = o; } } }
.LBB0_47:
	v_lshl_add_u64 v[0:1], v[0:1], 0, v[164:165]
	global_load_dwordx4 v[28:31], v[0:1], off
	global_load_dwordx4 v[24:27], v[0:1], off offset:1024
	global_load_dwordx4 v[20:23], v[0:1], off offset:2048
	global_load_dwordx4 v[16:19], v[0:1], off offset:3072
	v_add_co_u32_e32 v0, vcc, s47, v0
	v_mov_b32_e32 v49, 0x6000
	s_nop 0
	v_addc_co_u32_e32 v1, vcc, 0, v1, vcc
	global_load_dwordx4 v[12:15], v[0:1], off
	global_load_dwordx4 v[8:11], v[0:1], off offset:1024
	global_load_dwordx4 v[4:7], v[0:1], off offset:2048
	s_nop 0
	global_load_dwordx4 v[0:3], v[0:1], off offset:3072
	s_nop 0
	global_load_dwordx4 v[78:81], v[34:35], off
	v_cmp_lt_i32_e32 vcc, s11, v44
	v_readlane_b32 s0, v254, 57
	v_mov_b32_e32 v67, v165
	v_cndmask_b32_e32 v66, 0, v49, vcc
	v_readlane_b32 s1, v254, 58
	v_mov_b32_e32 v49, v165
	v_lshlrev_b64 v[64:65], 12, v[64:65]
	v_lshl_add_u64 v[66:67], s[0:1], 0, v[66:67]
	s_mov_b64 s[0:1], 0x2000
	v_lshl_add_u64 v[68:69], v[66:67], 0, s[0:1]
	v_lshl_add_u64 v[70:71], v[68:69], 0, v[48:49]
	global_load_dwordx4 v[82:85], v[70:71], off
	v_lshl_add_u64 v[70:71], v[66:67], 0, v[48:49]
	global_load_dwordx4 v[86:89], v[70:71], off
	v_lshl_add_u64 v[64:65], v[32:33], 0, v[64:65]
	v_mov_b32_e32 v57, v165
	v_mov_b32_e32 v59, v165
	v_mov_b32_e32 v61, v165
	v_mov_b32_e32 v63, v165
	v_lshl_add_u64 v[44:45], v[44:45], 0, s[62:63]
	v_lshl_add_u64 v[46:47], v[46:47], 0, s[6:7]
	s_waitcnt vmcnt(10)
	v_mul_f32_e32 v49, v29, v29
	s_waitcnt vmcnt(9)
	v_mul_f32_e32 v51, v25, v25
	s_waitcnt vmcnt(8)
	v_mul_f32_e32 v53, v21, v21
	v_fmac_f32_e32 v49, v28, v28
	v_fmac_f32_e32 v51, v24, v24
	s_waitcnt vmcnt(7)
	v_mul_f32_e32 v55, v17, v17
	v_fmac_f32_e32 v53, v20, v20
	s_waitcnt vmcnt(6)
	v_mov_b32_e32 v92, v13
	s_waitcnt vmcnt(5)
	v_mov_b32_e32 v93, v9
	v_fmac_f32_e32 v49, v30, v30
	v_fmac_f32_e32 v51, v26, v26
	v_fmac_f32_e32 v55, v16, v16
	v_mov_b32_e32 v90, v12
	v_mov_b32_e32 v91, v8
	v_fmac_f32_e32 v53, v22, v22
	v_pk_mul_f32 v[92:93], v[92:93], v[92:93]
	v_fmac_f32_e32 v49, v31, v31
	v_fmac_f32_e32 v51, v27, v27
	v_mov_b32_e32 v94, v14
	v_mov_b32_e32 v95, v10
	s_waitcnt vmcnt(4)
	v_mov_b32_e32 v100, v5
	s_waitcnt vmcnt(3)
	v_mov_b32_e32 v101, v1
	v_fmac_f32_e32 v55, v18, v18
	v_fmac_f32_e32 v53, v23, v23
	v_pk_fma_f32 v[90:91], v[90:91], v[90:91], v[92:93]
	v_add_f32_e32 v49, v49, v51
	v_mov_b32_e32 v96, v15
	v_mov_b32_e32 v97, v11
	v_mov_b32_e32 v98, v4
	v_mov_b32_e32 v99, v0
	v_pk_mul_f32 v[100:101], v[100:101], v[100:101]
	v_fmac_f32_e32 v55, v19, v19
	v_pk_fma_f32 v[90:91], v[94:95], v[94:95], v[90:91]
	v_add_f32_e32 v49, v49, v53
	v_mov_b32_e32 v102, v6
	v_mov_b32_e32 v103, v2
	v_pk_fma_f32 v[92:93], v[98:99], v[98:99], v[100:101]
	v_pk_fma_f32 v[90:91], v[96:97], v[96:97], v[90:91]
	v_add_f32_e32 v49, v49, v55
	v_mov_b32_e32 v104, v7
	v_mov_b32_e32 v105, v3
	v_pk_fma_f32 v[92:93], v[102:103], v[102:103], v[92:93]
	v_add_f32_e32 v49, v49, v90
	v_pk_fma_f32 v[92:93], v[104:105], v[104:105], v[92:93]
	v_add_f32_e32 v49, v49, v91
	v_add_f32_e32 v49, v49, v92
	v_add_f32_e32 v49, v49, v93
	s_waitcnt vmcnt(2)
	v_mov_b32_e32 v90, v78
	v_mov_b32_e32 v91, v80
	v_mov_b32_e32 v80, v79
	v_mov_b32_e32 v78, v28
	s_waitcnt lgkmcnt(0)
	s_nop 1
	v_add_f32_dpp v49, v49, v49 quad_perm:[1,0,3,2] row_mask:0xf bank_mask:0xf
	v_mov_b32_e32 v79, v30
	v_mov_b32_e32 v30, v29
	s_waitcnt vmcnt(1)
	v_mov_b32_e32 v28, v82
	v_mov_b32_e32 v29, v84
	s_waitcnt lgkmcnt(0)
	s_nop 1
	v_add_f32_dpp v49, v49, v49 quad_perm:[2,3,0,1] row_mask:0xf bank_mask:0xf
	v_mov_b32_e32 v84, v83
	v_pk_add_f32 v[82:83], v[28:29], 1.0 op_sel_hi:[1,0]
	s_waitcnt vmcnt(0)
	v_mov_b32_e32 v93, v88
	v_mov_b32_e32 v88, v87
	s_waitcnt lgkmcnt(0)
	s_nop 1
	v_add_f32_dpp v49, v49, v49 row_half_mirror row_mask:0xf bank_mask:0xf
	v_pk_add_f32 v[84:85], v[84:85], 1.0 op_sel_hi:[1,0]
	v_mov_b32_e32 v92, v86
	v_mov_b32_e32 v51, v165
	s_waitcnt lgkmcnt(0)
	s_nop 1
	v_add_f32_dpp v49, v49, v49 row_mirror row_mask:0xf bank_mask:0xf
	s_waitcnt lgkmcnt(0)
	v_mov_b32_e32 v53, v49
	s_nop 1
	v_permlane16_swap_b32_e32 v49, v53
	v_add_f32_e32 v49, v49, v53
	s_waitcnt lgkmcnt(0)
	v_mov_b32_e32 v53, v49
	s_nop 1
	v_permlane32_swap_b32_e32 v49, v53
	v_add_f32_e32 v49, v49, v53
	v_fmamk_f32 v49, v49, 0x3a000000, v179
	v_mul_f32_e32 v53, 0x4b800000, v49
	v_cmp_gt_f32_e32 vcc, s91, v49
	s_nop 1
	v_cndmask_b32_e32 v49, v49, v53, vcc
	v_rsq_f32_e32 v49, v49
	s_nop 0
	v_mul_f32_e32 v28, 0x45800000, v49
	v_cndmask_b32_e32 v28, v49, v28, vcc
	v_pk_mul_f32 v[30:31], v[28:29], v[30:31] op_sel_hi:[0,1]
	v_pk_mul_f32 v[78:79], v[28:29], v[78:79] op_sel_hi:[0,1]
	v_pk_mul_f32 v[30:31], v[80:81], v[30:31]
	v_pk_mul_f32 v[78:79], v[90:91], v[78:79]
	v_pk_fma_f32 v[30:31], v[84:85], v[30:31], v[88:89]
	v_pk_fma_f32 v[78:79], v[82:83], v[78:79], v[92:93]
	v_and_b32_sdwa v53, v31, v180 dst_sel:DWORD dst_unused:UNUSED_PAD src0_sel:WORD_1 src1_sel:DWORD
	v_and_b32_sdwa v55, v30, v180 dst_sel:DWORD dst_unused:UNUSED_PAD src0_sel:WORD_1 src1_sel:DWORD
	v_and_b32_sdwa v29, v79, v180 dst_sel:DWORD dst_unused:UNUSED_PAD src0_sel:WORD_1 src1_sel:DWORD
	v_and_b32_sdwa v49, v78, v180 dst_sel:DWORD dst_unused:UNUSED_PAD src0_sel:WORD_1 src1_sel:DWORD
	v_add3_u32 v31, v31, v53, s3
	v_add3_u32 v30, v30, v55, s3
	v_add3_u32 v49, v78, v49, s3
	v_add3_u32 v29, v79, v29, s3
	v_and_b32_e32 v31, 0xffff0000, v31
	v_and_b32_e32 v30, 0xffff0000, v30
	v_or_b32_sdwa v31, v31, v29 dst_sel:DWORD dst_unused:UNUSED_PAD src0_sel:DWORD src1_sel:WORD_1
	v_or_b32_sdwa v30, v30, v49 dst_sel:DWORD dst_unused:UNUSED_PAD src0_sel:DWORD src1_sel:WORD_1
	global_store_dwordx2 v[64:65], v[30:31], off
	global_load_dwordx4 v[78:81], v[34:35], off offset:1024
	v_lshl_add_u64 v[30:31], v[68:69], 0, v[50:51]
	global_load_dwordx4 v[82:85], v[30:31], off
	global_load_dwordx4 v[86:89], v[70:71], off offset:1024
	v_mov_b32_e32 v30, v24
	v_mov_b32_e32 v31, v26
	v_mov_b32_e32 v26, v25
	v_pk_mul_f32 v[24:25], v[28:29], v[30:31] op_sel_hi:[0,1]
	v_pk_mul_f32 v[26:27], v[28:29], v[26:27] op_sel_hi:[0,1]
	v_mov_b32_e32 v53, v165
	v_mov_b32_e32 v55, v165
	v_cmp_lt_i32_e32 vcc, s4, v44
	s_or_b64 s[40:41], vcc, s[40:41]
	s_waitcnt vmcnt(2)
; __device__ __forceinline__ unsigned pk2(float lo, float hi) { return f2bf(lo) | (f2bf(hi) << 16); }
; __global__ void __launch_bounds__(512, 2) mega(Params p) {
;     ...
; #pragma unroll
;               for (int j = 0; j < 8; ++j) { const int col = 4 * (lane + 64 * j); const float4 w4 = *(const float4*)(nw + col), sc = *(const float4*)(md + 2048 + col), sh = *(const float4*)(md + col);
;                   uint2 o; o.x = pk2(v[j].x * r * w4.x * (1.f + sc.x) + sh.x, v[j].y * r * w4.y * (1.f + sc.y) + sh.y);
;                   o.y = pk2(v[j].z * r * w4.z * (1.f + sc.z) + sh.z, v[j].w * r * w4.w * (1.f + sc.w) + sh.w); hp[64 * j] = o; } } }
	v_mov_b32_e32 v31, v80
	s_waitcnt vmcnt(1)
	v_mov_b32_e32 v91, v84
	v_mov_b32_e32 v80, v79
	v_mov_b32_e32 v84, v83
	v_mov_b32_e32 v30, v78
	v_mov_b32_e32 v90, v82
	s_waitcnt vmcnt(0)
	v_mov_b32_e32 v93, v88
	v_mov_b32_e32 v88, v87
	v_pk_mul_f32 v[26:27], v[80:81], v[26:27]
	v_pk_add_f32 v[78:79], v[84:85], 1.0 op_sel_hi:[1,0]
	v_mov_b32_e32 v92, v86
	v_pk_mul_f32 v[24:25], v[30:31], v[24:25]
	v_pk_add_f32 v[30:31], v[90:91], 1.0 op_sel_hi:[1,0]
	v_pk_fma_f32 v[26:27], v[78:79], v[26:27], v[88:89]
	v_pk_fma_f32 v[24:25], v[30:31], v[24:25], v[92:93]
	v_and_b32_sdwa v31, v27, v180 dst_sel:DWORD dst_unused:UNUSED_PAD src0_sel:WORD_1 src1_sel:DWORD
	v_and_b32_sdwa v49, v26, v180 dst_sel:DWORD dst_unused:UNUSED_PAD src0_sel:WORD_1 src1_sel:DWORD
	v_and_b32_sdwa v29, v25, v180 dst_sel:DWORD dst_unused:UNUSED_PAD src0_sel:WORD_1 src1_sel:DWORD
	v_and_b32_sdwa v30, v24, v180 dst_sel:DWORD dst_unused:UNUSED_PAD src0_sel:WORD_1 src1_sel:DWORD
	v_add3_u32 v27, v27, v31, s3
	v_add3_u32 v26, v26, v49, s3
	v_add3_u32 v24, v24, v30, s3
	v_add3_u32 v25, v25, v29, s3
	v_and_b32_e32 v27, 0xffff0000, v27
	v_and_b32_e32 v26, 0xffff0000, v26
	v_or_b32_sdwa v25, v27, v25 dst_sel:DWORD dst_unused:UNUSED_PAD src0_sel:DWORD src1_sel:WORD_1
	v_or_b32_sdwa v24, v26, v24 dst_sel:DWORD dst_unused:UNUSED_PAD src0_sel:DWORD src1_sel:WORD_1
	global_store_dwordx2 v[64:65], v[24:25], off offset:512
	global_load_dwordx4 v[24:27], v[34:35], off offset:2048
	v_lshl_add_u64 v[30:31], v[68:69], 0, v[52:53]
	global_load_dwordx4 v[78:81], v[30:31], off
	global_load_dwordx4 v[82:85], v[70:71], off offset:2048
	v_mov_b32_e32 v30, v20
	v_mov_b32_e32 v31, v22
	v_mov_b32_e32 v22, v21
	v_pk_mul_f32 v[20:21], v[28:29], v[30:31] op_sel_hi:[0,1]
	v_pk_mul_f32 v[22:23], v[28:29], v[22:23] op_sel_hi:[0,1]
	s_waitcnt vmcnt(2)
	v_mov_b32_e32 v31, v26
	s_waitcnt vmcnt(1)
	v_mov_b32_e32 v87, v80
	v_mov_b32_e32 v26, v25
	v_mov_b32_e32 v80, v79
	v_mov_b32_e32 v30, v24
	v_mov_b32_e32 v86, v78
	s_waitcnt vmcnt(0)
	v_mov_b32_e32 v89, v84
	v_mov_b32_e32 v84, v83
	v_pk_mul_f32 v[22:23], v[26:27], v[22:23]
	v_pk_add_f32 v[26:27], v[80:81], 1.0 op_sel_hi:[1,0]
	v_mov_b32_e32 v88, v82
	v_pk_mul_f32 v[20:21], v[30:31], v[20:21]
	v_pk_add_f32 v[24:25], v[86:87], 1.0 op_sel_hi:[1,0]
	v_pk_fma_f32 v[22:23], v[26:27], v[22:23], v[84:85]
	v_pk_fma_f32 v[20:21], v[24:25], v[20:21], v[88:89]
	v_and_b32_sdwa v26, v23, v180 dst_sel:DWORD dst_unused:UNUSED_PAD src0_sel:WORD_1 src1_sel:DWORD
	v_and_b32_sdwa v27, v22, v180 dst_sel:DWORD dst_unused:UNUSED_PAD src0_sel:WORD_1 src1_sel:DWORD
	v_and_b32_sdwa v24, v21, v180 dst_sel:DWORD dst_unused:UNUSED_PAD src0_sel:WORD_1 src1_sel:DWORD
	v_and_b32_sdwa v25, v20, v180 dst_sel:DWORD dst_unused:UNUSED_PAD src0_sel:WORD_1 src1_sel:DWORD
	v_add3_u32 v23, v23, v26, s3
	v_add3_u32 v22, v22, v27, s3
	v_add3_u32 v20, v20, v25, s3
	v_add3_u32 v21, v21, v24, s3
	v_and_b32_e32 v23, 0xffff0000, v23
	v_and_b32_e32 v22, 0xffff0000, v22
	v_or_b32_sdwa v21, v23, v21 dst_sel:DWORD dst_unused:UNUSED_PAD src0_sel:DWORD src1_sel:WORD_1
	v_or_b32_sdwa v20, v22, v20 dst_sel:DWORD dst_unused:UNUSED_PAD src0_sel:DWORD src1_sel:WORD_1
	global_store_dwordx2 v[64:65], v[20:21], off offset:1024
	global_load_dwordx4 v[20:23], v[34:35], off offset:3072
	v_lshl_add_u64 v[24:25], v[68:69], 0, v[54:55]
	global_load_dwordx4 v[24:27], v[24:25], off
	s_nop 0
	global_load_dwordx4 v[78:81], v[70:71], off offset:3072
	v_mov_b32_e32 v30, v16
	v_mov_b32_e32 v31, v18
	v_mov_b32_e32 v18, v17
	v_pk_mul_f32 v[16:17], v[28:29], v[30:31] op_sel_hi:[0,1]
	v_pk_mul_f32 v[18:19], v[28:29], v[18:19] op_sel_hi:[0,1]
	s_waitcnt vmcnt(2)
	v_mov_b32_e32 v31, v22
	s_waitcnt vmcnt(1)
	v_mov_b32_e32 v71, v26
	v_mov_b32_e32 v22, v21
	v_mov_b32_e32 v26, v25
	v_mov_b32_e32 v30, v20
	v_mov_b32_e32 v70, v24
	s_waitcnt vmcnt(0)
	v_mov_b32_e32 v83, v80
	v_mov_b32_e32 v80, v79
	v_pk_mul_f32 v[18:19], v[22:23], v[18:19]
	v_pk_add_f32 v[22:23], v[26:27], 1.0 op_sel_hi:[1,0]
	v_mov_b32_e32 v82, v78
	v_pk_mul_f32 v[16:17], v[30:31], v[16:17]
	v_pk_add_f32 v[20:21], v[70:71], 1.0 op_sel_hi:[1,0]
	v_pk_fma_f32 v[18:19], v[22:23], v[18:19], v[80:81]
	v_pk_fma_f32 v[16:17], v[20:21], v[16:17], v[82:83]
	v_and_b32_sdwa v22, v19, v180 dst_sel:DWORD dst_unused:UNUSED_PAD src0_sel:WORD_1 src1_sel:DWORD
	v_and_b32_sdwa v23, v18, v180 dst_sel:DWORD dst_unused:UNUSED_PAD src0_sel:WORD_1 src1_sel:DWORD
	v_and_b32_sdwa v20, v17, v180 dst_sel:DWORD dst_unused:UNUSED_PAD src0_sel:WORD_1 src1_sel:DWORD
	v_and_b32_sdwa v21, v16, v180 dst_sel:DWORD dst_unused:UNUSED_PAD src0_sel:WORD_1 src1_sel:DWORD
	v_add3_u32 v19, v19, v22, s3
	v_add3_u32 v18, v18, v23, s3
	v_add3_u32 v16, v16, v21, s3
	v_add3_u32 v17, v17, v20, s3
	v_and_b32_e32 v19, 0xffff0000, v19
	v_and_b32_e32 v18, 0xffff0000, v18
	v_or_b32_sdwa v17, v19, v17 dst_sel:DWORD dst_unused:UNUSED_PAD src0_sel:DWORD src1_sel:WORD_1
	v_or_b32_sdwa v16, v18, v16 dst_sel:DWORD dst_unused:UNUSED_PAD src0_sel:DWORD src1_sel:WORD_1
	global_store_dwordx2 v[64:65], v[16:17], off offset:1536
	v_lshl_add_u64 v[20:21], v[68:69], 0, v[56:57]
	global_load_dwordx4 v[16:19], v[36:37], off
	v_lshl_add_u64 v[24:25], v[66:67], 0, v[56:57]
	global_load_dwordx4 v[20:23], v[20:21], off
	v_mov_b32_e32 v30, v12
	global_load_dwordx4 v[24:27], v[24:25], off
	v_mov_b32_e32 v31, v14
	v_mov_b32_e32 v12, v13
	v_mov_b32_e32 v13, v15
	v_pk_mul_f32 v[14:15], v[28:29], v[30:31] op_sel_hi:[0,1]
	v_pk_mul_f32 v[12:13], v[28:29], v[12:13] op_sel_hi:[0,1]
	s_waitcnt vmcnt(2)
	v_mov_b32_e32 v31, v18
	v_mov_b32_e32 v18, v17
	s_waitcnt vmcnt(1)
	v_mov_b32_e32 v71, v22
	v_mov_b32_e32 v22, v21
	v_mov_b32_e32 v30, v16
	v_mov_b32_e32 v70, v20
	s_waitcnt vmcnt(0)
; __device__ __forceinline__ unsigned pk2(float lo, float hi) { return f2bf(lo) | (f2bf(hi) << 16); }
; __global__ void __launch_bounds__(512, 2) mega(Params p) {
;     ...
; #pragma unroll
;               for (int j = 0; j < 8; ++j) { const int col = 4 * (lane + 64 * j); const float4 w4 = *(const float4*)(nw + col), sc = *(const float4*)(md + 2048 + col), sh = *(const float4*)(md + col);
;                   uint2 o; o.x = pk2(v[j].x * r * w4.x * (1.f + sc.x) + sh.x, v[j].y * r * w4.y * (1.f + sc.y) + sh.y);
;                   o.y = pk2(v[j].z * r * w4.z * (1.f + sc.z) + sh.z, v[j].w * r * w4.w * (1.f + sc.w) + sh.w); hp[64 * j] = o; } } }
	v_mov_b32_e32 v79, v26
	v_mov_b32_e32 v26, v25
	v_pk_mul_f32 v[12:13], v[18:19], v[12:13]
	v_pk_add_f32 v[18:19], v[22:23], 1.0 op_sel_hi:[1,0]
	v_mov_b32_e32 v78, v24
	v_pk_mul_f32 v[14:15], v[30:31], v[14:15]
	v_pk_add_f32 v[16:17], v[70:71], 1.0 op_sel_hi:[1,0]
	v_pk_fma_f32 v[12:13], v[18:19], v[12:13], v[26:27]
	v_pk_fma_f32 v[14:15], v[16:17], v[14:15], v[78:79]
	v_and_b32_sdwa v18, v13, v180 dst_sel:DWORD dst_unused:UNUSED_PAD src0_sel:WORD_1 src1_sel:DWORD
	v_and_b32_sdwa v19, v12, v180 dst_sel:DWORD dst_unused:UNUSED_PAD src0_sel:WORD_1 src1_sel:DWORD
	v_and_b32_sdwa v16, v15, v180 dst_sel:DWORD dst_unused:UNUSED_PAD src0_sel:WORD_1 src1_sel:DWORD
	v_and_b32_sdwa v17, v14, v180 dst_sel:DWORD dst_unused:UNUSED_PAD src0_sel:WORD_1 src1_sel:DWORD
	v_add3_u32 v13, v13, v18, s3
	v_add3_u32 v12, v12, v19, s3
	v_add3_u32 v14, v14, v17, s3
	v_add3_u32 v15, v15, v16, s3
	v_and_b32_e32 v13, 0xffff0000, v13
	v_and_b32_e32 v12, 0xffff0000, v12
	v_or_b32_sdwa v13, v13, v15 dst_sel:DWORD dst_unused:UNUSED_PAD src0_sel:DWORD src1_sel:WORD_1
	v_or_b32_sdwa v12, v12, v14 dst_sel:DWORD dst_unused:UNUSED_PAD src0_sel:DWORD src1_sel:WORD_1
	global_store_dwordx2 v[64:65], v[12:13], off offset:2048
	v_lshl_add_u64 v[16:17], v[68:69], 0, v[58:59]
	global_load_dwordx4 v[12:15], v[38:39], off
	v_lshl_add_u64 v[20:21], v[66:67], 0, v[58:59]
	global_load_dwordx4 v[16:19], v[16:17], off
	v_mov_b32_e32 v24, v8
	global_load_dwordx4 v[20:23], v[20:21], off
	v_mov_b32_e32 v25, v10
	v_mov_b32_e32 v10, v9
	v_pk_mul_f32 v[8:9], v[28:29], v[24:25] op_sel_hi:[0,1]
	v_pk_mul_f32 v[10:11], v[28:29], v[10:11] op_sel_hi:[0,1]
	s_waitcnt vmcnt(2)
	v_mov_b32_e32 v25, v14
	v_mov_b32_e32 v14, v13
	s_waitcnt vmcnt(1)
	v_mov_b32_e32 v27, v18
	v_mov_b32_e32 v18, v17
	v_mov_b32_e32 v24, v12
	v_mov_b32_e32 v26, v16
	s_waitcnt vmcnt(0)
	v_mov_b32_e32 v31, v22
	v_mov_b32_e32 v22, v21
	v_pk_mul_f32 v[10:11], v[14:15], v[10:11]
	v_pk_add_f32 v[14:15], v[18:19], 1.0 op_sel_hi:[1,0]
	v_mov_b32_e32 v30, v20
	v_pk_mul_f32 v[8:9], v[24:25], v[8:9]
	v_pk_add_f32 v[12:13], v[26:27], 1.0 op_sel_hi:[1,0]
	v_pk_fma_f32 v[10:11], v[14:15], v[10:11], v[22:23]
	v_pk_fma_f32 v[8:9], v[12:13], v[8:9], v[30:31]
	v_and_b32_sdwa v14, v11, v180 dst_sel:DWORD dst_unused:UNUSED_PAD src0_sel:WORD_1 src1_sel:DWORD
	v_and_b32_sdwa v15, v10, v180 dst_sel:DWORD dst_unused:UNUSED_PAD src0_sel:WORD_1 src1_sel:DWORD
	v_and_b32_sdwa v12, v9, v180 dst_sel:DWORD dst_unused:UNUSED_PAD src0_sel:WORD_1 src1_sel:DWORD
	v_and_b32_sdwa v13, v8, v180 dst_sel:DWORD dst_unused:UNUSED_PAD src0_sel:WORD_1 src1_sel:DWORD
	v_add3_u32 v11, v11, v14, s3
	v_add3_u32 v10, v10, v15, s3
	v_add3_u32 v8, v8, v13, s3
	v_add3_u32 v9, v9, v12, s3
	v_and_b32_e32 v11, 0xffff0000, v11
	v_and_b32_e32 v10, 0xffff0000, v10
	v_or_b32_sdwa v9, v11, v9 dst_sel:DWORD dst_unused:UNUSED_PAD src0_sel:DWORD src1_sel:WORD_1
	v_or_b32_sdwa v8, v10, v8 dst_sel:DWORD dst_unused:UNUSED_PAD src0_sel:DWORD src1_sel:WORD_1
	global_store_dwordx2 v[64:65], v[8:9], off offset:2560
	v_lshl_add_u64 v[12:13], v[68:69], 0, v[60:61]
	global_load_dwordx4 v[8:11], v[40:41], off
	v_lshl_add_u64 v[16:17], v[66:67], 0, v[60:61]
	global_load_dwordx4 v[12:15], v[12:13], off
	v_mov_b32_e32 v20, v4
	global_load_dwordx4 v[16:19], v[16:17], off
	v_mov_b32_e32 v21, v6
	v_mov_b32_e32 v4, v5
	v_mov_b32_e32 v5, v7
	v_pk_mul_f32 v[6:7], v[28:29], v[20:21] op_sel_hi:[0,1]
	v_pk_mul_f32 v[4:5], v[28:29], v[4:5] op_sel_hi:[0,1]
	s_waitcnt vmcnt(2)
	v_mov_b32_e32 v21, v10
	v_mov_b32_e32 v10, v9
	s_waitcnt vmcnt(1)
	v_mov_b32_e32 v23, v14
	v_mov_b32_e32 v14, v13
	v_mov_b32_e32 v20, v8
	v_mov_b32_e32 v22, v12
	s_waitcnt vmcnt(0)
	v_mov_b32_e32 v25, v18
	v_mov_b32_e32 v18, v17
	v_pk_mul_f32 v[4:5], v[10:11], v[4:5]
	v_pk_add_f32 v[10:11], v[14:15], 1.0 op_sel_hi:[1,0]
	v_mov_b32_e32 v24, v16
	v_pk_mul_f32 v[6:7], v[20:21], v[6:7]
	v_pk_add_f32 v[8:9], v[22:23], 1.0 op_sel_hi:[1,0]
	v_pk_fma_f32 v[4:5], v[10:11], v[4:5], v[18:19]
	v_pk_fma_f32 v[6:7], v[8:9], v[6:7], v[24:25]
	v_and_b32_sdwa v10, v5, v180 dst_sel:DWORD dst_unused:UNUSED_PAD src0_sel:WORD_1 src1_sel:DWORD
	v_and_b32_sdwa v11, v4, v180 dst_sel:DWORD dst_unused:UNUSED_PAD src0_sel:WORD_1 src1_sel:DWORD
	v_and_b32_sdwa v8, v7, v180 dst_sel:DWORD dst_unused:UNUSED_PAD src0_sel:WORD_1 src1_sel:DWORD
	v_and_b32_sdwa v9, v6, v180 dst_sel:DWORD dst_unused:UNUSED_PAD src0_sel:WORD_1 src1_sel:DWORD
	v_add3_u32 v5, v5, v10, s3
	v_add3_u32 v4, v4, v11, s3
	v_add3_u32 v6, v6, v9, s3
	v_add3_u32 v7, v7, v8, s3
	v_and_b32_e32 v5, 0xffff0000, v5
	v_and_b32_e32 v4, 0xffff0000, v4
	v_or_b32_sdwa v5, v5, v7 dst_sel:DWORD dst_unused:UNUSED_PAD src0_sel:DWORD src1_sel:WORD_1
	v_or_b32_sdwa v4, v4, v6 dst_sel:DWORD dst_unused:UNUSED_PAD src0_sel:DWORD src1_sel:WORD_1
	global_store_dwordx2 v[64:65], v[4:5], off offset:3072
	v_lshl_add_u64 v[8:9], v[68:69], 0, v[62:63]
	global_load_dwordx4 v[4:7], v[42:43], off
	v_lshl_add_u64 v[12:13], v[66:67], 0, v[62:63]
	global_load_dwordx4 v[8:11], v[8:9], off
	v_mov_b32_e32 v16, v0
	global_load_dwordx4 v[12:15], v[12:13], off
	v_mov_b32_e32 v17, v2
	v_mov_b32_e32 v2, v1
	v_pk_mul_f32 v[0:1], v[28:29], v[16:17] op_sel_hi:[0,1]
	v_pk_mul_f32 v[2:3], v[28:29], v[2:3] op_sel_hi:[0,1]
	s_waitcnt vmcnt(2)
	v_mov_b32_e32 v17, v6
	v_mov_b32_e32 v6, v5
	s_waitcnt vmcnt(1)
	v_mov_b32_e32 v19, v10
	v_mov_b32_e32 v10, v9
	v_mov_b32_e32 v16, v4
	v_mov_b32_e32 v18, v8
	s_waitcnt vmcnt(0)
	v_mov_b32_e32 v21, v14
	v_mov_b32_e32 v14, v13
	v_pk_mul_f32 v[2:3], v[6:7], v[2:3]
	v_pk_add_f32 v[6:7], v[10:11], 1.0 op_sel_hi:[1,0]
	v_mov_b32_e32 v20, v12
	v_pk_mul_f32 v[0:1], v[16:17], v[0:1]
	v_pk_add_f32 v[4:5], v[18:19], 1.0 op_sel_hi:[1,0]
	v_pk_fma_f32 v[2:3], v[6:7], v[2:3], v[14:15]
	v_pk_fma_f32 v[0:1], v[4:5], v[0:1], v[20:21]
	v_and_b32_sdwa v6, v3, v180 dst_sel:DWORD dst_unused:UNUSED_PAD src0_sel:WORD_1 src1_sel:DWORD
	v_and_b32_sdwa v7, v2, v180 dst_sel:DWORD dst_unused:UNUSED_PAD src0_sel:WORD_1 src1_sel:DWORD
	v_and_b32_sdwa v4, v1, v180 dst_sel:DWORD dst_unused:UNUSED_PAD src0_sel:WORD_1 src1_sel:DWORD
	v_and_b32_sdwa v5, v0, v180 dst_sel:DWORD dst_unused:UNUSED_PAD src0_sel:WORD_1 src1_sel:DWORD
	v_add3_u32 v3, v3, v6, s3
	v_add3_u32 v2, v2, v7, s3
	v_add3_u32 v0, v0, v5, s3
	v_add3_u32 v1, v1, v4, s3
	v_and_b32_e32 v3, 0xffff0000, v3
	v_and_b32_e32 v2, 0xffff0000, v2
	v_or_b32_sdwa v1, v3, v1 dst_sel:DWORD dst_unused:UNUSED_PAD src0_sel:DWORD src1_sel:WORD_1
	v_or_b32_sdwa v0, v2, v0 dst_sel:DWORD dst_unused:UNUSED_PAD src0_sel:DWORD src1_sel:WORD_1
	global_store_dwordx2 v[64:65], v[0:1], off offset:3584
	s_andn2_b64 exec, exec, s[40:41]
	s_cbranch_execz .LBB0_54

; __device__ __forceinline__ void gmlp_item(const u16* P, const float* lnw, const float* lnb, const float* wsl  , const float* bsl  , u16* Y, int c, int h, LAS unsigned char* L, int tid) {
;     ...
;     float4 wreg[8]; uint4 srow[16], vch[4], uu[4], zz[4];
;     { const float* wg = wsl + (size_t)h * 16384;
; #pragma unroll
;       for (int i = 0; i < 8; ++i) { const int idx = tid + 512 * i; wreg[i] = *(const float4*)(wg + (idx >> 5) * 128 + (idx & 31) * 4); } }
; #pragma unroll
;     for (int rr = 0; rr < 16; ++rr) srow[rr] = *(const uint4*)(P + (size_t)(R0 + 16 * w + rr) * PST + C_AV + lane * 8);
; #pragma unroll
;     for (int i = 0; i < 4; ++i) { const int idx = tid + 512 * i; vch[i] = *(const uint4*)(P + (size_t)(R0 + (idx >> 4)) * PST + C_AV + h * 128 + (idx & 15) * 8); }
.LBB0_348:
	s_and_b64 vcc, exec, s[0:1]
	s_cbranch_vccz .LBB0_339
	s_and_b32 s18, s17, 3
	s_lshl_b32 s0, s18, 16
	v_lshlrev_b32_e32 v2, 2, v140
	s_add_u32 s0, s13, s0
	v_and_b32_e32 v155, 0x7c, v2
	s_addc_u32 s1, s16, 0
	v_lshlrev_b32_e32 v164, 2, v155
	v_and_b32_e32 v2, 0xffffff80, v2
	v_lshl_add_u64 v[0:1], s[0:1], 0, v[164:165]
	v_ashrrev_i32_e32 v3, 31, v2
	v_add_u32_e32 v6, 0x800, v2
	v_lshl_add_u64 v[4:5], v[2:3], 2, v[0:1]
	v_ashrrev_i32_e32 v7, 31, v6
	v_lshl_add_u64 v[6:7], v[6:7], 2, v[0:1]
	global_load_dwordx4 v[76:79], v[4:5], off
	global_load_dwordx4 v[72:75], v[6:7], off
	v_add_u32_e32 v4, 0x1000, v2
	v_ashrrev_i32_e32 v5, 31, v4
	v_add_u32_e32 v6, 0x1800, v2
	v_lshl_add_u64 v[4:5], v[4:5], 2, v[0:1]
	v_ashrrev_i32_e32 v7, 31, v6
	v_lshl_add_u64 v[6:7], v[6:7], 2, v[0:1]
	global_load_dwordx4 v[68:71], v[4:5], off
	global_load_dwordx4 v[64:67], v[6:7], off
	v_add_u32_e32 v4, 0x2000, v2
	v_ashrrev_i32_e32 v5, 31, v4
	v_add_u32_e32 v6, 0x2800, v2
	v_lshl_add_u64 v[4:5], v[4:5], 2, v[0:1]
	v_ashrrev_i32_e32 v7, 31, v6
	v_lshl_add_u64 v[6:7], v[6:7], 2, v[0:1]
	global_load_dwordx4 v[24:27], v[4:5], off
	global_load_dwordx4 v[20:23], v[6:7], off
	v_add_u32_e32 v4, 0x3000, v2
	v_ashrrev_i32_e32 v152, 6, v140
	v_ashrrev_i32_e32 v5, 31, v4
	v_add_u32_e32 v2, 0x3800, v2
	s_lshl_b32 s0, s17, 5
	v_lshl_add_u64 v[4:5], v[4:5], 2, v[0:1]
	v_ashrrev_i32_e32 v3, 31, v2
	s_and_b32 s19, s0, 0xffffff80
	v_lshlrev_b32_e32 v174, 4, v152
	v_lshl_add_u64 v[0:1], v[2:3], 2, v[0:1]
	global_load_dwordx4 v[16:19], v[4:5], off
	global_load_dwordx4 v[12:15], v[0:1], off
	v_and_b32_e32 v166, 63, v140
	v_add_u32_e32 v4, s19, v174
	v_mov_b64_e32 v[32:33], s[78:79]
	v_mad_i64_i32 v[0:1], s[0:1], v4, s93, v[32:33]
	v_lshlrev_b32_e32 v164, 4, v166
	v_or_b32_e32 v2, 1, v4
	v_lshl_add_u64 v[0:1], v[0:1], 0, v[164:165]
	v_mad_i64_i32 v[2:3], s[0:1], v2, s93, v[32:33]
	v_lshl_add_u64 v[2:3], v[2:3], 0, v[164:165]
	global_load_dwordx4 v[36:39], v[0:1], off offset:1024
	global_load_dwordx4 v[136:139], v[2:3], off offset:1024
	v_or_b32_e32 v0, 2, v4
	v_or_b32_e32 v2, 3, v4
	v_mad_i64_i32 v[0:1], s[0:1], v0, s93, v[32:33]
	v_mad_i64_i32 v[2:3], s[0:1], v2, s93, v[32:33]
	v_lshl_add_u64 v[0:1], v[0:1], 0, v[164:165]
	v_lshl_add_u64 v[2:3], v[2:3], 0, v[164:165]
	global_load_dwordx4 v[132:135], v[0:1], off offset:1024
	global_load_dwordx4 v[128:131], v[2:3], off offset:1024
	v_or_b32_e32 v0, 4, v4
	v_or_b32_e32 v2, 5, v4
	v_mad_i64_i32 v[0:1], s[0:1], v0, s93, v[32:33]
	v_mad_i64_i32 v[2:3], s[0:1], v2, s93, v[32:33]
	v_lshl_add_u64 v[0:1], v[0:1], 0, v[164:165]
	v_lshl_add_u64 v[2:3], v[2:3], 0, v[164:165]
	global_load_dwordx4 v[124:127], v[0:1], off offset:1024
	global_load_dwordx4 v[120:123], v[2:3], off offset:1024
	v_or_b32_e32 v0, 6, v4
	v_or_b32_e32 v2, 7, v4
	v_mad_i64_i32 v[0:1], s[0:1], v0, s93, v[32:33]
	v_mad_i64_i32 v[2:3], s[0:1], v2, s93, v[32:33]
	v_lshl_add_u64 v[0:1], v[0:1], 0, v[164:165]
	v_lshl_add_u64 v[2:3], v[2:3], 0, v[164:165]
	global_load_dwordx4 v[116:119], v[0:1], off offset:1024
	global_load_dwordx4 v[112:115], v[2:3], off offset:1024
	v_or_b32_e32 v0, 8, v4
	v_or_b32_e32 v2, 9, v4
	v_mad_i64_i32 v[0:1], s[0:1], v0, s93, v[32:33]
	v_mad_i64_i32 v[2:3], s[0:1], v2, s93, v[32:33]
	v_lshl_add_u64 v[0:1], v[0:1], 0, v[164:165]
	v_lshl_add_u64 v[2:3], v[2:3], 0, v[164:165]
	global_load_dwordx4 v[108:111], v[0:1], off offset:1024
	global_load_dwordx4 v[104:107], v[2:3], off offset:1024
	v_or_b32_e32 v0, 10, v4
	v_or_b32_e32 v2, 11, v4
	v_mad_i64_i32 v[0:1], s[0:1], v0, s93, v[32:33]
	v_mad_i64_i32 v[2:3], s[0:1], v2, s93, v[32:33]
	v_lshl_add_u64 v[0:1], v[0:1], 0, v[164:165]
	v_lshl_add_u64 v[2:3], v[2:3], 0, v[164:165]
	global_load_dwordx4 v[100:103], v[0:1], off offset:1024
	global_load_dwordx4 v[96:99], v[2:3], off offset:1024
	v_or_b32_e32 v0, 12, v4
	v_or_b32_e32 v2, 13, v4
	v_mad_i64_i32 v[0:1], s[0:1], v0, s93, v[32:33]
	v_mad_i64_i32 v[2:3], s[0:1], v2, s93, v[32:33]
	v_lshl_add_u64 v[0:1], v[0:1], 0, v[164:165]
	v_lshl_add_u64 v[2:3], v[2:3], 0, v[164:165]
	global_load_dwordx4 v[92:95], v[0:1], off offset:1024
	global_load_dwordx4 v[88:91], v[2:3], off offset:1024
	v_or_b32_e32 v0, 14, v4
	v_or_b32_e32 v2, 15, v4
	v_mad_i64_i32 v[0:1], s[0:1], v0, s93, v[32:33]
	v_mad_i64_i32 v[2:3], s[0:1], v2, s93, v[32:33]
	v_lshl_add_u64 v[0:1], v[0:1], 0, v[164:165]
	v_lshl_add_u64 v[2:3], v[2:3], 0, v[164:165]
	global_load_dwordx4 v[84:87], v[0:1], off offset:1024
	global_load_dwordx4 v[80:83], v[2:3], off offset:1024
	v_add_u32_e32 v0, s19, v149
	v_add_u32_e32 v2, s19, v148
	v_mad_i64_i32 v[0:1], s[0:1], v0, s93, v[32:33]
	s_lshl_b32 s84, s18, 8
	v_mad_i64_i32 v[2:3], s[0:1], v2, s93, v[32:33]
	v_lshl_add_u64 v[0:1], v[0:1], 0, s[84:85]
	v_lshlrev_b32_e32 v164, 1, v150
	v_lshl_add_u64 v[2:3], v[2:3], 0, s[84:85]
	v_add_u32_e32 v157, 0x400, v140
	v_add_u32_e32 v156, 0x600, v140
	v_lshl_add_u64 v[0:1], v[0:1], 0, v[164:165]
	v_lshl_add_u64 v[2:3], v[2:3], 0, v[164:165]
	v_ashrrev_i32_e32 v154, 4, v157
	s_waitcnt vmcnt(15)
; __device__ __forceinline__ float bflo(unsigned w) { return __uint_as_float(w << 16); }
; __device__ __forceinline__ float bfhi(unsigned w) { return __uint_as_float(w & 0xffff0000u); }
; __device__ __forceinline__ float wave_sum(float v) {
; #pragma unroll
;     for (int o = 1; o < 64; o <<= 1) v += __shfl_xor(v, o);
;     return v;
; __device__ __forceinline__ void gmlp_item(const u16* P, const float* lnw, const float* lnb, const float* wsl  , const float* bsl  , u16* Y, int c, int h, LAS unsigned char* L, int tid) {
;     ...
;     for (int rr = 0; rr < 16; ++rr) { const int t = 16 * w + rr; const uint4 wv = srow[rr];
;         float x[8] = {bflo(wv.x), bfhi(wv.x), bflo(wv.y), bfhi(wv.y), bflo(wv.z), bfhi(wv.z), bflo(wv.w), bfhi(wv.w)};
;         float s = 0.f;
; #pragma unroll
;         for (int i = 0; i < 8; ++i) s += x[i];
;         const float mu = wave_sum(s) * (1.f / 512.f); float s2 = 0.f;
; #pragma unroll
;         for (int i = 0; i < 8; ++i) { const float d = x[i] - mu; s2 += d * d; }
;         const float var = wave_sum(s2) * (1.f / 512.f);
;         if (lane == 0) { mean[t] = mu; rstd[t] = rsqrtf(var + EPS); } }
	v_lshlrev_b32_e32 v168, 16, v36
	v_and_b32_e32 v169, 0xffff0000, v36
	v_add_f32_e32 v36, 0, v168
	v_lshlrev_b32_e32 v175, 16, v37
	v_add_f32_e32 v36, v36, v169
	v_and_b32_e32 v181, 0xffff0000, v37
	v_add_f32_e32 v36, v36, v175
	v_lshlrev_b32_e32 v182, 16, v38
	v_add_f32_e32 v36, v36, v181
	v_and_b32_e32 v184, 0xffff0000, v38
	v_add_f32_e32 v36, v36, v182
	v_ashrrev_i32_e32 v153, 4, v156
	v_cmp_lt_i32_e32 vcc, v178, v172
	v_lshlrev_b32_e32 v185, 16, v39
	v_add_f32_e32 v36, v36, v184
	global_load_dwordx4 v[28:31], v[0:1], off offset:1024
	global_load_dwordx4 v[8:11], v[2:3], off offset:1024
	v_add_u32_e32 v0, s19, v154
	v_add_u32_e32 v2, s19, v153
	v_cndmask_b32_e32 v44, v171, v178, vcc
	v_and_b32_e32 v186, 0xffff0000, v39
	v_add_f32_e32 v36, v36, v185
	v_mad_i64_i32 v[0:1], s[0:1], v0, s93, v[32:33]
	v_mad_i64_i32 v[2:3], s[0:1], v2, s93, v[32:33]
	v_lshlrev_b32_e32 v34, 5, v140
	v_add_u32_e32 v142, s19, v144
	v_lshlrev_b32_e32 v158, 2, v44
	v_add_f32_e32 v52, v36, v186
	v_lshl_add_u64 v[0:1], v[0:1], 0, s[84:85]
	v_lshl_add_u64 v[2:3], v[2:3], 0, s[84:85]
	v_and_b32_e32 v141, 0x60, v34
	v_mad_i64_i32 v[32:33], s[0:1], v142, s93, v[32:33]
	v_lshl_add_u64 v[0:1], v[0:1], 0, v[164:165]
	v_lshl_add_u64 v[2:3], v[2:3], 0, v[164:165]
	v_lshl_add_u64 v[32:33], v[32:33], 0, s[84:85]
	v_lshlrev_b32_e32 v164, 1, v141
	v_lshl_add_u64 v[60:61], v[32:33], 0, v[164:165]
	global_load_dwordx4 v[4:7], v[0:1], off offset:1024
	s_nop 0
	global_load_dwordx4 v[0:3], v[2:3], off offset:1024
	s_nop 0
	global_load_dwordx4 v[32:35], v[60:61], off offset:48
	global_load_dwordx4 v[40:43], v[60:61], off offset:32
	global_load_dwordx4 v[48:51], v[60:61], off offset:16
	global_load_dwordx4 v[56:59], v[60:61], off
	v_cmp_lt_i32_e32 vcc, v177, v172
	global_load_dwordx4 v[36:39], v[60:61], off offset:2096
	global_load_dwordx4 v[44:47], v[60:61], off offset:2080
	v_cndmask_b32_e32 v54, v171, v177, vcc
	v_lshlrev_b32_e32 v159, 2, v54
	s_waitcnt lgkmcnt(0)
	s_nop 1
	v_add_f32_dpp v161, v52, v52 quad_perm:[1,0,3,2] row_mask:0xf bank_mask:0xf
	global_load_dwordx4 v[52:55], v[60:61], off offset:2064
	s_nop 0
	global_load_dwordx4 v[60:63], v[60:61], off offset:2048
	v_cmp_lt_i32_e32 vcc, v176, v172
	s_waitcnt lgkmcnt(0)
	s_nop 1
	v_add_f32_dpp v162, v161, v161 quad_perm:[2,3,0,1] row_mask:0xf bank_mask:0xf
	v_cndmask_b32_e32 v160, v171, v176, vcc
	v_lshlrev_b32_e32 v160, 2, v160
	v_xor_b32_e32 v161, 8, v171
	v_cmp_lt_i32_e32 vcc, v161, v172
	s_waitcnt lgkmcnt(0)
	s_nop 1
	v_add_f32_dpp v163, v162, v162 row_half_mirror row_mask:0xf bank_mask:0xf
	v_cndmask_b32_e32 v161, v171, v161, vcc
	v_lshlrev_b32_e32 v161, 2, v161
	v_xor_b32_e32 v162, 16, v171
	v_cmp_lt_i32_e32 vcc, v162, v172
	s_waitcnt lgkmcnt(0)
	s_nop 1
	v_add_f32_dpp v167, v163, v163 row_mirror row_mask:0xf bank_mask:0xf
	v_cndmask_b32_e32 v162, v171, v162, vcc
	v_lshlrev_b32_e32 v162, 2, v162
	v_xor_b32_e32 v163, 32, v171
	v_cmp_lt_i32_e32 vcc, v163, v172
	s_waitcnt lgkmcnt(0)
	v_mov_b32_e32 v187, v167
	s_nop 1
	v_permlane16_swap_b32_e32 v167, v187
	v_add_f32_e32 v167, v167, v187
	v_cndmask_b32_e32 v163, v171, v163, vcc
	v_lshlrev_b32_e32 v163, 2, v163
	v_cmp_eq_u32_e32 vcc, 0, v166
	v_lshl_add_u32 v166, v174, 2, 0
	s_waitcnt lgkmcnt(0)
	v_mov_b32_e32 v187, v167
	s_nop 1
	v_permlane32_swap_b32_e32 v167, v187
	v_add_f32_e32 v167, v167, v187
	v_fmac_f32_e32 v169, 0xbb000000, v167
	v_fmac_f32_e32 v168, 0xbb000000, v167
	v_mul_f32_e32 v169, v169, v169
	v_fmac_f32_e32 v169, v168, v168
	v_fmac_f32_e32 v175, 0xbb000000, v167
	v_fmac_f32_e32 v169, v175, v175
	v_fmac_f32_e32 v181, 0xbb000000, v167
	v_fmac_f32_e32 v169, v181, v181
	v_fmac_f32_e32 v182, 0xbb000000, v167
	v_fmac_f32_e32 v169, v182, v182
	v_fmac_f32_e32 v184, 0xbb000000, v167
	v_fmac_f32_e32 v169, v184, v184
	v_fmac_f32_e32 v185, 0xbb000000, v167
	v_fmac_f32_e32 v169, v185, v185
	v_fmac_f32_e32 v186, 0xbb000000, v167
	v_fmac_f32_e32 v169, v186, v186
	s_waitcnt lgkmcnt(0)
	s_nop 1
	v_add_f32_dpp v168, v169, v169 quad_perm:[1,0,3,2] row_mask:0xf bank_mask:0xf
	s_waitcnt lgkmcnt(0)
	s_nop 1
	v_add_f32_dpp v168, v168, v168 quad_perm:[2,3,0,1] row_mask:0xf bank_mask:0xf
	s_waitcnt lgkmcnt(0)
	s_nop 1
	v_add_f32_dpp v168, v168, v168 row_half_mirror row_mask:0xf bank_mask:0xf
	s_waitcnt lgkmcnt(0)
	s_nop 1
	v_add_f32_dpp v168, v168, v168 row_mirror row_mask:0xf bank_mask:0xf
	s_waitcnt lgkmcnt(0)
	v_mov_b32_e32 v169, v168
	s_nop 1
	v_permlane16_swap_b32_e32 v168, v169
	v_add_f32_e32 v168, v168, v169
	ds_bpermute_b32 v169, v163, v168
	s_and_saveexec_b64 s[22:23], vcc
	s_cbranch_execz .LBB0_351
	s_waitcnt lgkmcnt(0)
	v_add_f32_e32 v168, v168, v169
	v_fmamk_f32 v168, v168, 0x3b000000, v179
	v_mul_f32_e32 v169, 0x4b800000, v168
	v_cmp_gt_f32_e64 s[0:1], s91, v168
	v_mul_f32_e32 v167, 0x3b000000, v167
	s_nop 0
	v_cndmask_b32_e64 v168, v168, v169, s[0:1]
	v_rsq_f32_e32 v168, v168
	v_add_u32_e32 v169, 0x11000, v166
	ds_write_b32 v169, v167
	v_mul_f32_e32 v167, 0x45800000, v168
	v_cndmask_b32_e64 v167, v168, v167, s[0:1]
	v_add_u32_e32 v168, 0x11200, v166
	ds_write_b32 v168, v167
; __device__ __forceinline__ float bflo(unsigned w) { return __uint_as_float(w << 16); }
; __device__ __forceinline__ float bfhi(unsigned w) { return __uint_as_float(w & 0xffff0000u); }
; __device__ __forceinline__ void gmlp_item(const u16* P, const float* lnw, const float* lnb, const float* wsl  , const float* bsl  , u16* Y, int c, int h, LAS unsigned char* L, int tid) {
;     ...
;     for (int rr = 0; rr < 16; ++rr) { const int t = 16 * w + rr; const uint4 wv = srow[rr];
;         float x[8] = {bflo(wv.x), bfhi(wv.x), bflo(wv.y), bfhi(wv.y), bflo(wv.z), bfhi(wv.z), bflo(wv.w), bfhi(wv.w)};
;         float s = 0.f;
; #pragma unroll
;         for (int i = 0; i < 8; ++i) s += x[i];
;         const float mu = wave_sum(s) * (1.f / 512.f); float s2 = 0.f;
; #pragma unroll
;         for (int i = 0; i < 8; ++i) { const float d = x[i] - mu; s2 += d * d; }
;         const float var = wave_sum(s2) * (1.f / 512.f);
;         if (lane == 0) { mean[t] = mu; rstd[t] = rsqrtf(var + EPS); } }
.LBB0_351:
	s_or_b64 exec, exec, s[22:23]
	s_waitcnt vmcnt(26)
	v_lshlrev_b32_e32 v167, 16, v136
	v_and_b32_e32 v168, 0xffff0000, v136
	v_add_f32_e32 v136, 0, v167
	s_waitcnt lgkmcnt(0)
	v_lshlrev_b32_e32 v169, 16, v137
	v_add_f32_e32 v136, v136, v168
	v_and_b32_e32 v137, 0xffff0000, v137
	v_add_f32_e32 v136, v136, v169
	v_lshlrev_b32_e32 v174, 16, v138
	v_add_f32_e32 v136, v136, v137
	v_and_b32_e32 v138, 0xffff0000, v138
	v_add_f32_e32 v136, v136, v174
	v_lshlrev_b32_e32 v175, 16, v139
	v_add_f32_e32 v136, v136, v138
	v_and_b32_e32 v139, 0xffff0000, v139
	v_add_f32_e32 v136, v136, v175
	v_add_f32_e32 v136, v136, v139
	s_waitcnt lgkmcnt(0)
	s_nop 1
	v_add_f32_dpp v136, v136, v136 quad_perm:[1,0,3,2] row_mask:0xf bank_mask:0xf
	s_waitcnt lgkmcnt(0)
	s_nop 1
	v_add_f32_dpp v136, v136, v136 quad_perm:[2,3,0,1] row_mask:0xf bank_mask:0xf
	s_waitcnt lgkmcnt(0)
	s_nop 1
	v_add_f32_dpp v136, v136, v136 row_half_mirror row_mask:0xf bank_mask:0xf
	s_waitcnt lgkmcnt(0)
	s_nop 1
	v_add_f32_dpp v136, v136, v136 row_mirror row_mask:0xf bank_mask:0xf
	s_waitcnt lgkmcnt(0)
	v_mov_b32_e32 v181, v136
	s_nop 1
	v_permlane16_swap_b32_e32 v136, v181
	v_add_f32_e32 v136, v136, v181
	s_waitcnt lgkmcnt(0)
	v_mov_b32_e32 v181, v136
	s_nop 1
	v_permlane32_swap_b32_e32 v136, v181
	v_add_f32_e32 v136, v136, v181
	v_fmac_f32_e32 v168, 0xbb000000, v136
	v_fmac_f32_e32 v167, 0xbb000000, v136
	v_mul_f32_e32 v168, v168, v168
	v_fmac_f32_e32 v169, 0xbb000000, v136
	v_fmac_f32_e32 v168, v167, v167
	v_fmac_f32_e32 v137, 0xbb000000, v136
	v_fmac_f32_e32 v168, v169, v169
	v_fmac_f32_e32 v174, 0xbb000000, v136
	v_fmac_f32_e32 v168, v137, v137
	v_fmac_f32_e32 v138, 0xbb000000, v136
	v_fmac_f32_e32 v168, v174, v174
	v_fmac_f32_e32 v175, 0xbb000000, v136
	v_fmac_f32_e32 v168, v138, v138
	v_fmac_f32_e32 v168, v175, v175
	v_fmac_f32_e32 v139, 0xbb000000, v136
	v_fmac_f32_e32 v168, v139, v139
	s_waitcnt lgkmcnt(0)
	s_nop 1
	v_add_f32_dpp v137, v168, v168 quad_perm:[1,0,3,2] row_mask:0xf bank_mask:0xf
	s_waitcnt lgkmcnt(0)
	s_nop 1
	v_add_f32_dpp v137, v137, v137 quad_perm:[2,3,0,1] row_mask:0xf bank_mask:0xf
	s_waitcnt lgkmcnt(0)
	s_nop 1
	v_add_f32_dpp v137, v137, v137 row_half_mirror row_mask:0xf bank_mask:0xf
	s_waitcnt lgkmcnt(0)
	s_nop 1
	v_add_f32_dpp v137, v137, v137 row_mirror row_mask:0xf bank_mask:0xf
	s_waitcnt lgkmcnt(0)
	v_mov_b32_e32 v138, v137
	s_nop 1
	v_permlane16_swap_b32_e32 v137, v138
	v_add_f32_e32 v137, v137, v138
	ds_bpermute_b32 v138, v163, v137
	s_and_saveexec_b64 s[22:23], vcc
	s_cbranch_execz .LBB0_353
	s_waitcnt lgkmcnt(0)
	v_add_f32_e32 v137, v137, v138
	v_fmamk_f32 v137, v137, 0x3b000000, v179
	v_mul_f32_e32 v138, 0x4b800000, v137
	v_cmp_gt_f32_e64 s[0:1], s91, v137
	v_mul_f32_e32 v136, 0x3b000000, v136
	s_nop 0
	v_cndmask_b32_e64 v137, v137, v138, s[0:1]
	v_rsq_f32_e32 v137, v137
	v_add_u32_e32 v138, 0x11004, v166
	ds_write_b32 v138, v136
	v_mul_f32_e32 v136, 0x45800000, v137
	v_cndmask_b32_e64 v136, v137, v136, s[0:1]
	v_add_u32_e32 v137, 0x11204, v166
	ds_write_b32 v137, v136
.LBB0_353:
	s_or_b64 exec, exec, s[22:23]
	s_waitcnt vmcnt(25)
	v_lshlrev_b32_e32 v136, 16, v132
	v_and_b32_e32 v137, 0xffff0000, v132
	v_add_f32_e32 v132, 0, v136
	s_waitcnt lgkmcnt(0)
	v_lshlrev_b32_e32 v138, 16, v133
	v_add_f32_e32 v132, v132, v137
	v_and_b32_e32 v133, 0xffff0000, v133
	v_add_f32_e32 v132, v132, v138
	v_lshlrev_b32_e32 v139, 16, v134
	v_add_f32_e32 v132, v132, v133
	v_and_b32_e32 v134, 0xffff0000, v134
	v_add_f32_e32 v132, v132, v139
	v_lshlrev_b32_e32 v167, 16, v135
	v_add_f32_e32 v132, v132, v134
	v_and_b32_e32 v135, 0xffff0000, v135
	v_add_f32_e32 v132, v132, v167
	v_add_f32_e32 v132, v132, v135
	s_waitcnt lgkmcnt(0)
	s_nop 1
	v_add_f32_dpp v132, v132, v132 quad_perm:[1,0,3,2] row_mask:0xf bank_mask:0xf
	s_waitcnt lgkmcnt(0)
	s_nop 1
	v_add_f32_dpp v132, v132, v132 quad_perm:[2,3,0,1] row_mask:0xf bank_mask:0xf
	s_waitcnt lgkmcnt(0)
	s_nop 1
	v_add_f32_dpp v132, v132, v132 row_half_mirror row_mask:0xf bank_mask:0xf
	s_waitcnt lgkmcnt(0)
	s_nop 1
	v_add_f32_dpp v132, v132, v132 row_mirror row_mask:0xf bank_mask:0xf
	s_waitcnt lgkmcnt(0)
	v_mov_b32_e32 v168, v132
	s_nop 1
	v_permlane16_swap_b32_e32 v132, v168
	v_add_f32_e32 v132, v132, v168
	s_waitcnt lgkmcnt(0)
	v_mov_b32_e32 v168, v132
	s_nop 1
	v_permlane32_swap_b32_e32 v132, v168
	v_add_f32_e32 v132, v132, v168
	v_fmac_f32_e32 v137, 0xbb000000, v132
	v_fmac_f32_e32 v136, 0xbb000000, v132
	v_mul_f32_e32 v137, v137, v137
	v_fmac_f32_e32 v138, 0xbb000000, v132
	v_fmac_f32_e32 v137, v136, v136
	v_fmac_f32_e32 v133, 0xbb000000, v132
	v_fmac_f32_e32 v137, v138, v138
	v_fmac_f32_e32 v139, 0xbb000000, v132
	v_fmac_f32_e32 v137, v133, v133
	v_fmac_f32_e32 v134, 0xbb000000, v132
	v_fmac_f32_e32 v137, v139, v139
	v_fmac_f32_e32 v167, 0xbb000000, v132
	v_fmac_f32_e32 v137, v134, v134
	v_fmac_f32_e32 v137, v167, v167
	v_fmac_f32_e32 v135, 0xbb000000, v132
	v_fmac_f32_e32 v137, v135, v135
	s_waitcnt lgkmcnt(0)
	s_nop 1
	v_add_f32_dpp v133, v137, v137 quad_perm:[1,0,3,2] row_mask:0xf bank_mask:0xf
	s_waitcnt lgkmcnt(0)
	s_nop 1
	v_add_f32_dpp v133, v133, v133 quad_perm:[2,3,0,1] row_mask:0xf bank_mask:0xf
	s_waitcnt lgkmcnt(0)
	s_nop 1
	v_add_f32_dpp v133, v133, v133 row_half_mirror row_mask:0xf bank_mask:0xf
	s_waitcnt lgkmcnt(0)
	s_nop 1
	v_add_f32_dpp v133, v133, v133 row_mirror row_mask:0xf bank_mask:0xf
	s_waitcnt lgkmcnt(0)
	v_mov_b32_e32 v134, v133
	s_nop 1
	v_permlane16_swap_b32_e32 v133, v134
	v_add_f32_e32 v133, v133, v134
	ds_bpermute_b32 v134, v163, v133
	s_and_saveexec_b64 s[22:23], vcc
	s_cbranch_execz .LBB0_355
	s_waitcnt lgkmcnt(0)
	v_add_f32_e32 v133, v133, v134
	v_fmamk_f32 v133, v133, 0x3b000000, v179
	v_mul_f32_e32 v134, 0x4b800000, v133
	v_cmp_gt_f32_e64 s[0:1], s91, v133
	v_mul_f32_e32 v132, 0x3b000000, v132
	s_nop 0
	v_cndmask_b32_e64 v133, v133, v134, s[0:1]
	v_rsq_f32_e32 v133, v133
	v_add_u32_e32 v134, 0x11008, v166
	ds_write_b32 v134, v132
	v_mul_f32_e32 v132, 0x45800000, v133
	v_cndmask_b32_e64 v132, v133, v132, s[0:1]
	v_add_u32_e32 v133, 0x11208, v166
	ds_write_b32 v133, v132
; __device__ __forceinline__ float bflo(unsigned w) { return __uint_as_float(w << 16); }
; __device__ __forceinline__ float bfhi(unsigned w) { return __uint_as_float(w & 0xffff0000u); }
; __device__ __forceinline__ void gmlp_item(const u16* P, const float* lnw, const float* lnb, const float* wsl  , const float* bsl  , u16* Y, int c, int h, LAS unsigned char* L, int tid) {
;     ...
;     for (int rr = 0; rr < 16; ++rr) { const int t = 16 * w + rr; const uint4 wv = srow[rr];
;         float x[8] = {bflo(wv.x), bfhi(wv.x), bflo(wv.y), bfhi(wv.y), bflo(wv.z), bfhi(wv.z), bflo(wv.w), bfhi(wv.w)};
;         float s = 0.f;
; #pragma unroll
;         for (int i = 0; i < 8; ++i) s += x[i];
;         const float mu = wave_sum(s) * (1.f / 512.f); float s2 = 0.f;
; #pragma unroll
;         for (int i = 0; i < 8; ++i) { const float d = x[i] - mu; s2 += d * d; }
;         const float var = wave_sum(s2) * (1.f / 512.f);
;         if (lane == 0) { mean[t] = mu; rstd[t] = rsqrtf(var + EPS); } }
.LBB0_355:
	s_or_b64 exec, exec, s[22:23]
	s_waitcnt vmcnt(24)
	v_lshlrev_b32_e32 v132, 16, v128
	v_and_b32_e32 v133, 0xffff0000, v128
	v_add_f32_e32 v128, 0, v132
	s_waitcnt lgkmcnt(0)
	v_lshlrev_b32_e32 v134, 16, v129
	v_add_f32_e32 v128, v128, v133
	v_and_b32_e32 v129, 0xffff0000, v129
	v_add_f32_e32 v128, v128, v134
	v_lshlrev_b32_e32 v135, 16, v130
	v_add_f32_e32 v128, v128, v129
	v_and_b32_e32 v130, 0xffff0000, v130
	v_add_f32_e32 v128, v128, v135
	v_lshlrev_b32_e32 v136, 16, v131
	v_add_f32_e32 v128, v128, v130
	v_and_b32_e32 v131, 0xffff0000, v131
	v_add_f32_e32 v128, v128, v136
	v_add_f32_e32 v128, v128, v131
	s_waitcnt lgkmcnt(0)
	s_nop 1
	v_add_f32_dpp v128, v128, v128 quad_perm:[1,0,3,2] row_mask:0xf bank_mask:0xf
	s_waitcnt lgkmcnt(0)
	s_nop 1
	v_add_f32_dpp v128, v128, v128 quad_perm:[2,3,0,1] row_mask:0xf bank_mask:0xf
	s_waitcnt lgkmcnt(0)
	s_nop 1
	v_add_f32_dpp v128, v128, v128 row_half_mirror row_mask:0xf bank_mask:0xf
	s_waitcnt lgkmcnt(0)
	s_nop 1
	v_add_f32_dpp v128, v128, v128 row_mirror row_mask:0xf bank_mask:0xf
	s_waitcnt lgkmcnt(0)
	v_mov_b32_e32 v137, v128
	s_nop 1
	v_permlane16_swap_b32_e32 v128, v137
	v_add_f32_e32 v128, v128, v137
	s_waitcnt lgkmcnt(0)
	v_mov_b32_e32 v137, v128
	s_nop 1
	v_permlane32_swap_b32_e32 v128, v137
	v_add_f32_e32 v128, v128, v137
	v_fmac_f32_e32 v133, 0xbb000000, v128
	v_fmac_f32_e32 v132, 0xbb000000, v128
	v_mul_f32_e32 v133, v133, v133
	v_fmac_f32_e32 v134, 0xbb000000, v128
	v_fmac_f32_e32 v133, v132, v132
	v_fmac_f32_e32 v129, 0xbb000000, v128
	v_fmac_f32_e32 v133, v134, v134
	v_fmac_f32_e32 v135, 0xbb000000, v128
	v_fmac_f32_e32 v133, v129, v129
	v_fmac_f32_e32 v130, 0xbb000000, v128
	v_fmac_f32_e32 v133, v135, v135
	v_fmac_f32_e32 v136, 0xbb000000, v128
	v_fmac_f32_e32 v133, v130, v130
	v_fmac_f32_e32 v133, v136, v136
	v_fmac_f32_e32 v131, 0xbb000000, v128
	v_fmac_f32_e32 v133, v131, v131
	s_waitcnt lgkmcnt(0)
	s_nop 1
	v_add_f32_dpp v129, v133, v133 quad_perm:[1,0,3,2] row_mask:0xf bank_mask:0xf
	s_waitcnt lgkmcnt(0)
	s_nop 1
	v_add_f32_dpp v129, v129, v129 quad_perm:[2,3,0,1] row_mask:0xf bank_mask:0xf
	s_waitcnt lgkmcnt(0)
	s_nop 1
	v_add_f32_dpp v129, v129, v129 row_half_mirror row_mask:0xf bank_mask:0xf
	s_waitcnt lgkmcnt(0)
	s_nop 1
	v_add_f32_dpp v129, v129, v129 row_mirror row_mask:0xf bank_mask:0xf
	s_waitcnt lgkmcnt(0)
	v_mov_b32_e32 v130, v129
	s_nop 1
	v_permlane16_swap_b32_e32 v129, v130
	v_add_f32_e32 v129, v129, v130
	ds_bpermute_b32 v130, v163, v129
	s_and_saveexec_b64 s[22:23], vcc
	s_cbranch_execz .LBB0_357
	s_waitcnt lgkmcnt(0)
	v_add_f32_e32 v129, v129, v130
	v_fmamk_f32 v129, v129, 0x3b000000, v179
	v_mul_f32_e32 v130, 0x4b800000, v129
	v_cmp_gt_f32_e64 s[0:1], s91, v129
	v_mul_f32_e32 v128, 0x3b000000, v128
	s_nop 0
	v_cndmask_b32_e64 v129, v129, v130, s[0:1]
	v_rsq_f32_e32 v129, v129
	v_add_u32_e32 v130, 0x1100c, v166
	ds_write_b32 v130, v128
	v_mul_f32_e32 v128, 0x45800000, v129
	v_cndmask_b32_e64 v128, v129, v128, s[0:1]
	v_add_u32_e32 v129, 0x1120c, v166
	ds_write_b32 v129, v128
.LBB0_357:
	s_or_b64 exec, exec, s[22:23]
	s_waitcnt vmcnt(23)
	v_lshlrev_b32_e32 v128, 16, v124
	v_and_b32_e32 v129, 0xffff0000, v124
	v_add_f32_e32 v124, 0, v128
	s_waitcnt lgkmcnt(0)
	v_lshlrev_b32_e32 v130, 16, v125
	v_add_f32_e32 v124, v124, v129
	v_and_b32_e32 v125, 0xffff0000, v125
	v_add_f32_e32 v124, v124, v130
	v_lshlrev_b32_e32 v131, 16, v126
	v_add_f32_e32 v124, v124, v125
	v_and_b32_e32 v126, 0xffff0000, v126
	v_add_f32_e32 v124, v124, v131
	v_lshlrev_b32_e32 v132, 16, v127
	v_add_f32_e32 v124, v124, v126
	v_and_b32_e32 v127, 0xffff0000, v127
	v_add_f32_e32 v124, v124, v132
	v_add_f32_e32 v124, v124, v127
	s_waitcnt lgkmcnt(0)
	s_nop 1
	v_add_f32_dpp v124, v124, v124 quad_perm:[1,0,3,2] row_mask:0xf bank_mask:0xf
	s_waitcnt lgkmcnt(0)
	s_nop 1
	v_add_f32_dpp v124, v124, v124 quad_perm:[2,3,0,1] row_mask:0xf bank_mask:0xf
	s_waitcnt lgkmcnt(0)
	s_nop 1
	v_add_f32_dpp v124, v124, v124 row_half_mirror row_mask:0xf bank_mask:0xf
	s_waitcnt lgkmcnt(0)
	s_nop 1
	v_add_f32_dpp v124, v124, v124 row_mirror row_mask:0xf bank_mask:0xf
	s_waitcnt lgkmcnt(0)
	v_mov_b32_e32 v133, v124
	s_nop 1
	v_permlane16_swap_b32_e32 v124, v133
	v_add_f32_e32 v124, v124, v133
	s_waitcnt lgkmcnt(0)
	v_mov_b32_e32 v133, v124
	s_nop 1
	v_permlane32_swap_b32_e32 v124, v133
	v_add_f32_e32 v124, v124, v133
	v_fmac_f32_e32 v129, 0xbb000000, v124
	v_fmac_f32_e32 v128, 0xbb000000, v124
	v_mul_f32_e32 v129, v129, v129
	v_fmac_f32_e32 v130, 0xbb000000, v124
	v_fmac_f32_e32 v129, v128, v128
	v_fmac_f32_e32 v125, 0xbb000000, v124
	v_fmac_f32_e32 v129, v130, v130
	v_fmac_f32_e32 v131, 0xbb000000, v124
	v_fmac_f32_e32 v129, v125, v125
	v_fmac_f32_e32 v126, 0xbb000000, v124
	v_fmac_f32_e32 v129, v131, v131
	v_fmac_f32_e32 v132, 0xbb000000, v124
	v_fmac_f32_e32 v129, v126, v126
	v_fmac_f32_e32 v129, v132, v132
	v_fmac_f32_e32 v127, 0xbb000000, v124
	v_fmac_f32_e32 v129, v127, v127
	s_waitcnt lgkmcnt(0)
	s_nop 1
	v_add_f32_dpp v125, v129, v129 quad_perm:[1,0,3,2] row_mask:0xf bank_mask:0xf
	s_waitcnt lgkmcnt(0)
	s_nop 1
	v_add_f32_dpp v125, v125, v125 quad_perm:[2,3,0,1] row_mask:0xf bank_mask:0xf
	s_waitcnt lgkmcnt(0)
	s_nop 1
	v_add_f32_dpp v125, v125, v125 row_half_mirror row_mask:0xf bank_mask:0xf
	s_waitcnt lgkmcnt(0)
	s_nop 1
	v_add_f32_dpp v125, v125, v125 row_mirror row_mask:0xf bank_mask:0xf
	s_waitcnt lgkmcnt(0)
	v_mov_b32_e32 v126, v125
	s_nop 1
	v_permlane16_swap_b32_e32 v125, v126
	v_add_f32_e32 v125, v125, v126
	ds_bpermute_b32 v126, v163, v125
	s_and_saveexec_b64 s[22:23], vcc
	s_cbranch_execz .LBB0_359
	s_waitcnt lgkmcnt(0)
	v_add_f32_e32 v125, v125, v126
	v_fmamk_f32 v125, v125, 0x3b000000, v179
	v_mul_f32_e32 v126, 0x4b800000, v125
	v_cmp_gt_f32_e64 s[0:1], s91, v125
	v_mul_f32_e32 v124, 0x3b000000, v124
	s_nop 0
	v_cndmask_b32_e64 v125, v125, v126, s[0:1]
	v_rsq_f32_e32 v125, v125
	v_add_u32_e32 v126, 0x11010, v166
	ds_write_b32 v126, v124
	v_mul_f32_e32 v124, 0x45800000, v125
	v_cndmask_b32_e64 v124, v125, v124, s[0:1]
	v_add_u32_e32 v125, 0x11210, v166
	ds_write_b32 v125, v124
; __device__ __forceinline__ float bflo(unsigned w) { return __uint_as_float(w << 16); }
; __device__ __forceinline__ float bfhi(unsigned w) { return __uint_as_float(w & 0xffff0000u); }
; __device__ __forceinline__ void gmlp_item(const u16* P, const float* lnw, const float* lnb, const float* wsl  , const float* bsl  , u16* Y, int c, int h, LAS unsigned char* L, int tid) {
;     ...
;     for (int rr = 0; rr < 16; ++rr) { const int t = 16 * w + rr; const uint4 wv = srow[rr];
;         float x[8] = {bflo(wv.x), bfhi(wv.x), bflo(wv.y), bfhi(wv.y), bflo(wv.z), bfhi(wv.z), bflo(wv.w), bfhi(wv.w)};
;         float s = 0.f;
; #pragma unroll
;         for (int i = 0; i < 8; ++i) s += x[i];
;         const float mu = wave_sum(s) * (1.f / 512.f); float s2 = 0.f;
; #pragma unroll
;         for (int i = 0; i < 8; ++i) { const float d = x[i] - mu; s2 += d * d; }
;         const float var = wave_sum(s2) * (1.f / 512.f);
;         if (lane == 0) { mean[t] = mu; rstd[t] = rsqrtf(var + EPS); } }
.LBB0_359:
	s_or_b64 exec, exec, s[22:23]
	s_waitcnt vmcnt(22)
	v_lshlrev_b32_e32 v124, 16, v120
	v_and_b32_e32 v125, 0xffff0000, v120
	v_add_f32_e32 v120, 0, v124
	s_waitcnt lgkmcnt(0)
	v_lshlrev_b32_e32 v126, 16, v121
	v_add_f32_e32 v120, v120, v125
	v_and_b32_e32 v121, 0xffff0000, v121
	v_add_f32_e32 v120, v120, v126
	v_lshlrev_b32_e32 v127, 16, v122
	v_add_f32_e32 v120, v120, v121
	v_and_b32_e32 v122, 0xffff0000, v122
	v_add_f32_e32 v120, v120, v127
	v_lshlrev_b32_e32 v128, 16, v123
	v_add_f32_e32 v120, v120, v122
	v_and_b32_e32 v123, 0xffff0000, v123
	v_add_f32_e32 v120, v120, v128
	v_add_f32_e32 v120, v120, v123
	s_waitcnt lgkmcnt(0)
	s_nop 1
	v_add_f32_dpp v120, v120, v120 quad_perm:[1,0,3,2] row_mask:0xf bank_mask:0xf
	s_waitcnt lgkmcnt(0)
	s_nop 1
	v_add_f32_dpp v120, v120, v120 quad_perm:[2,3,0,1] row_mask:0xf bank_mask:0xf
	s_waitcnt lgkmcnt(0)
	s_nop 1
	v_add_f32_dpp v120, v120, v120 row_half_mirror row_mask:0xf bank_mask:0xf
	s_waitcnt lgkmcnt(0)
	s_nop 1
	v_add_f32_dpp v120, v120, v120 row_mirror row_mask:0xf bank_mask:0xf
	s_waitcnt lgkmcnt(0)
	v_mov_b32_e32 v129, v120
	s_nop 1
	v_permlane16_swap_b32_e32 v120, v129
	v_add_f32_e32 v120, v120, v129
	s_waitcnt lgkmcnt(0)
	v_mov_b32_e32 v129, v120
	s_nop 1
	v_permlane32_swap_b32_e32 v120, v129
	v_add_f32_e32 v120, v120, v129
	v_fmac_f32_e32 v125, 0xbb000000, v120
	v_fmac_f32_e32 v124, 0xbb000000, v120
	v_mul_f32_e32 v125, v125, v125
	v_fmac_f32_e32 v126, 0xbb000000, v120
	v_fmac_f32_e32 v125, v124, v124
	v_fmac_f32_e32 v121, 0xbb000000, v120
	v_fmac_f32_e32 v125, v126, v126
	v_fmac_f32_e32 v127, 0xbb000000, v120
	v_fmac_f32_e32 v125, v121, v121
	v_fmac_f32_e32 v122, 0xbb000000, v120
	v_fmac_f32_e32 v125, v127, v127
	v_fmac_f32_e32 v128, 0xbb000000, v120
	v_fmac_f32_e32 v125, v122, v122
	v_fmac_f32_e32 v125, v128, v128
	v_fmac_f32_e32 v123, 0xbb000000, v120
	v_fmac_f32_e32 v125, v123, v123
	s_waitcnt lgkmcnt(0)
	s_nop 1
	v_add_f32_dpp v121, v125, v125 quad_perm:[1,0,3,2] row_mask:0xf bank_mask:0xf
	s_waitcnt lgkmcnt(0)
	s_nop 1
	v_add_f32_dpp v121, v121, v121 quad_perm:[2,3,0,1] row_mask:0xf bank_mask:0xf
	s_waitcnt lgkmcnt(0)
	s_nop 1
	v_add_f32_dpp v121, v121, v121 row_half_mirror row_mask:0xf bank_mask:0xf
	s_waitcnt lgkmcnt(0)
	s_nop 1
	v_add_f32_dpp v121, v121, v121 row_mirror row_mask:0xf bank_mask:0xf
	s_waitcnt lgkmcnt(0)
	v_mov_b32_e32 v122, v121
	s_nop 1
	v_permlane16_swap_b32_e32 v121, v122
	v_add_f32_e32 v121, v121, v122
	ds_bpermute_b32 v122, v163, v121
	s_and_saveexec_b64 s[22:23], vcc
	s_cbranch_execz .LBB0_361
	s_waitcnt lgkmcnt(0)
	v_add_f32_e32 v121, v121, v122
	v_fmamk_f32 v121, v121, 0x3b000000, v179
	v_mul_f32_e32 v122, 0x4b800000, v121
	v_cmp_gt_f32_e64 s[0:1], s91, v121
	v_mul_f32_e32 v120, 0x3b000000, v120
	s_nop 0
	v_cndmask_b32_e64 v121, v121, v122, s[0:1]
	v_rsq_f32_e32 v121, v121
	v_add_u32_e32 v122, 0x11014, v166
	ds_write_b32 v122, v120
	v_mul_f32_e32 v120, 0x45800000, v121
	v_cndmask_b32_e64 v120, v121, v120, s[0:1]
	v_add_u32_e32 v121, 0x11214, v166
	ds_write_b32 v121, v120
.LBB0_361:
	s_or_b64 exec, exec, s[22:23]
	s_waitcnt vmcnt(21)
	v_lshlrev_b32_e32 v120, 16, v116
	v_and_b32_e32 v121, 0xffff0000, v116
	v_add_f32_e32 v116, 0, v120
	s_waitcnt lgkmcnt(0)
	v_lshlrev_b32_e32 v122, 16, v117
	v_add_f32_e32 v116, v116, v121
	v_and_b32_e32 v117, 0xffff0000, v117
	v_add_f32_e32 v116, v116, v122
	v_lshlrev_b32_e32 v123, 16, v118
	v_add_f32_e32 v116, v116, v117
	v_and_b32_e32 v118, 0xffff0000, v118
	v_add_f32_e32 v116, v116, v123
	v_lshlrev_b32_e32 v124, 16, v119
	v_add_f32_e32 v116, v116, v118
	v_and_b32_e32 v119, 0xffff0000, v119
	v_add_f32_e32 v116, v116, v124
	v_add_f32_e32 v116, v116, v119
	s_waitcnt lgkmcnt(0)
	s_nop 1
	v_add_f32_dpp v116, v116, v116 quad_perm:[1,0,3,2] row_mask:0xf bank_mask:0xf
	s_waitcnt lgkmcnt(0)
	s_nop 1
	v_add_f32_dpp v116, v116, v116 quad_perm:[2,3,0,1] row_mask:0xf bank_mask:0xf
	s_waitcnt lgkmcnt(0)
	s_nop 1
	v_add_f32_dpp v116, v116, v116 row_half_mirror row_mask:0xf bank_mask:0xf
	s_waitcnt lgkmcnt(0)
	s_nop 1
	v_add_f32_dpp v116, v116, v116 row_mirror row_mask:0xf bank_mask:0xf
	s_waitcnt lgkmcnt(0)
	v_mov_b32_e32 v125, v116
	s_nop 1
	v_permlane16_swap_b32_e32 v116, v125
	v_add_f32_e32 v116, v116, v125
	s_waitcnt lgkmcnt(0)
	v_mov_b32_e32 v125, v116
	s_nop 1
	v_permlane32_swap_b32_e32 v116, v125
	v_add_f32_e32 v116, v116, v125
	v_fmac_f32_e32 v121, 0xbb000000, v116
	v_fmac_f32_e32 v120, 0xbb000000, v116
	v_mul_f32_e32 v121, v121, v121
	v_fmac_f32_e32 v122, 0xbb000000, v116
	v_fmac_f32_e32 v121, v120, v120
	v_fmac_f32_e32 v117, 0xbb000000, v116
	v_fmac_f32_e32 v121, v122, v122
	v_fmac_f32_e32 v123, 0xbb000000, v116
	v_fmac_f32_e32 v121, v117, v117
	v_fmac_f32_e32 v118, 0xbb000000, v116
	v_fmac_f32_e32 v121, v123, v123
	v_fmac_f32_e32 v124, 0xbb000000, v116
	v_fmac_f32_e32 v121, v118, v118
	v_fmac_f32_e32 v121, v124, v124
	v_fmac_f32_e32 v119, 0xbb000000, v116
	v_fmac_f32_e32 v121, v119, v119
	s_waitcnt lgkmcnt(0)
	s_nop 1
	v_add_f32_dpp v117, v121, v121 quad_perm:[1,0,3,2] row_mask:0xf bank_mask:0xf
	s_waitcnt lgkmcnt(0)
	s_nop 1
	v_add_f32_dpp v117, v117, v117 quad_perm:[2,3,0,1] row_mask:0xf bank_mask:0xf
	s_waitcnt lgkmcnt(0)
	s_nop 1
	v_add_f32_dpp v117, v117, v117 row_half_mirror row_mask:0xf bank_mask:0xf
	s_waitcnt lgkmcnt(0)
	s_nop 1
	v_add_f32_dpp v117, v117, v117 row_mirror row_mask:0xf bank_mask:0xf
	s_waitcnt lgkmcnt(0)
	v_mov_b32_e32 v118, v117
	s_nop 1
	v_permlane16_swap_b32_e32 v117, v118
	v_add_f32_e32 v117, v117, v118
	ds_bpermute_b32 v118, v163, v117
	s_and_saveexec_b64 s[22:23], vcc
	s_cbranch_execz .LBB0_363
	s_waitcnt lgkmcnt(0)
	v_add_f32_e32 v117, v117, v118
	v_fmamk_f32 v117, v117, 0x3b000000, v179
	v_mul_f32_e32 v118, 0x4b800000, v117
	v_cmp_gt_f32_e64 s[0:1], s91, v117
	v_mul_f32_e32 v116, 0x3b000000, v116
	s_nop 0
	v_cndmask_b32_e64 v117, v117, v118, s[0:1]
	v_rsq_f32_e32 v117, v117
	v_add_u32_e32 v118, 0x11018, v166
	ds_write_b32 v118, v116
	v_mul_f32_e32 v116, 0x45800000, v117
	v_cndmask_b32_e64 v116, v117, v116, s[0:1]
	v_add_u32_e32 v117, 0x11218, v166
	ds_write_b32 v117, v116
; __device__ __forceinline__ float bflo(unsigned w) { return __uint_as_float(w << 16); }
; __device__ __forceinline__ float bfhi(unsigned w) { return __uint_as_float(w & 0xffff0000u); }
; __device__ __forceinline__ void gmlp_item(const u16* P, const float* lnw, const float* lnb, const float* wsl  , const float* bsl  , u16* Y, int c, int h, LAS unsigned char* L, int tid) {
;     ...
;     for (int rr = 0; rr < 16; ++rr) { const int t = 16 * w + rr; const uint4 wv = srow[rr];
;         float x[8] = {bflo(wv.x), bfhi(wv.x), bflo(wv.y), bfhi(wv.y), bflo(wv.z), bfhi(wv.z), bflo(wv.w), bfhi(wv.w)};
;         float s = 0.f;
; #pragma unroll
;         for (int i = 0; i < 8; ++i) s += x[i];
;         const float mu = wave_sum(s) * (1.f / 512.f); float s2 = 0.f;
; #pragma unroll
;         for (int i = 0; i < 8; ++i) { const float d = x[i] - mu; s2 += d * d; }
;         const float var = wave_sum(s2) * (1.f / 512.f);
;         if (lane == 0) { mean[t] = mu; rstd[t] = rsqrtf(var + EPS); } }
.LBB0_363:
	s_or_b64 exec, exec, s[22:23]
	s_waitcnt vmcnt(20)
	v_lshlrev_b32_e32 v116, 16, v112
	v_and_b32_e32 v117, 0xffff0000, v112
	v_add_f32_e32 v112, 0, v116
	s_waitcnt lgkmcnt(0)
	v_lshlrev_b32_e32 v118, 16, v113
	v_add_f32_e32 v112, v112, v117
	v_and_b32_e32 v113, 0xffff0000, v113
	v_add_f32_e32 v112, v112, v118
	v_lshlrev_b32_e32 v119, 16, v114
	v_add_f32_e32 v112, v112, v113
	v_and_b32_e32 v114, 0xffff0000, v114
	v_add_f32_e32 v112, v112, v119
	v_lshlrev_b32_e32 v120, 16, v115
	v_add_f32_e32 v112, v112, v114
	v_and_b32_e32 v115, 0xffff0000, v115
	v_add_f32_e32 v112, v112, v120
	v_add_f32_e32 v112, v112, v115
	s_waitcnt lgkmcnt(0)
	s_nop 1
	v_add_f32_dpp v112, v112, v112 quad_perm:[1,0,3,2] row_mask:0xf bank_mask:0xf
	s_waitcnt lgkmcnt(0)
	s_nop 1
	v_add_f32_dpp v112, v112, v112 quad_perm:[2,3,0,1] row_mask:0xf bank_mask:0xf
	s_waitcnt lgkmcnt(0)
	s_nop 1
	v_add_f32_dpp v112, v112, v112 row_half_mirror row_mask:0xf bank_mask:0xf
	s_waitcnt lgkmcnt(0)
	s_nop 1
	v_add_f32_dpp v112, v112, v112 row_mirror row_mask:0xf bank_mask:0xf
	s_waitcnt lgkmcnt(0)
	v_mov_b32_e32 v121, v112
	s_nop 1
	v_permlane16_swap_b32_e32 v112, v121
	v_add_f32_e32 v112, v112, v121
	s_waitcnt lgkmcnt(0)
	v_mov_b32_e32 v121, v112
	s_nop 1
	v_permlane32_swap_b32_e32 v112, v121
	v_add_f32_e32 v112, v112, v121
	v_fmac_f32_e32 v117, 0xbb000000, v112
	v_fmac_f32_e32 v116, 0xbb000000, v112
	v_mul_f32_e32 v117, v117, v117
	v_fmac_f32_e32 v118, 0xbb000000, v112
	v_fmac_f32_e32 v117, v116, v116
	v_fmac_f32_e32 v113, 0xbb000000, v112
	v_fmac_f32_e32 v117, v118, v118
	v_fmac_f32_e32 v119, 0xbb000000, v112
	v_fmac_f32_e32 v117, v113, v113
	v_fmac_f32_e32 v114, 0xbb000000, v112
	v_fmac_f32_e32 v117, v119, v119
	v_fmac_f32_e32 v120, 0xbb000000, v112
	v_fmac_f32_e32 v117, v114, v114
	v_fmac_f32_e32 v117, v120, v120
	v_fmac_f32_e32 v115, 0xbb000000, v112
	v_fmac_f32_e32 v117, v115, v115
	s_waitcnt lgkmcnt(0)
	s_nop 1
	v_add_f32_dpp v113, v117, v117 quad_perm:[1,0,3,2] row_mask:0xf bank_mask:0xf
	s_waitcnt lgkmcnt(0)
	s_nop 1
	v_add_f32_dpp v113, v113, v113 quad_perm:[2,3,0,1] row_mask:0xf bank_mask:0xf
	s_waitcnt lgkmcnt(0)
	s_nop 1
	v_add_f32_dpp v113, v113, v113 row_half_mirror row_mask:0xf bank_mask:0xf
	s_waitcnt lgkmcnt(0)
	s_nop 1
	v_add_f32_dpp v113, v113, v113 row_mirror row_mask:0xf bank_mask:0xf
	s_waitcnt lgkmcnt(0)
	v_mov_b32_e32 v114, v113
	s_nop 1
	v_permlane16_swap_b32_e32 v113, v114
	v_add_f32_e32 v113, v113, v114
	ds_bpermute_b32 v114, v163, v113
	s_and_saveexec_b64 s[22:23], vcc
	s_cbranch_execz .LBB0_365
	s_waitcnt lgkmcnt(0)
	v_add_f32_e32 v113, v113, v114
	v_fmamk_f32 v113, v113, 0x3b000000, v179
	v_mul_f32_e32 v114, 0x4b800000, v113
	v_cmp_gt_f32_e64 s[0:1], s91, v113
	v_mul_f32_e32 v112, 0x3b000000, v112
	s_nop 0
	v_cndmask_b32_e64 v113, v113, v114, s[0:1]
	v_rsq_f32_e32 v113, v113
	v_add_u32_e32 v114, 0x1101c, v166
	ds_write_b32 v114, v112
	v_mul_f32_e32 v112, 0x45800000, v113
	v_cndmask_b32_e64 v112, v113, v112, s[0:1]
	v_add_u32_e32 v113, 0x1121c, v166
	ds_write_b32 v113, v112
.LBB0_365:
	s_or_b64 exec, exec, s[22:23]
	s_waitcnt vmcnt(19)
	v_lshlrev_b32_e32 v112, 16, v108
	v_and_b32_e32 v113, 0xffff0000, v108
	v_add_f32_e32 v108, 0, v112
	s_waitcnt lgkmcnt(0)
	v_lshlrev_b32_e32 v114, 16, v109
	v_add_f32_e32 v108, v108, v113
	v_and_b32_e32 v109, 0xffff0000, v109
	v_add_f32_e32 v108, v108, v114
	v_lshlrev_b32_e32 v115, 16, v110
	v_add_f32_e32 v108, v108, v109
	v_and_b32_e32 v110, 0xffff0000, v110
	v_add_f32_e32 v108, v108, v115
	v_lshlrev_b32_e32 v116, 16, v111
	v_add_f32_e32 v108, v108, v110
	v_and_b32_e32 v111, 0xffff0000, v111
	v_add_f32_e32 v108, v108, v116
	v_add_f32_e32 v108, v108, v111
	s_waitcnt lgkmcnt(0)
	s_nop 1
	v_add_f32_dpp v108, v108, v108 quad_perm:[1,0,3,2] row_mask:0xf bank_mask:0xf
	s_waitcnt lgkmcnt(0)
	s_nop 1
	v_add_f32_dpp v108, v108, v108 quad_perm:[2,3,0,1] row_mask:0xf bank_mask:0xf
	s_waitcnt lgkmcnt(0)
	s_nop 1
	v_add_f32_dpp v108, v108, v108 row_half_mirror row_mask:0xf bank_mask:0xf
	s_waitcnt lgkmcnt(0)
	s_nop 1
	v_add_f32_dpp v108, v108, v108 row_mirror row_mask:0xf bank_mask:0xf
	s_waitcnt lgkmcnt(0)
	v_mov_b32_e32 v117, v108
	s_nop 1
	v_permlane16_swap_b32_e32 v108, v117
	v_add_f32_e32 v108, v108, v117
	s_waitcnt lgkmcnt(0)
	v_mov_b32_e32 v117, v108
	s_nop 1
	v_permlane32_swap_b32_e32 v108, v117
	v_add_f32_e32 v108, v108, v117
	v_fmac_f32_e32 v113, 0xbb000000, v108
	v_fmac_f32_e32 v112, 0xbb000000, v108
	v_mul_f32_e32 v113, v113, v113
	v_fmac_f32_e32 v114, 0xbb000000, v108
	v_fmac_f32_e32 v113, v112, v112
	v_fmac_f32_e32 v109, 0xbb000000, v108
	v_fmac_f32_e32 v113, v114, v114
	v_fmac_f32_e32 v115, 0xbb000000, v108
	v_fmac_f32_e32 v113, v109, v109
	v_fmac_f32_e32 v110, 0xbb000000, v108
	v_fmac_f32_e32 v113, v115, v115
	v_fmac_f32_e32 v116, 0xbb000000, v108
	v_fmac_f32_e32 v113, v110, v110
	v_fmac_f32_e32 v113, v116, v116
	v_fmac_f32_e32 v111, 0xbb000000, v108
	v_fmac_f32_e32 v113, v111, v111
	s_waitcnt lgkmcnt(0)
	s_nop 1
	v_add_f32_dpp v109, v113, v113 quad_perm:[1,0,3,2] row_mask:0xf bank_mask:0xf
	s_waitcnt lgkmcnt(0)
	s_nop 1
	v_add_f32_dpp v109, v109, v109 quad_perm:[2,3,0,1] row_mask:0xf bank_mask:0xf
	s_waitcnt lgkmcnt(0)
	s_nop 1
	v_add_f32_dpp v109, v109, v109 row_half_mirror row_mask:0xf bank_mask:0xf
	s_waitcnt lgkmcnt(0)
	s_nop 1
	v_add_f32_dpp v109, v109, v109 row_mirror row_mask:0xf bank_mask:0xf
	s_waitcnt lgkmcnt(0)
	v_mov_b32_e32 v110, v109
	s_nop 1
	v_permlane16_swap_b32_e32 v109, v110
	v_add_f32_e32 v109, v109, v110
	ds_bpermute_b32 v110, v163, v109
	s_and_saveexec_b64 s[22:23], vcc
	s_cbranch_execz .LBB0_367
	s_waitcnt lgkmcnt(0)
	v_add_f32_e32 v109, v109, v110
	v_fmamk_f32 v109, v109, 0x3b000000, v179
	v_mul_f32_e32 v110, 0x4b800000, v109
	v_cmp_gt_f32_e64 s[0:1], s91, v109
	v_mul_f32_e32 v108, 0x3b000000, v108
	s_nop 0
	v_cndmask_b32_e64 v109, v109, v110, s[0:1]
	v_rsq_f32_e32 v109, v109
	v_add_u32_e32 v110, 0x11020, v166
	ds_write_b32 v110, v108
	v_mul_f32_e32 v108, 0x45800000, v109
	v_cndmask_b32_e64 v108, v109, v108, s[0:1]
	v_add_u32_e32 v109, 0x11220, v166
	ds_write_b32 v109, v108
; __device__ __forceinline__ float bflo(unsigned w) { return __uint_as_float(w << 16); }
; __device__ __forceinline__ float bfhi(unsigned w) { return __uint_as_float(w & 0xffff0000u); }
; __device__ __forceinline__ float wave_sum(float v) {
; #pragma unroll
;     for (int o = 1; o < 64; o <<= 1) v += __shfl_xor(v, o);
;     return v;
; }
; __device__ __forceinline__ void gmlp_item(const u16* P, const float* lnw, const float* lnb, const float* wsl  , const float* bsl  , u16* Y, int c, int h, LAS unsigned char* L, int tid) {
;     ...
;     for (int rr = 0; rr < 16; ++rr) { const int t = 16 * w + rr; const uint4 wv = srow[rr];
;         float x[8] = {bflo(wv.x), bfhi(wv.x), bflo(wv.y), bfhi(wv.y), bflo(wv.z), bfhi(wv.z), bflo(wv.w), bfhi(wv.w)};
;         float s = 0.f;
; #pragma unroll
;         for (int i = 0; i < 8; ++i) s += x[i];
;         const float mu = wave_sum(s) * (1.f / 512.f); float s2 = 0.f;
; #pragma unroll
;         for (int i = 0; i < 8; ++i) { const float d = x[i] - mu; s2 += d * d; }
;         const float var = wave_sum(s2) * (1.f / 512.f);
;         if (lane == 0) { mean[t] = mu; rstd[t] = rsqrtf(var + EPS); } }
.LBB0_367:
	s_or_b64 exec, exec, s[22:23]
	s_waitcnt vmcnt(18)
	v_lshlrev_b32_e32 v108, 16, v104
	v_and_b32_e32 v109, 0xffff0000, v104
	v_add_f32_e32 v104, 0, v108
	s_waitcnt lgkmcnt(0)
	v_lshlrev_b32_e32 v110, 16, v105
	v_add_f32_e32 v104, v104, v109
	v_and_b32_e32 v105, 0xffff0000, v105
	v_add_f32_e32 v104, v104, v110
	v_lshlrev_b32_e32 v111, 16, v106
	v_add_f32_e32 v104, v104, v105
	v_and_b32_e32 v106, 0xffff0000, v106
	v_add_f32_e32 v104, v104, v111
	v_lshlrev_b32_e32 v112, 16, v107
	v_add_f32_e32 v104, v104, v106
	v_and_b32_e32 v107, 0xffff0000, v107
	v_add_f32_e32 v104, v104, v112
	v_add_f32_e32 v104, v104, v107
	s_waitcnt lgkmcnt(0)
	s_nop 1
	v_add_f32_dpp v104, v104, v104 quad_perm:[1,0,3,2] row_mask:0xf bank_mask:0xf
	s_waitcnt lgkmcnt(0)
	s_nop 1
	v_add_f32_dpp v104, v104, v104 quad_perm:[2,3,0,1] row_mask:0xf bank_mask:0xf
	s_waitcnt lgkmcnt(0)
	s_nop 1
	v_add_f32_dpp v104, v104, v104 row_half_mirror row_mask:0xf bank_mask:0xf
	s_waitcnt lgkmcnt(0)
	s_nop 1
	v_add_f32_dpp v104, v104, v104 row_mirror row_mask:0xf bank_mask:0xf
	s_waitcnt lgkmcnt(0)
	v_mov_b32_e32 v113, v104
	s_nop 1
	v_permlane16_swap_b32_e32 v104, v113
	v_add_f32_e32 v104, v104, v113
	s_waitcnt lgkmcnt(0)
	v_mov_b32_e32 v113, v104
	s_nop 1
	v_permlane32_swap_b32_e32 v104, v113
	v_add_f32_e32 v104, v104, v113
	v_fmac_f32_e32 v109, 0xbb000000, v104
	v_fmac_f32_e32 v108, 0xbb000000, v104
	v_mul_f32_e32 v109, v109, v109
	v_fmac_f32_e32 v110, 0xbb000000, v104
	v_fmac_f32_e32 v109, v108, v108
	v_fmac_f32_e32 v105, 0xbb000000, v104
	v_fmac_f32_e32 v109, v110, v110
	v_fmac_f32_e32 v111, 0xbb000000, v104
	v_fmac_f32_e32 v109, v105, v105
	v_fmac_f32_e32 v106, 0xbb000000, v104
	v_fmac_f32_e32 v109, v111, v111
	v_fmac_f32_e32 v112, 0xbb000000, v104
	v_fmac_f32_e32 v109, v106, v106
	v_fmac_f32_e32 v109, v112, v112
	v_fmac_f32_e32 v107, 0xbb000000, v104
	v_fmac_f32_e32 v109, v107, v107
	s_waitcnt lgkmcnt(0)
	s_nop 1
	v_add_f32_dpp v105, v109, v109 quad_perm:[1,0,3,2] row_mask:0xf bank_mask:0xf
	s_waitcnt lgkmcnt(0)
	s_nop 1
	v_add_f32_dpp v105, v105, v105 quad_perm:[2,3,0,1] row_mask:0xf bank_mask:0xf
	s_waitcnt lgkmcnt(0)
	s_nop 1
	v_add_f32_dpp v105, v105, v105 row_half_mirror row_mask:0xf bank_mask:0xf
	s_waitcnt lgkmcnt(0)
	s_nop 1
	v_add_f32_dpp v105, v105, v105 row_mirror row_mask:0xf bank_mask:0xf
	s_waitcnt lgkmcnt(0)
	v_mov_b32_e32 v106, v105
	s_nop 1
	v_permlane16_swap_b32_e32 v105, v106
	v_add_f32_e32 v105, v105, v106
	ds_bpermute_b32 v106, v163, v105
	s_and_saveexec_b64 s[22:23], vcc
	s_cbranch_execz .LBB0_369
	s_waitcnt lgkmcnt(0)
	v_add_f32_e32 v105, v105, v106
	v_fmamk_f32 v105, v105, 0x3b000000, v179
	v_mul_f32_e32 v106, 0x4b800000, v105
	v_cmp_gt_f32_e64 s[0:1], s91, v105
	v_mul_f32_e32 v104, 0x3b000000, v104
	s_nop 0
	v_cndmask_b32_e64 v105, v105, v106, s[0:1]
	v_rsq_f32_e32 v105, v105
	v_add_u32_e32 v106, 0x11024, v166
	ds_write_b32 v106, v104
	v_mul_f32_e32 v104, 0x45800000, v105
	v_cndmask_b32_e64 v104, v105, v104, s[0:1]
	v_add_u32_e32 v105, 0x11224, v166
	ds_write_b32 v105, v104
.LBB0_369:
	s_or_b64 exec, exec, s[22:23]
	s_waitcnt vmcnt(17)
	v_lshlrev_b32_e32 v104, 16, v100
	v_and_b32_e32 v105, 0xffff0000, v100
	v_add_f32_e32 v100, 0, v104
	s_waitcnt lgkmcnt(0)
	v_lshlrev_b32_e32 v106, 16, v101
	v_add_f32_e32 v100, v100, v105
	v_and_b32_e32 v101, 0xffff0000, v101
	v_add_f32_e32 v100, v100, v106
	v_lshlrev_b32_e32 v107, 16, v102
	v_add_f32_e32 v100, v100, v101
	v_and_b32_e32 v102, 0xffff0000, v102
	v_add_f32_e32 v100, v100, v107
	v_lshlrev_b32_e32 v108, 16, v103
	v_add_f32_e32 v100, v100, v102
	v_and_b32_e32 v103, 0xffff0000, v103
	v_add_f32_e32 v100, v100, v108
	v_add_f32_e32 v100, v100, v103
	s_waitcnt lgkmcnt(0)
	s_nop 1
	v_add_f32_dpp v100, v100, v100 quad_perm:[1,0,3,2] row_mask:0xf bank_mask:0xf
	s_waitcnt lgkmcnt(0)
	s_nop 1
	v_add_f32_dpp v100, v100, v100 quad_perm:[2,3,0,1] row_mask:0xf bank_mask:0xf
	s_waitcnt lgkmcnt(0)
	s_nop 1
	v_add_f32_dpp v100, v100, v100 row_half_mirror row_mask:0xf bank_mask:0xf
	s_waitcnt lgkmcnt(0)
	s_nop 1
	v_add_f32_dpp v100, v100, v100 row_mirror row_mask:0xf bank_mask:0xf
	s_waitcnt lgkmcnt(0)
	v_mov_b32_e32 v109, v100
	s_nop 1
	v_permlane16_swap_b32_e32 v100, v109
	v_add_f32_e32 v100, v100, v109
	s_waitcnt lgkmcnt(0)
	v_mov_b32_e32 v109, v100
	s_nop 1
	v_permlane32_swap_b32_e32 v100, v109
	v_add_f32_e32 v100, v100, v109
	v_fmac_f32_e32 v105, 0xbb000000, v100
	v_fmac_f32_e32 v104, 0xbb000000, v100
	v_mul_f32_e32 v105, v105, v105
	v_fmac_f32_e32 v106, 0xbb000000, v100
	v_fmac_f32_e32 v105, v104, v104
	v_fmac_f32_e32 v101, 0xbb000000, v100
	v_fmac_f32_e32 v105, v106, v106
	v_fmac_f32_e32 v107, 0xbb000000, v100
	v_fmac_f32_e32 v105, v101, v101
	v_fmac_f32_e32 v102, 0xbb000000, v100
	v_fmac_f32_e32 v105, v107, v107
	v_fmac_f32_e32 v108, 0xbb000000, v100
	v_fmac_f32_e32 v105, v102, v102
	v_fmac_f32_e32 v105, v108, v108
	v_fmac_f32_e32 v103, 0xbb000000, v100
	v_fmac_f32_e32 v105, v103, v103
	s_waitcnt lgkmcnt(0)
	s_nop 1
	v_add_f32_dpp v101, v105, v105 quad_perm:[1,0,3,2] row_mask:0xf bank_mask:0xf
	s_waitcnt lgkmcnt(0)
	s_nop 1
	v_add_f32_dpp v101, v101, v101 quad_perm:[2,3,0,1] row_mask:0xf bank_mask:0xf
	s_waitcnt lgkmcnt(0)
	s_nop 1
	v_add_f32_dpp v101, v101, v101 row_half_mirror row_mask:0xf bank_mask:0xf
	s_waitcnt lgkmcnt(0)
	s_nop 1
	v_add_f32_dpp v101, v101, v101 row_mirror row_mask:0xf bank_mask:0xf
	s_waitcnt lgkmcnt(0)
	v_mov_b32_e32 v102, v101
	s_nop 1
	v_permlane16_swap_b32_e32 v101, v102
	v_add_f32_e32 v101, v101, v102
	ds_bpermute_b32 v102, v163, v101
	s_and_saveexec_b64 s[22:23], vcc
	s_cbranch_execz .LBB0_371
	s_waitcnt lgkmcnt(0)
	v_add_f32_e32 v101, v101, v102
	v_fmamk_f32 v101, v101, 0x3b000000, v179
	v_mul_f32_e32 v102, 0x4b800000, v101
	v_cmp_gt_f32_e64 s[0:1], s91, v101
	v_mul_f32_e32 v100, 0x3b000000, v100
	s_nop 0
	v_cndmask_b32_e64 v101, v101, v102, s[0:1]
	v_rsq_f32_e32 v101, v101
	v_add_u32_e32 v102, 0x11028, v166
	ds_write_b32 v102, v100
	v_mul_f32_e32 v100, 0x45800000, v101
	v_cndmask_b32_e64 v100, v101, v100, s[0:1]
	v_add_u32_e32 v101, 0x11228, v166
	ds_write_b32 v101, v100
; __device__ __forceinline__ float bflo(unsigned w) { return __uint_as_float(w << 16); }
; __device__ __forceinline__ float bfhi(unsigned w) { return __uint_as_float(w & 0xffff0000u); }
; __device__ __forceinline__ float wave_sum(float v) {
; #pragma unroll
;     for (int o = 1; o < 64; o <<= 1) v += __shfl_xor(v, o);
;     return v;
; }
; __device__ __forceinline__ void gmlp_item(const u16* P, const float* lnw, const float* lnb, const float* wsl  , const float* bsl  , u16* Y, int c, int h, LAS unsigned char* L, int tid) {
;     ...
;     for (int rr = 0; rr < 16; ++rr) { const int t = 16 * w + rr; const uint4 wv = srow[rr];
;         float x[8] = {bflo(wv.x), bfhi(wv.x), bflo(wv.y), bfhi(wv.y), bflo(wv.z), bfhi(wv.z), bflo(wv.w), bfhi(wv.w)};
;         float s = 0.f;
; #pragma unroll
;         for (int i = 0; i < 8; ++i) s += x[i];
;         const float mu = wave_sum(s) * (1.f / 512.f); float s2 = 0.f;
; #pragma unroll
;         for (int i = 0; i < 8; ++i) { const float d = x[i] - mu; s2 += d * d; }
;         const float var = wave_sum(s2) * (1.f / 512.f);
;         if (lane == 0) { mean[t] = mu; rstd[t] = rsqrtf(var + EPS); } }
.LBB0_371:
	s_or_b64 exec, exec, s[22:23]
	s_waitcnt vmcnt(16)
	v_lshlrev_b32_e32 v100, 16, v96
	v_and_b32_e32 v101, 0xffff0000, v96
	v_add_f32_e32 v96, 0, v100
	s_waitcnt lgkmcnt(0)
	v_lshlrev_b32_e32 v102, 16, v97
	v_add_f32_e32 v96, v96, v101
	v_and_b32_e32 v97, 0xffff0000, v97
	v_add_f32_e32 v96, v96, v102
	v_lshlrev_b32_e32 v103, 16, v98
	v_add_f32_e32 v96, v96, v97
	v_and_b32_e32 v98, 0xffff0000, v98
	v_add_f32_e32 v96, v96, v103
	v_lshlrev_b32_e32 v104, 16, v99
	v_add_f32_e32 v96, v96, v98
	v_and_b32_e32 v99, 0xffff0000, v99
	v_add_f32_e32 v96, v96, v104
	v_add_f32_e32 v96, v96, v99
	s_waitcnt lgkmcnt(0)
	s_nop 1
	v_add_f32_dpp v96, v96, v96 quad_perm:[1,0,3,2] row_mask:0xf bank_mask:0xf
	s_waitcnt lgkmcnt(0)
	s_nop 1
	v_add_f32_dpp v96, v96, v96 quad_perm:[2,3,0,1] row_mask:0xf bank_mask:0xf
	s_waitcnt lgkmcnt(0)
	s_nop 1
	v_add_f32_dpp v96, v96, v96 row_half_mirror row_mask:0xf bank_mask:0xf
	s_waitcnt lgkmcnt(0)
	s_nop 1
	v_add_f32_dpp v96, v96, v96 row_mirror row_mask:0xf bank_mask:0xf
	s_waitcnt lgkmcnt(0)
	v_mov_b32_e32 v105, v96
	s_nop 1
	v_permlane16_swap_b32_e32 v96, v105
	v_add_f32_e32 v96, v96, v105
	s_waitcnt lgkmcnt(0)
	v_mov_b32_e32 v105, v96
	s_nop 1
	v_permlane32_swap_b32_e32 v96, v105
	v_add_f32_e32 v96, v96, v105
	v_fmac_f32_e32 v101, 0xbb000000, v96
	v_fmac_f32_e32 v100, 0xbb000000, v96
	v_mul_f32_e32 v101, v101, v101
	v_fmac_f32_e32 v102, 0xbb000000, v96
	v_fmac_f32_e32 v101, v100, v100
	v_fmac_f32_e32 v97, 0xbb000000, v96
	v_fmac_f32_e32 v101, v102, v102
	v_fmac_f32_e32 v103, 0xbb000000, v96
	v_fmac_f32_e32 v101, v97, v97
	v_fmac_f32_e32 v98, 0xbb000000, v96
	v_fmac_f32_e32 v101, v103, v103
	v_fmac_f32_e32 v104, 0xbb000000, v96
	v_fmac_f32_e32 v101, v98, v98
	v_fmac_f32_e32 v101, v104, v104
	v_fmac_f32_e32 v99, 0xbb000000, v96
	v_fmac_f32_e32 v101, v99, v99
	s_waitcnt lgkmcnt(0)
	s_nop 1
	v_add_f32_dpp v97, v101, v101 quad_perm:[1,0,3,2] row_mask:0xf bank_mask:0xf
	s_waitcnt lgkmcnt(0)
	s_nop 1
	v_add_f32_dpp v97, v97, v97 quad_perm:[2,3,0,1] row_mask:0xf bank_mask:0xf
	s_waitcnt lgkmcnt(0)
	s_nop 1
	v_add_f32_dpp v97, v97, v97 row_half_mirror row_mask:0xf bank_mask:0xf
	s_waitcnt lgkmcnt(0)
	s_nop 1
	v_add_f32_dpp v97, v97, v97 row_mirror row_mask:0xf bank_mask:0xf
	s_waitcnt lgkmcnt(0)
	v_mov_b32_e32 v98, v97
	s_nop 1
	v_permlane16_swap_b32_e32 v97, v98
	v_add_f32_e32 v97, v97, v98
	ds_bpermute_b32 v98, v163, v97
	s_and_saveexec_b64 s[22:23], vcc
	s_cbranch_execz .LBB0_373
	s_waitcnt lgkmcnt(0)
	v_add_f32_e32 v97, v97, v98
	v_fmamk_f32 v97, v97, 0x3b000000, v179
	v_mul_f32_e32 v98, 0x4b800000, v97
	v_cmp_gt_f32_e64 s[0:1], s91, v97
	v_mul_f32_e32 v96, 0x3b000000, v96
	s_nop 0
	v_cndmask_b32_e64 v97, v97, v98, s[0:1]
	v_rsq_f32_e32 v97, v97
	v_add_u32_e32 v98, 0x1102c, v166
	ds_write_b32 v98, v96
	v_mul_f32_e32 v96, 0x45800000, v97
	v_cndmask_b32_e64 v96, v97, v96, s[0:1]
	v_add_u32_e32 v97, 0x1122c, v166
	ds_write_b32 v97, v96
.LBB0_373:
	s_or_b64 exec, exec, s[22:23]
	s_waitcnt vmcnt(15)
	v_lshlrev_b32_e32 v96, 16, v92
	v_and_b32_e32 v97, 0xffff0000, v92
	v_add_f32_e32 v92, 0, v96
	s_waitcnt lgkmcnt(0)
	v_lshlrev_b32_e32 v98, 16, v93
	v_add_f32_e32 v92, v92, v97
	v_and_b32_e32 v93, 0xffff0000, v93
	v_add_f32_e32 v92, v92, v98
	v_lshlrev_b32_e32 v99, 16, v94
	v_add_f32_e32 v92, v92, v93
	v_and_b32_e32 v94, 0xffff0000, v94
	v_add_f32_e32 v92, v92, v99
	v_lshlrev_b32_e32 v100, 16, v95
	v_add_f32_e32 v92, v92, v94
	v_and_b32_e32 v95, 0xffff0000, v95
	v_add_f32_e32 v92, v92, v100
	v_add_f32_e32 v92, v92, v95
	s_waitcnt lgkmcnt(0)
	s_nop 1
	v_add_f32_dpp v92, v92, v92 quad_perm:[1,0,3,2] row_mask:0xf bank_mask:0xf
	s_waitcnt lgkmcnt(0)
	s_nop 1
	v_add_f32_dpp v92, v92, v92 quad_perm:[2,3,0,1] row_mask:0xf bank_mask:0xf
	s_waitcnt lgkmcnt(0)
	s_nop 1
	v_add_f32_dpp v92, v92, v92 row_half_mirror row_mask:0xf bank_mask:0xf
	s_waitcnt lgkmcnt(0)
	s_nop 1
	v_add_f32_dpp v92, v92, v92 row_mirror row_mask:0xf bank_mask:0xf
	s_waitcnt lgkmcnt(0)
	v_mov_b32_e32 v101, v92
	s_nop 1
	v_permlane16_swap_b32_e32 v92, v101
	v_add_f32_e32 v92, v92, v101
	s_waitcnt lgkmcnt(0)
	v_mov_b32_e32 v101, v92
	s_nop 1
	v_permlane32_swap_b32_e32 v92, v101
	v_add_f32_e32 v92, v92, v101
	v_fmac_f32_e32 v97, 0xbb000000, v92
	v_fmac_f32_e32 v96, 0xbb000000, v92
	v_mul_f32_e32 v97, v97, v97
	v_fmac_f32_e32 v98, 0xbb000000, v92
	v_fmac_f32_e32 v97, v96, v96
	v_fmac_f32_e32 v93, 0xbb000000, v92
	v_fmac_f32_e32 v97, v98, v98
	v_fmac_f32_e32 v99, 0xbb000000, v92
	v_fmac_f32_e32 v97, v93, v93
	v_fmac_f32_e32 v94, 0xbb000000, v92
	v_fmac_f32_e32 v97, v99, v99
	v_fmac_f32_e32 v100, 0xbb000000, v92
	v_fmac_f32_e32 v97, v94, v94
	v_fmac_f32_e32 v97, v100, v100
	v_fmac_f32_e32 v95, 0xbb000000, v92
	v_fmac_f32_e32 v97, v95, v95
	s_waitcnt lgkmcnt(0)
	s_nop 1
	v_add_f32_dpp v93, v97, v97 quad_perm:[1,0,3,2] row_mask:0xf bank_mask:0xf
	s_waitcnt lgkmcnt(0)
	s_nop 1
	v_add_f32_dpp v93, v93, v93 quad_perm:[2,3,0,1] row_mask:0xf bank_mask:0xf
	s_waitcnt lgkmcnt(0)
	s_nop 1
	v_add_f32_dpp v93, v93, v93 row_half_mirror row_mask:0xf bank_mask:0xf
	s_waitcnt lgkmcnt(0)
	s_nop 1
	v_add_f32_dpp v93, v93, v93 row_mirror row_mask:0xf bank_mask:0xf
	s_waitcnt lgkmcnt(0)
	v_mov_b32_e32 v94, v93
	s_nop 1
	v_permlane16_swap_b32_e32 v93, v94
	v_add_f32_e32 v93, v93, v94
	ds_bpermute_b32 v94, v163, v93
	s_and_saveexec_b64 s[22:23], vcc
	s_cbranch_execz .LBB0_375
	s_waitcnt lgkmcnt(0)
	v_add_f32_e32 v93, v93, v94
	v_fmamk_f32 v93, v93, 0x3b000000, v179
	v_mul_f32_e32 v94, 0x4b800000, v93
	v_cmp_gt_f32_e64 s[0:1], s91, v93
	v_mul_f32_e32 v92, 0x3b000000, v92
	s_nop 0
	v_cndmask_b32_e64 v93, v93, v94, s[0:1]
	v_rsq_f32_e32 v93, v93
	v_add_u32_e32 v94, 0x11030, v166
	ds_write_b32 v94, v92
	v_mul_f32_e32 v92, 0x45800000, v93
	v_cndmask_b32_e64 v92, v93, v92, s[0:1]
	v_add_u32_e32 v93, 0x11230, v166
	ds_write_b32 v93, v92
; __device__ __forceinline__ float bflo(unsigned w) { return __uint_as_float(w << 16); }
; __device__ __forceinline__ float bfhi(unsigned w) { return __uint_as_float(w & 0xffff0000u); }
; __device__ __forceinline__ float wave_sum(float v) {
; #pragma unroll
;     for (int o = 1; o < 64; o <<= 1) v += __shfl_xor(v, o);
;     return v;
; }
; __device__ __forceinline__ void gmlp_item(const u16* P, const float* lnw, const float* lnb, const float* wsl  , const float* bsl  , u16* Y, int c, int h, LAS unsigned char* L, int tid) {
;     ...
;     for (int rr = 0; rr < 16; ++rr) { const int t = 16 * w + rr; const uint4 wv = srow[rr];
;         float x[8] = {bflo(wv.x), bfhi(wv.x), bflo(wv.y), bfhi(wv.y), bflo(wv.z), bfhi(wv.z), bflo(wv.w), bfhi(wv.w)};
;         float s = 0.f;
; #pragma unroll
;         for (int i = 0; i < 8; ++i) s += x[i];
;         const float mu = wave_sum(s) * (1.f / 512.f); float s2 = 0.f;
; #pragma unroll
;         for (int i = 0; i < 8; ++i) { const float d = x[i] - mu; s2 += d * d; }
;         const float var = wave_sum(s2) * (1.f / 512.f);
;         if (lane == 0) { mean[t] = mu; rstd[t] = rsqrtf(var + EPS); } }
.LBB0_375:
	s_or_b64 exec, exec, s[22:23]
	s_waitcnt vmcnt(14)
	v_lshlrev_b32_e32 v92, 16, v88
	v_and_b32_e32 v93, 0xffff0000, v88
	v_add_f32_e32 v88, 0, v92
	s_waitcnt lgkmcnt(0)
	v_lshlrev_b32_e32 v94, 16, v89
	v_add_f32_e32 v88, v88, v93
	v_and_b32_e32 v89, 0xffff0000, v89
	v_add_f32_e32 v88, v88, v94
	v_lshlrev_b32_e32 v95, 16, v90
	v_add_f32_e32 v88, v88, v89
	v_and_b32_e32 v90, 0xffff0000, v90
	v_add_f32_e32 v88, v88, v95
	v_lshlrev_b32_e32 v96, 16, v91
	v_add_f32_e32 v88, v88, v90
	v_and_b32_e32 v91, 0xffff0000, v91
	v_add_f32_e32 v88, v88, v96
	v_add_f32_e32 v88, v88, v91
	s_waitcnt lgkmcnt(0)
	s_nop 1
	v_add_f32_dpp v88, v88, v88 quad_perm:[1,0,3,2] row_mask:0xf bank_mask:0xf
	s_waitcnt lgkmcnt(0)
	s_nop 1
	v_add_f32_dpp v88, v88, v88 quad_perm:[2,3,0,1] row_mask:0xf bank_mask:0xf
	s_waitcnt lgkmcnt(0)
	s_nop 1
	v_add_f32_dpp v88, v88, v88 row_half_mirror row_mask:0xf bank_mask:0xf
	s_waitcnt lgkmcnt(0)
	s_nop 1
	v_add_f32_dpp v88, v88, v88 row_mirror row_mask:0xf bank_mask:0xf
	s_waitcnt lgkmcnt(0)
	v_mov_b32_e32 v97, v88
	s_nop 1
	v_permlane16_swap_b32_e32 v88, v97
	v_add_f32_e32 v88, v88, v97
	s_waitcnt lgkmcnt(0)
	v_mov_b32_e32 v97, v88
	s_nop 1
	v_permlane32_swap_b32_e32 v88, v97
	v_add_f32_e32 v88, v88, v97
	v_fmac_f32_e32 v93, 0xbb000000, v88
	v_fmac_f32_e32 v92, 0xbb000000, v88
	v_mul_f32_e32 v93, v93, v93
	v_fmac_f32_e32 v94, 0xbb000000, v88
	v_fmac_f32_e32 v93, v92, v92
	v_fmac_f32_e32 v89, 0xbb000000, v88
	v_fmac_f32_e32 v93, v94, v94
	v_fmac_f32_e32 v95, 0xbb000000, v88
	v_fmac_f32_e32 v93, v89, v89
	v_fmac_f32_e32 v90, 0xbb000000, v88
	v_fmac_f32_e32 v93, v95, v95
	v_fmac_f32_e32 v96, 0xbb000000, v88
	v_fmac_f32_e32 v93, v90, v90
	v_fmac_f32_e32 v93, v96, v96
	v_fmac_f32_e32 v91, 0xbb000000, v88
	v_fmac_f32_e32 v93, v91, v91
	s_waitcnt lgkmcnt(0)
	s_nop 1
	v_add_f32_dpp v89, v93, v93 quad_perm:[1,0,3,2] row_mask:0xf bank_mask:0xf
	s_waitcnt lgkmcnt(0)
	s_nop 1
	v_add_f32_dpp v89, v89, v89 quad_perm:[2,3,0,1] row_mask:0xf bank_mask:0xf
	s_waitcnt lgkmcnt(0)
	s_nop 1
	v_add_f32_dpp v89, v89, v89 row_half_mirror row_mask:0xf bank_mask:0xf
	s_waitcnt lgkmcnt(0)
	s_nop 1
	v_add_f32_dpp v89, v89, v89 row_mirror row_mask:0xf bank_mask:0xf
	s_waitcnt lgkmcnt(0)
	v_mov_b32_e32 v90, v89
	s_nop 1
	v_permlane16_swap_b32_e32 v89, v90
	v_add_f32_e32 v89, v89, v90
	ds_bpermute_b32 v90, v163, v89
	s_and_saveexec_b64 s[22:23], vcc
	s_cbranch_execz .LBB0_377
	s_waitcnt lgkmcnt(0)
	v_add_f32_e32 v89, v89, v90
	v_fmamk_f32 v89, v89, 0x3b000000, v179
	v_mul_f32_e32 v90, 0x4b800000, v89
	v_cmp_gt_f32_e64 s[0:1], s91, v89
	v_mul_f32_e32 v88, 0x3b000000, v88
	s_nop 0
	v_cndmask_b32_e64 v89, v89, v90, s[0:1]
	v_rsq_f32_e32 v89, v89
	v_add_u32_e32 v90, 0x11034, v166
	ds_write_b32 v90, v88
	v_mul_f32_e32 v88, 0x45800000, v89
	v_cndmask_b32_e64 v88, v89, v88, s[0:1]
	v_add_u32_e32 v89, 0x11234, v166
	ds_write_b32 v89, v88
.LBB0_377:
	s_or_b64 exec, exec, s[22:23]
	s_waitcnt vmcnt(13)
	v_lshlrev_b32_e32 v88, 16, v84
	v_and_b32_e32 v89, 0xffff0000, v84
	v_add_f32_e32 v84, 0, v88
	s_waitcnt lgkmcnt(0)
	v_lshlrev_b32_e32 v90, 16, v85
	v_add_f32_e32 v84, v84, v89
	v_and_b32_e32 v85, 0xffff0000, v85
	v_add_f32_e32 v84, v84, v90
	v_lshlrev_b32_e32 v91, 16, v86
	v_add_f32_e32 v84, v84, v85
	v_and_b32_e32 v86, 0xffff0000, v86
	v_add_f32_e32 v84, v84, v91
	v_lshlrev_b32_e32 v92, 16, v87
	v_add_f32_e32 v84, v84, v86
	v_and_b32_e32 v87, 0xffff0000, v87
	v_add_f32_e32 v84, v84, v92
	v_add_f32_e32 v84, v84, v87
	s_waitcnt lgkmcnt(0)
	s_nop 1
	v_add_f32_dpp v84, v84, v84 quad_perm:[1,0,3,2] row_mask:0xf bank_mask:0xf
	s_waitcnt lgkmcnt(0)
	s_nop 1
	v_add_f32_dpp v84, v84, v84 quad_perm:[2,3,0,1] row_mask:0xf bank_mask:0xf
	s_waitcnt lgkmcnt(0)
	s_nop 1
	v_add_f32_dpp v84, v84, v84 row_half_mirror row_mask:0xf bank_mask:0xf
	s_waitcnt lgkmcnt(0)
	s_nop 1
	v_add_f32_dpp v84, v84, v84 row_mirror row_mask:0xf bank_mask:0xf
	s_waitcnt lgkmcnt(0)
	v_mov_b32_e32 v93, v84
	s_nop 1
	v_permlane16_swap_b32_e32 v84, v93
	v_add_f32_e32 v84, v84, v93
	s_waitcnt lgkmcnt(0)
	v_mov_b32_e32 v93, v84
	s_nop 1
	v_permlane32_swap_b32_e32 v84, v93
	v_add_f32_e32 v84, v84, v93
	v_fmac_f32_e32 v89, 0xbb000000, v84
	v_fmac_f32_e32 v88, 0xbb000000, v84
	v_mul_f32_e32 v89, v89, v89
	v_fmac_f32_e32 v90, 0xbb000000, v84
	v_fmac_f32_e32 v89, v88, v88
	v_fmac_f32_e32 v85, 0xbb000000, v84
	v_fmac_f32_e32 v89, v90, v90
	v_fmac_f32_e32 v91, 0xbb000000, v84
	v_fmac_f32_e32 v89, v85, v85
	v_fmac_f32_e32 v86, 0xbb000000, v84
	v_fmac_f32_e32 v89, v91, v91
	v_fmac_f32_e32 v92, 0xbb000000, v84
	v_fmac_f32_e32 v89, v86, v86
	v_fmac_f32_e32 v89, v92, v92
	v_fmac_f32_e32 v87, 0xbb000000, v84
	v_fmac_f32_e32 v89, v87, v87
	s_waitcnt lgkmcnt(0)
	s_nop 1
	v_add_f32_dpp v85, v89, v89 quad_perm:[1,0,3,2] row_mask:0xf bank_mask:0xf
	s_waitcnt lgkmcnt(0)
	s_nop 1
	v_add_f32_dpp v85, v85, v85 quad_perm:[2,3,0,1] row_mask:0xf bank_mask:0xf
	s_waitcnt lgkmcnt(0)
	s_nop 1
	v_add_f32_dpp v85, v85, v85 row_half_mirror row_mask:0xf bank_mask:0xf
	s_waitcnt lgkmcnt(0)
	s_nop 1
	v_add_f32_dpp v85, v85, v85 row_mirror row_mask:0xf bank_mask:0xf
	s_waitcnt lgkmcnt(0)
	v_mov_b32_e32 v86, v85
	s_nop 1
	v_permlane16_swap_b32_e32 v85, v86
	v_add_f32_e32 v85, v85, v86
	ds_bpermute_b32 v86, v163, v85
	s_and_saveexec_b64 s[22:23], vcc
	s_cbranch_execz .LBB0_379
	s_waitcnt lgkmcnt(0)
	v_add_f32_e32 v85, v85, v86
	v_fmamk_f32 v85, v85, 0x3b000000, v179
	v_mul_f32_e32 v86, 0x4b800000, v85
	v_cmp_gt_f32_e64 s[0:1], s91, v85
	v_mul_f32_e32 v84, 0x3b000000, v84
	s_nop 0
	v_cndmask_b32_e64 v85, v85, v86, s[0:1]
	v_rsq_f32_e32 v85, v85
	v_add_u32_e32 v86, 0x11038, v166
	ds_write_b32 v86, v84
	v_mul_f32_e32 v84, 0x45800000, v85
	v_cndmask_b32_e64 v84, v85, v84, s[0:1]
	v_add_u32_e32 v85, 0x11238, v166
	ds_write_b32 v85, v84
; __device__ __forceinline__ float bflo(unsigned w) { return __uint_as_float(w << 16); }
; __device__ __forceinline__ float bfhi(unsigned w) { return __uint_as_float(w & 0xffff0000u); }
; __device__ __forceinline__ float wave_sum(float v) {
; #pragma unroll
;     for (int o = 1; o < 64; o <<= 1) v += __shfl_xor(v, o);
;     return v;
; }
; __device__ __forceinline__ void gmlp_item(const u16* P, const float* lnw, const float* lnb, const float* wsl  , const float* bsl  , u16* Y, int c, int h, LAS unsigned char* L, int tid) {
;     ...
;     for (int rr = 0; rr < 16; ++rr) { const int t = 16 * w + rr; const uint4 wv = srow[rr];
;         float x[8] = {bflo(wv.x), bfhi(wv.x), bflo(wv.y), bfhi(wv.y), bflo(wv.z), bfhi(wv.z), bflo(wv.w), bfhi(wv.w)};
;         float s = 0.f;
; #pragma unroll
;         for (int i = 0; i < 8; ++i) s += x[i];
;         const float mu = wave_sum(s) * (1.f / 512.f); float s2 = 0.f;
; #pragma unroll
;         for (int i = 0; i < 8; ++i) { const float d = x[i] - mu; s2 += d * d; }
;         const float var = wave_sum(s2) * (1.f / 512.f);
;         if (lane == 0) { mean[t] = mu; rstd[t] = rsqrtf(var + EPS); } }
.LBB0_379:
	s_or_b64 exec, exec, s[22:23]
	s_waitcnt vmcnt(12)
	v_lshlrev_b32_e32 v84, 16, v80
	v_and_b32_e32 v85, 0xffff0000, v80
	v_add_f32_e32 v80, 0, v84
	s_waitcnt lgkmcnt(0)
	v_lshlrev_b32_e32 v86, 16, v81
	v_add_f32_e32 v80, v80, v85
	v_and_b32_e32 v81, 0xffff0000, v81
	v_add_f32_e32 v80, v80, v86
	v_lshlrev_b32_e32 v87, 16, v82
	v_add_f32_e32 v80, v80, v81
	v_and_b32_e32 v82, 0xffff0000, v82
	v_add_f32_e32 v80, v80, v87
	v_lshlrev_b32_e32 v88, 16, v83
	v_add_f32_e32 v80, v80, v82
	v_and_b32_e32 v83, 0xffff0000, v83
	v_add_f32_e32 v80, v80, v88
	v_add_f32_e32 v80, v80, v83
	s_lshl_b32 s18, s18, 7
	s_waitcnt lgkmcnt(0)
	s_nop 1
	v_add_f32_dpp v80, v80, v80 quad_perm:[1,0,3,2] row_mask:0xf bank_mask:0xf
	s_waitcnt lgkmcnt(0)
	s_nop 1
	v_add_f32_dpp v80, v80, v80 quad_perm:[2,3,0,1] row_mask:0xf bank_mask:0xf
	s_waitcnt lgkmcnt(0)
	s_nop 1
	v_add_f32_dpp v80, v80, v80 row_half_mirror row_mask:0xf bank_mask:0xf
	s_waitcnt lgkmcnt(0)
	s_nop 1
	v_add_f32_dpp v80, v80, v80 row_mirror row_mask:0xf bank_mask:0xf
	s_waitcnt lgkmcnt(0)
	v_mov_b32_e32 v89, v80
	s_nop 1
	v_permlane16_swap_b32_e32 v80, v89
	v_add_f32_e32 v80, v80, v89
	s_waitcnt lgkmcnt(0)
	v_mov_b32_e32 v89, v80
	s_nop 1
	v_permlane32_swap_b32_e32 v80, v89
	v_add_f32_e32 v80, v80, v89
	v_fmac_f32_e32 v85, 0xbb000000, v80
	v_fmac_f32_e32 v84, 0xbb000000, v80
	v_mul_f32_e32 v85, v85, v85
	v_fmac_f32_e32 v86, 0xbb000000, v80
	v_fmac_f32_e32 v85, v84, v84
	v_fmac_f32_e32 v81, 0xbb000000, v80
	v_fmac_f32_e32 v85, v86, v86
	v_fmac_f32_e32 v87, 0xbb000000, v80
	v_fmac_f32_e32 v85, v81, v81
	v_fmac_f32_e32 v82, 0xbb000000, v80
	v_fmac_f32_e32 v85, v87, v87
	v_fmac_f32_e32 v88, 0xbb000000, v80
	v_fmac_f32_e32 v85, v82, v82
	v_fmac_f32_e32 v85, v88, v88
	v_fmac_f32_e32 v83, 0xbb000000, v80
	v_fmac_f32_e32 v85, v83, v83
	s_waitcnt lgkmcnt(0)
	s_nop 1
	v_add_f32_dpp v81, v85, v85 quad_perm:[1,0,3,2] row_mask:0xf bank_mask:0xf
	s_waitcnt lgkmcnt(0)
	s_nop 1
	v_add_f32_dpp v81, v81, v81 quad_perm:[2,3,0,1] row_mask:0xf bank_mask:0xf
	s_waitcnt lgkmcnt(0)
	s_nop 1
	v_add_f32_dpp v81, v81, v81 row_half_mirror row_mask:0xf bank_mask:0xf
	s_waitcnt lgkmcnt(0)
	s_nop 1
	v_add_f32_dpp v81, v81, v81 row_mirror row_mask:0xf bank_mask:0xf
	s_waitcnt lgkmcnt(0)
	v_mov_b32_e32 v82, v81
	s_nop 1
	v_permlane16_swap_b32_e32 v81, v82
	v_add_f32_e32 v81, v81, v82
	ds_bpermute_b32 v82, v163, v81
	s_and_saveexec_b64 s[0:1], vcc
	s_cbranch_execz .LBB0_338
	s_waitcnt lgkmcnt(0)
	v_add_f32_e32 v81, v81, v82
	v_fmamk_f32 v81, v81, 0x3b000000, v179
	v_mul_f32_e32 v82, 0x4b800000, v81
	v_cmp_gt_f32_e32 vcc, s91, v81
	v_mul_f32_e32 v80, 0x3b000000, v80
	s_nop 0
	v_cndmask_b32_e32 v81, v81, v82, vcc
	v_rsq_f32_e32 v81, v81
	v_add_u32_e32 v82, 0x1103c, v166
	ds_write_b32 v82, v80
	v_mul_f32_e32 v80, 0x45800000, v81
	v_cndmask_b32_e32 v80, v81, v80, vcc
	v_add_u32_e32 v81, 0x1123c, v166
	ds_write_b32 v81, v80
	s_branch .LBB0_338

; __device__ __forceinline__ float bflo(unsigned w) { return __uint_as_float(w << 16); }
; __device__ __forceinline__ float bfhi(unsigned w) { return __uint_as_float(w & 0xffff0000u); }
; __global__ void __launch_bounds__(512, 2) mega(Params p) {
;     ...
;         { float mx = 0.f;
;           for (int row = gw; row < TT; row += ngw) { const u16* kp = P + (size_t)row * PST + C_CK + lane * 16;
;               const uint4 a = *(const uint4*)kp, b2 = *(const uint4*)(kp + 8); const unsigned ww[8] = {a.x, a.y, a.z, a.w, b2.x, b2.y, b2.z, b2.w}; float ss = 0.f;
; #pragma unroll
;               for (int e = 0; e < 8; ++e) { const float x0 = bflo(ww[e]), x1 = bfhi(ww[e]); ss += x0 * x0 + x1 * x1; }
;               ss += __shfl_xor(ss, 1); ss += __shfl_xor(ss, 2); ss += __shfl_xor(ss, 4); mx = fmaxf(mx, ss); }
;           if ((lane & 7) == 0) atomicMax((unsigned*)(ws + WS_CTL) + CW_KMAX + l * 8 + (lane >> 3), __float_as_uint(mx)); }
.LBB0_636:
	global_load_dwordx4 v[18:21], v[0:1], off
	global_load_dwordx4 v[22:25], v[0:1], off offset:-16
	v_add_u32_e32 v4, s62, v4
	v_max_f32_e32 v3, v3, v3
	v_cmp_lt_i32_e32 vcc, s64, v4
	s_or_b64 s[34:35], vcc, s[34:35]
	v_lshl_add_u64 v[0:1], v[0:1], 0, s[6:7]
	s_waitcnt vmcnt(2)
	v_lshlrev_b32_e32 v17, 16, v13
	v_lshlrev_b32_e32 v16, 16, v12
	v_and_b32_e32 v13, 0xffff0000, v13
	v_and_b32_e32 v12, 0xffff0000, v12
	v_pk_mul_f32 v[12:13], v[12:13], v[12:13]
	s_nop 0
	v_pk_fma_f32 v[12:13], v[16:17], v[16:17], v[12:13]
	v_lshlrev_b32_e32 v17, 16, v15
	v_lshlrev_b32_e32 v16, 16, v14
	v_and_b32_e32 v15, 0xffff0000, v15
	v_and_b32_e32 v14, 0xffff0000, v14
	v_pk_mul_f32 v[14:15], v[14:15], v[14:15]
	v_add_f32_e32 v12, v12, v13
	v_pk_fma_f32 v[14:15], v[16:17], v[16:17], v[14:15]
	v_lshlrev_b32_e32 v17, 16, v9
	v_lshlrev_b32_e32 v16, 16, v8
	v_and_b32_e32 v9, 0xffff0000, v9
	v_and_b32_e32 v8, 0xffff0000, v8
	v_pk_mul_f32 v[8:9], v[8:9], v[8:9]
	v_add_f32_e32 v12, v12, v14
	v_pk_fma_f32 v[8:9], v[16:17], v[16:17], v[8:9]
	v_lshlrev_b32_e32 v17, 16, v11
	v_lshlrev_b32_e32 v16, 16, v10
	v_and_b32_e32 v11, 0xffff0000, v11
	v_and_b32_e32 v10, 0xffff0000, v10
	v_add_f32_e32 v12, v12, v15
	v_pk_mul_f32 v[10:11], v[10:11], v[10:11]
	v_add_f32_e32 v8, v12, v8
	v_pk_fma_f32 v[10:11], v[16:17], v[16:17], v[10:11]
	v_add_f32_e32 v8, v8, v9
	v_add_f32_e32 v8, v8, v10
	v_add_f32_e32 v8, v8, v11
	s_waitcnt lgkmcnt(0)
	s_nop 1
	v_add_f32_dpp v8, v8, v8 quad_perm:[1,0,3,2] row_mask:0xf bank_mask:0xf
	s_waitcnt lgkmcnt(0)
	s_nop 1
	v_add_f32_dpp v8, v8, v8 quad_perm:[2,3,0,1] row_mask:0xf bank_mask:0xf
	s_waitcnt lgkmcnt(0)
	s_nop 1
	v_add_f32_dpp v8, v8, v8 row_half_mirror row_mask:0xf bank_mask:0xf
	v_max_f32_e32 v3, v3, v8
	s_andn2_b64 exec, exec, s[34:35]
	s_cbranch_execz .Lkmax_done
	global_load_dwordx4 v[8:11], v[0:1], off
	global_load_dwordx4 v[12:15], v[0:1], off offset:-16
	v_add_u32_e32 v4, s62, v4
	v_max_f32_e32 v3, v3, v3
	v_cmp_lt_i32_e32 vcc, s64, v4
	s_or_b64 s[34:35], vcc, s[34:35]
	v_lshl_add_u64 v[0:1], v[0:1], 0, s[6:7]
	s_waitcnt vmcnt(2)
	v_lshlrev_b32_e32 v17, 16, v23
	v_lshlrev_b32_e32 v16, 16, v22
	v_and_b32_e32 v23, 0xffff0000, v23
	v_and_b32_e32 v22, 0xffff0000, v22
	v_pk_mul_f32 v[22:23], v[22:23], v[22:23]
	s_nop 0
	v_pk_fma_f32 v[22:23], v[16:17], v[16:17], v[22:23]
	v_lshlrev_b32_e32 v17, 16, v25
	v_lshlrev_b32_e32 v16, 16, v24
	v_and_b32_e32 v25, 0xffff0000, v25
	v_and_b32_e32 v24, 0xffff0000, v24
	v_pk_mul_f32 v[24:25], v[24:25], v[24:25]
	v_add_f32_e32 v22, v22, v23
	v_pk_fma_f32 v[24:25], v[16:17], v[16:17], v[24:25]
	v_lshlrev_b32_e32 v17, 16, v19
	v_lshlrev_b32_e32 v16, 16, v18
	v_and_b32_e32 v19, 0xffff0000, v19
	v_and_b32_e32 v18, 0xffff0000, v18
	v_pk_mul_f32 v[18:19], v[18:19], v[18:19]
	v_add_f32_e32 v22, v22, v24
	v_pk_fma_f32 v[18:19], v[16:17], v[16:17], v[18:19]
	v_lshlrev_b32_e32 v17, 16, v21
	v_lshlrev_b32_e32 v16, 16, v20
	v_and_b32_e32 v21, 0xffff0000, v21
	v_and_b32_e32 v20, 0xffff0000, v20
	v_add_f32_e32 v22, v22, v25
	v_pk_mul_f32 v[20:21], v[20:21], v[20:21]
	v_add_f32_e32 v18, v22, v18
	v_pk_fma_f32 v[20:21], v[16:17], v[16:17], v[20:21]
	v_add_f32_e32 v18, v18, v19
	v_add_f32_e32 v18, v18, v20
	v_add_f32_e32 v18, v18, v21
	s_waitcnt lgkmcnt(0)
	s_nop 1
	v_add_f32_dpp v18, v18, v18 quad_perm:[1,0,3,2] row_mask:0xf bank_mask:0xf
	s_waitcnt lgkmcnt(0)
	s_nop 1
	v_add_f32_dpp v18, v18, v18 quad_perm:[2,3,0,1] row_mask:0xf bank_mask:0xf
	s_waitcnt lgkmcnt(0)
	s_nop 1
	v_add_f32_dpp v18, v18, v18 row_half_mirror row_mask:0xf bank_mask:0xf
	v_max_f32_e32 v3, v3, v18
	s_andn2_b64 exec, exec, s[34:35]
	s_cbranch_execnz .LBB0_636

; #define LAS __attribute__((address_space(3)))
; __device__ __forceinline__ int crow(int r, int hi) { return (r & 3) + 8 * (r >> 2) + 4 * hi; }
; __device__ __forceinline__ unsigned pk2(float lo, float hi) { return f2bf(lo) | (f2bf(hi) << 16); }
; __device__ __forceinline__ float bflo(unsigned w) { return __uint_as_float(w << 16); }
; __device__ __forceinline__ float bfhi(unsigned w) { return __uint_as_float(w & 0xffff0000u); }
; __device__ __forceinline__ int crow(int r, int hi) { return (r & 3) + 8 * (r >> 2) + 4 * hi; }
; __device__ __forceinline__ void hgrn_c_item(const u16* P, const float* LBl0, const float* LBl1, const float* ST, const float* hnw, u16* Y, int rc, int h, LAS unsigned char* L, int tid) {
;     ...
;     LAS float* Ob = (LAS float*)L;
; #pragma unroll
;     for (int r = 0; r < 16; ++r) Ob[(32 * mt + crow(r, lane >> 5)) * 132 + 32 * nt + (lane & 31)] = acc[r];
;     __syncthreads();
;     { float o[16]; float ss = 0.f;
; #pragma unroll
;       for (int i = 0; i < 16; ++i) { o[i] = Ob[te * 132 + c0 + i]; ss += o[i] * o[i]; }
;       ss += __shfl_xor(ss, 1); ss += __shfl_xor(ss, 2); ss += __shfl_xor(ss, 4);
;       const float rs = rsqrtf(ss * (1.f / 128.f) + EPS);
;       u16* yp = Y + (size_t)(R0 + te) * DM + 512 + h * 128 + c0;
;       const unsigned zz[8] = {z0.x, z0.y, z0.z, z0.w, z1.x, z1.y, z1.z, z1.w};
;       unsigned ow[8];
; #pragma unroll
;       for (int i = 0; i < 8; ++i) { const float y0 = o[2 * i] * rs * hnw[c0 + 2 * i] * bflo(zz[i]), y1 = o[2 * i + 1] * rs * hnw[c0 + 2 * i + 1] * bfhi(zz[i]); ow[i] = pk2(y0, y1); }
;       *(uint4*)yp = make_uint4(ow[0], ow[1], ow[2], ow[3]); *(uint4*)(yp + 8) = make_uint4(ow[4], ow[5], ow[6], ow[7]); }
.LBB0_900:
	v_lshrrev_b32_e32 v16, 3, v101
	v_and_b32_e32 v16, 4, v16
	v_lshl_or_b32 v16, v139, 5, v16
	s_movk_i32 s0, 0x210
	v_lshl_add_u32 v17, v140, 7, 0
	v_lshlrev_b32_e32 v18, 2, v163
	v_mul_lo_u32 v16, v16, s0
	v_add3_u32 v16, v17, v18, v16
	s_nop 2
	ds_write2_b32 v16, v0, v1 offset1:132
	v_add_u32_e32 v0, 0x400, v16
	ds_write2_b32 v0, v2, v3 offset0:8 offset1:140
	v_add_u32_e32 v0, 0x1000, v16
	ds_write2_b32 v0, v4, v5 offset0:32 offset1:164
	v_add_u32_e32 v0, 0x1400, v16
	ds_write2_b32 v0, v6, v7 offset0:40 offset1:172
	v_add_u32_e32 v0, 0x2000, v16
	ds_write2_b32 v0, v8, v9 offset0:64 offset1:196
	v_add_u32_e32 v0, 0x2400, v16
	ds_write2_b32 v0, v10, v11 offset0:72 offset1:204
	v_add_u32_e32 v0, 0x3000, v16
	ds_write2_b32 v0, v12, v13 offset0:96 offset1:228
	v_add_u32_e32 v0, 0x3400, v16
	v_lshlrev_b32_e32 v18, 2, v100
	ds_write2_b32 v0, v14, v15 offset0:104 offset1:236
	s_waitcnt lgkmcnt(0)
	s_barrier
	global_load_dwordx4 v[0:3], v18, s[74:75]
	global_load_dwordx4 v[4:7], v18, s[74:75] offset:16
	global_load_dwordx4 v[8:11], v18, s[74:75] offset:48
	global_load_dwordx4 v[12:15], v18, s[74:75] offset:32
	v_cmp_lt_i32_e32 vcc, v178, v172
	v_mul_lo_u32 v19, v138, s0
	v_lshlrev_b64 v[16:17], 12, v[102:103]
	v_cndmask_b32_e32 v20, v171, v178, vcc
	v_cmp_lt_i32_e32 vcc, v177, v172
	s_lshl_b32 s84, s13, 1
	v_add3_u32 v28, 0, v19, v18
	v_cndmask_b32_e32 v21, v171, v177, vcc
	v_lshl_add_u64 v[16:17], s[24:25], 0, v[16:17]
	s_waitcnt vmcnt(10)
	v_lshlrev_b32_e32 v68, 2, v20
	v_lshlrev_b32_e32 v69, 2, v21
	v_lshl_add_u64 v[20:21], v[16:17], 0, s[84:85]
	ds_read_b128 v[16:19], v28
	v_cmp_lt_i32_e32 vcc, v176, v172
	v_lshlrev_b32_e32 v164, 1, v100
	v_lshl_add_u64 v[48:49], v[20:21], 0, v[164:165]
	v_cndmask_b32_e32 v22, v171, v176, vcc
	v_lshlrev_b32_e32 v70, 2, v22
	ds_read_b128 v[20:23], v28 offset:16
	ds_read_b128 v[24:27], v28 offset:32
	ds_read_b128 v[28:31], v28 offset:48
	s_waitcnt lgkmcnt(3)
	v_pk_mul_f32 v[54:55], v[16:17], v[16:17]
	s_waitcnt vmcnt(4)
	v_lshlrev_b32_e32 v45, 16, v59
	v_lshlrev_b32_e32 v44, 16, v58
	v_and_b32_e32 v47, 0xffff0000, v59
	v_and_b32_e32 v46, 0xffff0000, v58
	v_mov_b32_e32 v50, v16
	v_pk_mul_f32 v[52:53], v[18:19], v[18:19]
	s_waitcnt lgkmcnt(2)
	v_mov_b32_e32 v16, v20
	v_pk_mul_f32 v[58:59], v[20:21], v[20:21]
	v_add_f32_e32 v20, v54, v55
	v_add_f32_e32 v20, v20, v52
	v_add_f32_e32 v20, v20, v53
	v_add_f32_e32 v20, v20, v58
	v_lshlrev_b32_e32 v41, 16, v57
	v_lshlrev_b32_e32 v40, 16, v56
	v_and_b32_e32 v43, 0xffff0000, v57
	v_and_b32_e32 v42, 0xffff0000, v56
	v_pk_mul_f32 v[56:57], v[22:23], v[22:23]
	v_lshlrev_b32_e32 v33, 16, v61
	v_lshlrev_b32_e32 v32, 16, v60
	v_and_b32_e32 v35, 0xffff0000, v61
	v_and_b32_e32 v34, 0xffff0000, v60
	s_waitcnt lgkmcnt(1)
	v_pk_mul_f32 v[60:61], v[24:25], v[24:25]
	v_lshlrev_b32_e32 v37, 16, v63
	v_lshlrev_b32_e32 v36, 16, v62
	v_and_b32_e32 v39, 0xffff0000, v63
	v_and_b32_e32 v38, 0xffff0000, v62
	v_pk_mul_f32 v[62:63], v[26:27], v[26:27]
	s_waitcnt lgkmcnt(0)
	v_pk_mul_f32 v[64:65], v[28:29], v[28:29]
	v_pk_mul_f32 v[66:67], v[30:31], v[30:31]
	v_mov_b32_e32 v51, v18
	v_mov_b32_e32 v18, v17
	v_mov_b32_e32 v17, v22
	v_mov_b32_e32 v22, v21
	v_readlane_b32 s62, v254, 40
	v_readlane_b32 s56, v254, 42
	v_readlane_b32 s58, v254, 44
	v_readlane_b32 s60, v254, 46
	v_readlane_b32 s48, v254, 48
	s_mov_b64 s[0:1], -1
	v_readlane_b32 s63, v254, 41
	v_readlane_b32 s57, v254, 43
	v_readlane_b32 s59, v254, 45
	v_readlane_b32 s61, v254, 47
	v_readlane_b32 s49, v254, 49
	s_movk_i32 s44, 0x1000
	s_waitcnt vmcnt(3)
	v_mov_b32_e32 v52, v0
	v_add_f32_e32 v0, v20, v59
	v_add_f32_e32 v0, v0, v56
	v_add_f32_e32 v0, v0, v57
	v_add_f32_e32 v0, v0, v60
	v_add_f32_e32 v0, v0, v61
	v_add_f32_e32 v0, v0, v62
	v_add_f32_e32 v0, v0, v63
	v_add_f32_e32 v0, v0, v64
	v_add_f32_e32 v0, v0, v65
	v_add_f32_e32 v0, v0, v66
	v_add_f32_e32 v0, v0, v67
	v_mov_b32_e32 v53, v2
	v_mov_b32_e32 v2, v1
	s_waitcnt vmcnt(2)
	v_mov_b32_e32 v20, v4
	v_mov_b32_e32 v4, v24
	v_mov_b32_e32 v24, v25
	v_mov_b32_e32 v25, v27
	s_waitcnt lgkmcnt(0)
	s_nop 1
	v_add_f32_dpp v0, v0, v0 quad_perm:[1,0,3,2] row_mask:0xf bank_mask:0xf
	s_waitcnt vmcnt(0)
	v_mov_b32_e32 v27, v14
	v_mov_b32_e32 v14, v13
	v_mov_b32_e32 v13, v30
	v_mov_b32_e32 v21, v6
	s_waitcnt lgkmcnt(0)
	s_nop 1
	v_add_f32_dpp v0, v0, v0 quad_perm:[2,3,0,1] row_mask:0xf bank_mask:0xf
	v_mov_b32_e32 v6, v5
	v_mov_b32_e32 v5, v26
	v_mov_b32_e32 v26, v12
	v_mov_b32_e32 v12, v28
	s_waitcnt lgkmcnt(0)
; __device__ __forceinline__ unsigned pk2(float lo, float hi) { return f2bf(lo) | (f2bf(hi) << 16); }
; __device__ __forceinline__ float bflo(unsigned w) { return __uint_as_float(w << 16); }
; __device__ __forceinline__ float bfhi(unsigned w) { return __uint_as_float(w & 0xffff0000u); }
; __device__ __forceinline__ void hgrn_c_item(const u16* P, const float* LBl0, const float* LBl1, const float* ST, const float* hnw, u16* Y, int rc, int h, LAS unsigned char* L, int tid) {
;     ...
;       const float rs = rsqrtf(ss * (1.f / 128.f) + EPS);
;       u16* yp = Y + (size_t)(R0 + te) * DM + 512 + h * 128 + c0;
;       const unsigned zz[8] = {z0.x, z0.y, z0.z, z0.w, z1.x, z1.y, z1.z, z1.w};
;       unsigned ow[8];
; #pragma unroll
;       for (int i = 0; i < 8; ++i) { const float y0 = o[2 * i] * rs * hnw[c0 + 2 * i] * bflo(zz[i]), y1 = o[2 * i + 1] * rs * hnw[c0 + 2 * i + 1] * bfhi(zz[i]); ow[i] = pk2(y0, y1); }
;       *(uint4*)yp = make_uint4(ow[0], ow[1], ow[2], ow[3]); *(uint4*)(yp + 8) = make_uint4(ow[4], ow[5], ow[6], ow[7]); }
	s_nop 1
	v_add_f32_dpp v0, v0, v0 row_half_mirror row_mask:0xf bank_mask:0xf
	v_fmamk_f32 v0, v0, 0x3c000000, v179
	v_mul_f32_e32 v1, 0x4b800000, v0
	v_cmp_gt_f32_e32 vcc, s91, v0
	v_mov_b32_e32 v28, v29
	v_mov_b32_e32 v29, v31
	v_cndmask_b32_e32 v0, v0, v1, vcc
	v_rsq_f32_e32 v0, v0
	s_nop 0
	v_mul_f32_e32 v1, 0x45800000, v0
	v_cndmask_b32_e32 v30, v0, v1, vcc
	v_pk_mul_f32 v[0:1], v[50:51], v[30:31] op_sel_hi:[1,0]
	v_pk_mul_f32 v[18:19], v[18:19], v[30:31] op_sel_hi:[1,0]
	v_pk_mul_f32 v[0:1], v[52:53], v[0:1]
	v_pk_mul_f32 v[2:3], v[2:3], v[18:19]
	v_pk_mul_f32 v[0:1], v[0:1], v[32:33]
	v_pk_mul_f32 v[2:3], v[2:3], v[34:35]
	v_and_b32_sdwa v18, v1, v180 dst_sel:DWORD dst_unused:UNUSED_PAD src0_sel:WORD_1 src1_sel:DWORD
	v_and_b32_sdwa v19, v0, v180 dst_sel:DWORD dst_unused:UNUSED_PAD src0_sel:WORD_1 src1_sel:DWORD
	v_add3_u32 v0, v0, v19, s3
	v_add3_u32 v1, v1, v18, s3
	v_and_b32_sdwa v18, v3, v180 dst_sel:DWORD dst_unused:UNUSED_PAD src0_sel:WORD_1 src1_sel:DWORD
	v_and_b32_sdwa v19, v2, v180 dst_sel:DWORD dst_unused:UNUSED_PAD src0_sel:WORD_1 src1_sel:DWORD
	v_add3_u32 v3, v3, v18, s3
	v_add3_u32 v2, v2, v19, s3
	v_and_b32_e32 v3, 0xffff0000, v3
	v_and_b32_e32 v2, 0xffff0000, v2
	v_or_b32_sdwa v1, v3, v1 dst_sel:DWORD dst_unused:UNUSED_PAD src0_sel:DWORD src1_sel:WORD_1
	v_or_b32_sdwa v0, v2, v0 dst_sel:DWORD dst_unused:UNUSED_PAD src0_sel:DWORD src1_sel:WORD_1
	v_pk_mul_f32 v[2:3], v[16:17], v[30:31] op_sel_hi:[1,0]
	v_pk_mul_f32 v[16:17], v[22:23], v[30:31] op_sel_hi:[1,0]
	v_pk_mul_f32 v[2:3], v[20:21], v[2:3]
	v_pk_mul_f32 v[6:7], v[6:7], v[16:17]
	v_pk_mul_f32 v[2:3], v[2:3], v[36:37]
	v_pk_mul_f32 v[6:7], v[6:7], v[38:39]
	v_and_b32_sdwa v16, v3, v180 dst_sel:DWORD dst_unused:UNUSED_PAD src0_sel:WORD_1 src1_sel:DWORD
	v_and_b32_sdwa v17, v2, v180 dst_sel:DWORD dst_unused:UNUSED_PAD src0_sel:WORD_1 src1_sel:DWORD
	v_add3_u32 v2, v2, v17, s3
	v_add3_u32 v3, v3, v16, s3
	v_and_b32_sdwa v16, v7, v180 dst_sel:DWORD dst_unused:UNUSED_PAD src0_sel:WORD_1 src1_sel:DWORD
	v_and_b32_sdwa v17, v6, v180 dst_sel:DWORD dst_unused:UNUSED_PAD src0_sel:WORD_1 src1_sel:DWORD
	v_add3_u32 v7, v7, v16, s3
	v_add3_u32 v6, v6, v17, s3
	v_and_b32_e32 v7, 0xffff0000, v7
	v_and_b32_e32 v6, 0xffff0000, v6
	v_pk_mul_f32 v[4:5], v[4:5], v[30:31] op_sel_hi:[1,0]
	v_or_b32_sdwa v3, v7, v3 dst_sel:DWORD dst_unused:UNUSED_PAD src0_sel:DWORD src1_sel:WORD_1
	v_or_b32_sdwa v2, v6, v2 dst_sel:DWORD dst_unused:UNUSED_PAD src0_sel:DWORD src1_sel:WORD_1
	v_pk_mul_f32 v[4:5], v[26:27], v[4:5]
	v_pk_mul_f32 v[6:7], v[24:25], v[30:31] op_sel_hi:[1,0]
	v_pk_mul_f32 v[4:5], v[4:5], v[40:41]
	v_pk_mul_f32 v[6:7], v[6:7], v[14:15]
	v_and_b32_sdwa v14, v5, v180 dst_sel:DWORD dst_unused:UNUSED_PAD src0_sel:WORD_1 src1_sel:DWORD
	v_pk_mul_f32 v[6:7], v[6:7], v[42:43]
	v_and_b32_sdwa v15, v4, v180 dst_sel:DWORD dst_unused:UNUSED_PAD src0_sel:WORD_1 src1_sel:DWORD
	v_add3_u32 v4, v4, v15, s3
	v_add3_u32 v5, v5, v14, s3
	v_and_b32_sdwa v14, v7, v180 dst_sel:DWORD dst_unused:UNUSED_PAD src0_sel:WORD_1 src1_sel:DWORD
	v_and_b32_sdwa v15, v6, v180 dst_sel:DWORD dst_unused:UNUSED_PAD src0_sel:WORD_1 src1_sel:DWORD
	v_add3_u32 v7, v7, v14, s3
	v_add3_u32 v6, v6, v15, s3
	v_and_b32_e32 v7, 0xffff0000, v7
	v_and_b32_e32 v6, 0xffff0000, v6
	v_or_b32_sdwa v5, v7, v5 dst_sel:DWORD dst_unused:UNUSED_PAD src0_sel:DWORD src1_sel:WORD_1
	v_or_b32_sdwa v4, v6, v4 dst_sel:DWORD dst_unused:UNUSED_PAD src0_sel:DWORD src1_sel:WORD_1
	v_pk_mul_f32 v[6:7], v[12:13], v[30:31] op_sel_hi:[1,0]
	v_mov_b32_e32 v12, v8
	v_mov_b32_e32 v13, v10
	v_pk_mul_f32 v[6:7], v[6:7], v[12:13]
	v_pk_mul_f32 v[12:13], v[28:29], v[30:31] op_sel_hi:[1,0]
	v_mov_b32_e32 v10, v9
	v_pk_mul_f32 v[6:7], v[6:7], v[44:45]
	v_pk_mul_f32 v[8:9], v[12:13], v[10:11]
	v_and_b32_sdwa v10, v7, v180 dst_sel:DWORD dst_unused:UNUSED_PAD src0_sel:WORD_1 src1_sel:DWORD
	v_pk_mul_f32 v[8:9], v[8:9], v[46:47]
	v_and_b32_sdwa v11, v6, v180 dst_sel:DWORD dst_unused:UNUSED_PAD src0_sel:WORD_1 src1_sel:DWORD
	v_add3_u32 v6, v6, v11, s3
	v_add3_u32 v7, v7, v10, s3
	v_and_b32_sdwa v10, v9, v180 dst_sel:DWORD dst_unused:UNUSED_PAD src0_sel:WORD_1 src1_sel:DWORD
	v_and_b32_sdwa v11, v8, v180 dst_sel:DWORD dst_unused:UNUSED_PAD src0_sel:WORD_1 src1_sel:DWORD
	v_add3_u32 v9, v9, v10, s3
	v_add3_u32 v8, v8, v11, s3
	v_and_b32_e32 v9, 0xffff0000, v9
	v_and_b32_e32 v8, 0xffff0000, v8
	v_or_b32_sdwa v7, v9, v7 dst_sel:DWORD dst_unused:UNUSED_PAD src0_sel:DWORD src1_sel:WORD_1
	v_or_b32_sdwa v6, v8, v6 dst_sel:DWORD dst_unused:UNUSED_PAD src0_sel:DWORD src1_sel:WORD_1
	global_store_dwordx4 v[48:49], v[0:3], off offset:1024
	global_store_dwordx4 v[48:49], v[4:7], off offset:1040
	s_barrier
	s_branch .LBB0_914

; #define LAS __attribute__((address_space(3)))
; __device__ __forceinline__ int crow(int r, int hi) { return (r & 3) + 8 * (r >> 2) + 4 * hi; }
; __device__ __forceinline__ unsigned pk2(float lo, float hi) { return f2bf(lo) | (f2bf(hi) << 16); }
; __device__ __forceinline__ float bflo(unsigned w) { return __uint_as_float(w << 16); }
; __device__ __forceinline__ float bfhi(unsigned w) { return __uint_as_float(w & 0xffff0000u); }
; __device__ __forceinline__ int crow(int r, int hi) { return (r & 3) + 8 * (r >> 2) + 4 * hi; }
; __device__ __forceinline__ void hgrn_c_item(const u16* P, const float* LBl0, const float* LBl1, const float* ST, const float* hnw, u16* Y, int rc, int h, LAS unsigned char* L, int tid) {
;     ...
;     LAS float* Ob = (LAS float*)L;
; #pragma unroll
;     for (int r = 0; r < 16; ++r) Ob[(32 * mt + crow(r, lane >> 5)) * 132 + 32 * nt + (lane & 31)] = acc[r];
;     __syncthreads();
;     { float o[16]; float ss = 0.f;
; #pragma unroll
;       for (int i = 0; i < 16; ++i) { o[i] = Ob[te * 132 + c0 + i]; ss += o[i] * o[i]; }
;       ss += __shfl_xor(ss, 1); ss += __shfl_xor(ss, 2); ss += __shfl_xor(ss, 4);
;       const float rs = rsqrtf(ss * (1.f / 128.f) + EPS);
;       u16* yp = Y + (size_t)(R0 + te) * DM + 512 + h * 128 + c0;
;       const unsigned zz[8] = {z0.x, z0.y, z0.z, z0.w, z1.x, z1.y, z1.z, z1.w};
;       unsigned ow[8];
; #pragma unroll
;       for (int i = 0; i < 8; ++i) { const float y0 = o[2 * i] * rs * hnw[c0 + 2 * i] * bflo(zz[i]), y1 = o[2 * i + 1] * rs * hnw[c0 + 2 * i + 1] * bfhi(zz[i]); ow[i] = pk2(y0, y1); }
;       *(uint4*)yp = make_uint4(ow[0], ow[1], ow[2], ow[3]); *(uint4*)(yp + 8) = make_uint4(ow[4], ow[5], ow[6], ow[7]); }
.LBB0_1169:
	v_lshrrev_b32_e32 v16, 3, v105
	v_and_b32_e32 v16, 4, v16
	v_lshl_or_b32 v16, v140, 5, v16
	s_movk_i32 s0, 0x210
	v_lshl_add_u32 v17, v141, 7, 0
	v_lshlrev_b32_e32 v18, 2, v163
	v_mul_lo_u32 v16, v16, s0
	v_add3_u32 v16, v17, v18, v16
	s_nop 2
	ds_write2_b32 v16, v0, v1 offset1:132
	v_add_u32_e32 v0, 0x400, v16
	ds_write2_b32 v0, v2, v3 offset0:8 offset1:140
	v_add_u32_e32 v0, 0x1000, v16
	ds_write2_b32 v0, v4, v5 offset0:32 offset1:164
	v_add_u32_e32 v0, 0x1400, v16
	ds_write2_b32 v0, v6, v7 offset0:40 offset1:172
	v_add_u32_e32 v0, 0x2000, v16
	ds_write2_b32 v0, v8, v9 offset0:64 offset1:196
	v_add_u32_e32 v0, 0x2400, v16
	ds_write2_b32 v0, v10, v11 offset0:72 offset1:204
	v_add_u32_e32 v0, 0x3000, v16
	ds_write2_b32 v0, v12, v13 offset0:96 offset1:228
	v_add_u32_e32 v0, 0x3400, v16
	v_lshlrev_b32_e32 v18, 2, v100
	ds_write2_b32 v0, v14, v15 offset0:104 offset1:236
	s_waitcnt lgkmcnt(0)
	s_barrier
	global_load_dwordx4 v[0:3], v18, s[74:75]
	global_load_dwordx4 v[4:7], v18, s[74:75] offset:16
	global_load_dwordx4 v[8:11], v18, s[74:75] offset:48
	global_load_dwordx4 v[12:15], v18, s[74:75] offset:32
	v_cmp_lt_i32_e32 vcc, v178, v172
	v_mul_lo_u32 v19, v139, s0
	v_readlane_b32 s0, v253, 57
	v_cndmask_b32_e32 v20, v171, v178, vcc
	v_cmp_lt_i32_e32 vcc, v177, v172
	v_lshlrev_b64 v[16:17], 12, v[102:103]
	v_add3_u32 v28, 0, v19, v18
	v_cndmask_b32_e32 v21, v171, v177, vcc
	v_readlane_b32 s1, v253, 58
	s_waitcnt vmcnt(10)
	v_lshlrev_b32_e32 v68, 2, v20
	v_lshlrev_b32_e32 v69, 2, v21
	v_lshl_add_u64 v[20:21], s[0:1], 0, v[16:17]
	ds_read_b128 v[16:19], v28
	v_cmp_lt_i32_e32 vcc, v176, v172
	v_lshlrev_b32_e32 v164, 1, v100
	v_lshl_add_u64 v[48:49], v[20:21], 0, v[164:165]
	v_cndmask_b32_e32 v22, v171, v176, vcc
	v_lshlrev_b32_e32 v70, 2, v22
	ds_read_b128 v[20:23], v28 offset:16
	ds_read_b128 v[24:27], v28 offset:32
	ds_read_b128 v[28:31], v28 offset:48
	s_waitcnt lgkmcnt(3)
	v_pk_mul_f32 v[54:55], v[16:17], v[16:17]
	s_waitcnt vmcnt(4)
	v_lshlrev_b32_e32 v45, 16, v59
	v_lshlrev_b32_e32 v44, 16, v58
	v_and_b32_e32 v47, 0xffff0000, v59
	v_and_b32_e32 v46, 0xffff0000, v58
	v_mov_b32_e32 v50, v16
	v_pk_mul_f32 v[52:53], v[18:19], v[18:19]
	s_waitcnt lgkmcnt(2)
	v_mov_b32_e32 v16, v20
	v_pk_mul_f32 v[58:59], v[20:21], v[20:21]
	v_add_f32_e32 v20, v54, v55
	v_add_f32_e32 v20, v20, v52
	v_add_f32_e32 v20, v20, v53
	v_add_f32_e32 v20, v20, v58
	v_lshlrev_b32_e32 v41, 16, v57
	v_lshlrev_b32_e32 v40, 16, v56
	v_and_b32_e32 v43, 0xffff0000, v57
	v_and_b32_e32 v42, 0xffff0000, v56
	v_pk_mul_f32 v[56:57], v[22:23], v[22:23]
	v_add_f32_e32 v20, v20, v59
	v_add_f32_e32 v20, v20, v56
	s_waitcnt lgkmcnt(1)
	v_pk_mul_f32 v[60:61], v[24:25], v[24:25]
	v_pk_mul_f32 v[62:63], v[26:27], v[26:27]
	v_lshlrev_b32_e32 v33, 16, v65
	v_lshlrev_b32_e32 v32, 16, v64
	v_and_b32_e32 v35, 0xffff0000, v65
	v_and_b32_e32 v34, 0xffff0000, v64
	s_waitcnt lgkmcnt(0)
	v_pk_mul_f32 v[64:65], v[28:29], v[28:29]
	v_lshlrev_b32_e32 v37, 16, v67
	v_lshlrev_b32_e32 v36, 16, v66
	v_and_b32_e32 v39, 0xffff0000, v67
	v_and_b32_e32 v38, 0xffff0000, v66
	v_pk_mul_f32 v[66:67], v[30:31], v[30:31]
	v_mov_b32_e32 v51, v18
	v_mov_b32_e32 v18, v17
	v_mov_b32_e32 v17, v22
	v_mov_b32_e32 v22, v21
	v_readlane_b32 s62, v254, 40
	v_readlane_b32 s60, v254, 46
	v_readlane_b32 s48, v254, 48
	s_mov_b64 s[0:1], 0
	v_readlane_b32 s63, v254, 41
	v_readlane_b32 s61, v254, 47
	v_readlane_b32 s49, v254, 49
	s_movk_i32 s82, 0x6000
	s_waitcnt vmcnt(3)
	v_mov_b32_e32 v52, v0
	v_add_f32_e32 v0, v20, v57
	v_add_f32_e32 v0, v0, v60
	v_add_f32_e32 v0, v0, v61
	v_add_f32_e32 v0, v0, v62
	v_add_f32_e32 v0, v0, v63
	v_add_f32_e32 v0, v0, v64
	v_add_f32_e32 v0, v0, v65
	v_add_f32_e32 v0, v0, v66
	v_add_f32_e32 v0, v0, v67
	v_mov_b32_e32 v53, v2
	v_mov_b32_e32 v2, v1
	s_waitcnt vmcnt(2)
	v_mov_b32_e32 v20, v4
	v_mov_b32_e32 v4, v24
	v_mov_b32_e32 v24, v25
	v_mov_b32_e32 v25, v27
	s_waitcnt lgkmcnt(0)
	s_nop 1
	v_add_f32_dpp v0, v0, v0 quad_perm:[1,0,3,2] row_mask:0xf bank_mask:0xf
	s_waitcnt vmcnt(0)
	v_mov_b32_e32 v27, v14
	v_mov_b32_e32 v14, v13
	v_mov_b32_e32 v13, v30
	v_mov_b32_e32 v21, v6
	s_waitcnt lgkmcnt(0)
	s_nop 1
	v_add_f32_dpp v0, v0, v0 quad_perm:[2,3,0,1] row_mask:0xf bank_mask:0xf
	v_mov_b32_e32 v6, v5
	v_mov_b32_e32 v5, v26
	v_mov_b32_e32 v26, v12
	v_mov_b32_e32 v12, v28
	s_waitcnt lgkmcnt(0)
; __device__ __forceinline__ unsigned pk2(float lo, float hi) { return f2bf(lo) | (f2bf(hi) << 16); }
; __device__ __forceinline__ float bflo(unsigned w) { return __uint_as_float(w << 16); }
; __device__ __forceinline__ float bfhi(unsigned w) { return __uint_as_float(w & 0xffff0000u); }
; __device__ __forceinline__ void hgrn_c_item(const u16* P, const float* LBl0, const float* LBl1, const float* ST, const float* hnw, u16* Y, int rc, int h, LAS unsigned char* L, int tid) {
;     ...
;       const float rs = rsqrtf(ss * (1.f / 128.f) + EPS);
;       u16* yp = Y + (size_t)(R0 + te) * DM + 512 + h * 128 + c0;
;       const unsigned zz[8] = {z0.x, z0.y, z0.z, z0.w, z1.x, z1.y, z1.z, z1.w};
;       unsigned ow[8];
; #pragma unroll
;       for (int i = 0; i < 8; ++i) { const float y0 = o[2 * i] * rs * hnw[c0 + 2 * i] * bflo(zz[i]), y1 = o[2 * i + 1] * rs * hnw[c0 + 2 * i + 1] * bfhi(zz[i]); ow[i] = pk2(y0, y1); }
;       *(uint4*)yp = make_uint4(ow[0], ow[1], ow[2], ow[3]); *(uint4*)(yp + 8) = make_uint4(ow[4], ow[5], ow[6], ow[7]); }
	s_nop 1
	v_add_f32_dpp v0, v0, v0 row_half_mirror row_mask:0xf bank_mask:0xf
	v_fmamk_f32 v0, v0, 0x3c000000, v179
	v_mul_f32_e32 v1, 0x4b800000, v0
	v_cmp_gt_f32_e32 vcc, s91, v0
	v_mov_b32_e32 v28, v29
	v_mov_b32_e32 v29, v31
	v_cndmask_b32_e32 v0, v0, v1, vcc
	v_rsq_f32_e32 v0, v0
	s_nop 0
	v_mul_f32_e32 v1, 0x45800000, v0
	v_cndmask_b32_e32 v30, v0, v1, vcc
	v_pk_mul_f32 v[0:1], v[50:51], v[30:31] op_sel_hi:[1,0]
	v_pk_mul_f32 v[18:19], v[18:19], v[30:31] op_sel_hi:[1,0]
	v_pk_mul_f32 v[0:1], v[52:53], v[0:1]
	v_pk_mul_f32 v[2:3], v[2:3], v[18:19]
	v_pk_mul_f32 v[0:1], v[0:1], v[32:33]
	v_pk_mul_f32 v[2:3], v[2:3], v[34:35]
	v_and_b32_sdwa v18, v1, v180 dst_sel:DWORD dst_unused:UNUSED_PAD src0_sel:WORD_1 src1_sel:DWORD
	v_and_b32_sdwa v19, v0, v180 dst_sel:DWORD dst_unused:UNUSED_PAD src0_sel:WORD_1 src1_sel:DWORD
	v_add3_u32 v0, v0, v19, s3
	v_add3_u32 v1, v1, v18, s3
	v_and_b32_sdwa v18, v3, v180 dst_sel:DWORD dst_unused:UNUSED_PAD src0_sel:WORD_1 src1_sel:DWORD
	v_and_b32_sdwa v19, v2, v180 dst_sel:DWORD dst_unused:UNUSED_PAD src0_sel:WORD_1 src1_sel:DWORD
	v_add3_u32 v3, v3, v18, s3
	v_add3_u32 v2, v2, v19, s3
	v_and_b32_e32 v3, 0xffff0000, v3
	v_and_b32_e32 v2, 0xffff0000, v2
	v_or_b32_sdwa v1, v3, v1 dst_sel:DWORD dst_unused:UNUSED_PAD src0_sel:DWORD src1_sel:WORD_1
	v_or_b32_sdwa v0, v2, v0 dst_sel:DWORD dst_unused:UNUSED_PAD src0_sel:DWORD src1_sel:WORD_1
	v_pk_mul_f32 v[2:3], v[16:17], v[30:31] op_sel_hi:[1,0]
	v_pk_mul_f32 v[16:17], v[22:23], v[30:31] op_sel_hi:[1,0]
	v_pk_mul_f32 v[2:3], v[20:21], v[2:3]
	v_pk_mul_f32 v[6:7], v[6:7], v[16:17]
	v_pk_mul_f32 v[2:3], v[2:3], v[36:37]
	v_pk_mul_f32 v[6:7], v[6:7], v[38:39]
	v_and_b32_sdwa v16, v3, v180 dst_sel:DWORD dst_unused:UNUSED_PAD src0_sel:WORD_1 src1_sel:DWORD
	v_and_b32_sdwa v17, v2, v180 dst_sel:DWORD dst_unused:UNUSED_PAD src0_sel:WORD_1 src1_sel:DWORD
	v_add3_u32 v2, v2, v17, s3
	v_add3_u32 v3, v3, v16, s3
	v_and_b32_sdwa v16, v7, v180 dst_sel:DWORD dst_unused:UNUSED_PAD src0_sel:WORD_1 src1_sel:DWORD
	v_and_b32_sdwa v17, v6, v180 dst_sel:DWORD dst_unused:UNUSED_PAD src0_sel:WORD_1 src1_sel:DWORD
	v_add3_u32 v7, v7, v16, s3
	v_add3_u32 v6, v6, v17, s3
	v_and_b32_e32 v7, 0xffff0000, v7
	v_and_b32_e32 v6, 0xffff0000, v6
	v_pk_mul_f32 v[4:5], v[4:5], v[30:31] op_sel_hi:[1,0]
	v_or_b32_sdwa v3, v7, v3 dst_sel:DWORD dst_unused:UNUSED_PAD src0_sel:DWORD src1_sel:WORD_1
	v_or_b32_sdwa v2, v6, v2 dst_sel:DWORD dst_unused:UNUSED_PAD src0_sel:DWORD src1_sel:WORD_1
	v_pk_mul_f32 v[4:5], v[26:27], v[4:5]
	v_pk_mul_f32 v[6:7], v[24:25], v[30:31] op_sel_hi:[1,0]
	v_pk_mul_f32 v[4:5], v[4:5], v[40:41]
	v_pk_mul_f32 v[6:7], v[6:7], v[14:15]
	v_and_b32_sdwa v14, v5, v180 dst_sel:DWORD dst_unused:UNUSED_PAD src0_sel:WORD_1 src1_sel:DWORD
	v_pk_mul_f32 v[6:7], v[6:7], v[42:43]
	v_and_b32_sdwa v15, v4, v180 dst_sel:DWORD dst_unused:UNUSED_PAD src0_sel:WORD_1 src1_sel:DWORD
	v_add3_u32 v4, v4, v15, s3
	v_add3_u32 v5, v5, v14, s3
	v_and_b32_sdwa v14, v7, v180 dst_sel:DWORD dst_unused:UNUSED_PAD src0_sel:WORD_1 src1_sel:DWORD
	v_and_b32_sdwa v15, v6, v180 dst_sel:DWORD dst_unused:UNUSED_PAD src0_sel:WORD_1 src1_sel:DWORD
	v_add3_u32 v7, v7, v14, s3
	v_add3_u32 v6, v6, v15, s3
	v_and_b32_e32 v7, 0xffff0000, v7
	v_and_b32_e32 v6, 0xffff0000, v6
	v_or_b32_sdwa v5, v7, v5 dst_sel:DWORD dst_unused:UNUSED_PAD src0_sel:DWORD src1_sel:WORD_1
	v_or_b32_sdwa v4, v6, v4 dst_sel:DWORD dst_unused:UNUSED_PAD src0_sel:DWORD src1_sel:WORD_1
	v_pk_mul_f32 v[6:7], v[12:13], v[30:31] op_sel_hi:[1,0]
	v_mov_b32_e32 v12, v8
	v_mov_b32_e32 v13, v10
	v_pk_mul_f32 v[6:7], v[6:7], v[12:13]
	v_pk_mul_f32 v[12:13], v[28:29], v[30:31] op_sel_hi:[1,0]
	v_mov_b32_e32 v10, v9
	v_pk_mul_f32 v[6:7], v[6:7], v[44:45]
	v_pk_mul_f32 v[8:9], v[12:13], v[10:11]
	v_and_b32_sdwa v10, v7, v180 dst_sel:DWORD dst_unused:UNUSED_PAD src0_sel:WORD_1 src1_sel:DWORD
	v_pk_mul_f32 v[8:9], v[8:9], v[46:47]
	v_and_b32_sdwa v11, v6, v180 dst_sel:DWORD dst_unused:UNUSED_PAD src0_sel:WORD_1 src1_sel:DWORD
	v_add3_u32 v6, v6, v11, s3
	v_add3_u32 v7, v7, v10, s3
	v_and_b32_sdwa v10, v9, v180 dst_sel:DWORD dst_unused:UNUSED_PAD src0_sel:WORD_1 src1_sel:DWORD
	v_and_b32_sdwa v11, v8, v180 dst_sel:DWORD dst_unused:UNUSED_PAD src0_sel:WORD_1 src1_sel:DWORD
	v_add3_u32 v9, v9, v10, s3
	v_add3_u32 v8, v8, v11, s3
	v_and_b32_e32 v9, 0xffff0000, v9
	v_and_b32_e32 v8, 0xffff0000, v8
	v_or_b32_sdwa v7, v9, v7 dst_sel:DWORD dst_unused:UNUSED_PAD src0_sel:DWORD src1_sel:WORD_1
	v_or_b32_sdwa v6, v8, v6 dst_sel:DWORD dst_unused:UNUSED_PAD src0_sel:DWORD src1_sel:WORD_1
	global_store_dwordx4 v[48:49], v[0:3], off offset:1024
	global_store_dwordx4 v[48:49], v[4:7], off offset:1040
	s_barrier

; __device__ __forceinline__ unsigned pk2(float lo, float hi) { return f2bf(lo) | (f2bf(hi) << 16); }
; __device__ __forceinline__ float bflo(unsigned w) { return __uint_as_float(w << 16); }
; __device__ __forceinline__ float bfhi(unsigned w) { return __uint_as_float(w & 0xffff0000u); }
; __global__ void __launch_bounds__(512, 2) mega(Params p) {
;     ...
;           { const float4 s4 = *(const float4*)(sw + lane * 4); const int vh = lane >> 5, e = (lane & 31) * 4, lim = nrow * 4;
;             for (int it0 = gw; it0 < lim; it0 += 4 * apn) {
;                 float4 o0[4], o1[4]; uint2 zw[4];
; #pragma unroll
;                 for (int q = 0; q < 4; ++q) { const int it = it0 + q * apn; const int itc = it < lim ? it : it0; const int row = itc >> 2, h = itc & 3;
;                     o0[q] = *(const float4*)(AO + (size_t)row * DM + (h * 4 + vh) * 128 + e); o1[q] = *(const float4*)(AO + (size_t)row * DM + (h * 4 + 2 + vh) * 128 + e);
;                     zw[q] = *(const uint2*)(P + (size_t)row * PST + C_CZ + h * 256 + lane * 4); }
;                 asm volatile("" ::: "memory");
; #pragma unroll
;                 for (int q = 0; q < 4; ++q) { const int it = it0 + q * apn; const int row = it >> 2, h = it & 3;
;                     const float d0 = o0[q].x - lam * o1[q].x, d1 = o0[q].y - lam * o1[q].y, d2 = o0[q].z - lam * o1[q].z, d3 = o0[q].w - lam * o1[q].w;
;                     const float rs = rsqrtf(wave_sum(d0 * d0 + d1 * d1 + d2 * d2 + d3 * d3) * (1.f / 256.f) + EPS) * li1;
;                     uint2 o; o.x = pk2(d0 * rs * s4.x * bflo(zw[q].x), d1 * rs * s4.y * bfhi(zw[q].x)); o.y = pk2(d2 * rs * s4.z * bflo(zw[q].y), d3 * rs * s4.w * bfhi(zw[q].y));
;                     if (it < lim) *(uint2*)(Y + (size_t)row * DM + 1024 + h * 256 + lane * 4) = o; } } } }
.LBB0_1174:
	v_ashrrev_i32_e32 v42, 2, v21
	v_mov_b64_e32 v[6:7], s[78:79]
	s_waitcnt lgkmcnt(0)
	v_mad_i64_i32 v[4:5], s[0:1], v42, s93, v[6:7]
	v_mov_b32_e32 v27, v165
	v_lshl_add_u64 v[4:5], v[4:5], 0, v[26:27]
	v_lshlrev_b32_e32 v164, 1, v20
	v_ashrrev_i32_e32 v43, 31, v42
	v_lshl_add_u64 v[4:5], v[4:5], 0, v[164:165]
	v_lshlrev_b64 v[2:3], 13, v[42:43]
	v_add_co_u32_e32 v4, vcc, s67, v4
	v_lshl_add_u64 v[2:3], v[24:25], 0, v[2:3]
	s_nop 0
	v_addc_co_u32_e32 v5, vcc, 0, v5, vcc
	global_load_dwordx2 v[34:35], v[4:5], off offset:2048
	global_load_dwordx4 v[38:41], v[2:3], off
	global_load_dwordx4 v[50:53], v[2:3], off offset:1024
	v_add_u32_e32 v47, s7, v21
	v_cmp_gt_i32_e64 s[40:41], s6, v47
	v_add_u32_e32 v48, s13, v21
	v_cmp_gt_i32_e64 s[38:39], s6, v48
	v_cndmask_b32_e64 v8, v21, v47, s[40:41]
	v_ashrrev_i32_e32 v2, 2, v8
	v_ashrrev_i32_e32 v3, 31, v2
	v_lshlrev_b64 v[4:5], 13, v[2:3]
	v_lshlrev_b32_e32 v3, 9, v8
	v_and_b32_e32 v8, 0x600, v3
	v_or_b32_e32 v3, v8, v45
	v_readlane_b32 s18, v251, 42
	v_lshlrev_b32_e32 v10, 2, v3
	v_mad_i64_i32 v[2:3], s[0:1], v2, s93, v[6:7]
	v_mov_b32_e32 v9, v165
	v_cndmask_b32_e64 v12, v21, v48, s[38:39]
	v_readlane_b32 s19, v251, 43
	v_lshl_add_u64 v[2:3], v[2:3], 0, v[8:9]
	v_ashrrev_i32_e32 v8, 2, v12
	v_lshl_add_u64 v[4:5], s[18:19], 0, v[4:5]
	v_mov_b32_e32 v11, v165
	v_ashrrev_i32_e32 v9, 31, v8
	v_lshl_add_u64 v[4:5], v[4:5], 0, v[10:11]
	v_lshlrev_b64 v[10:11], 13, v[8:9]
	v_lshlrev_b32_e32 v9, 9, v12
	s_waitcnt vmcnt(4)
	v_and_b32_e32 v30, 0x600, v9
	v_or_b32_e32 v9, v30, v45
	v_lshl_add_u64 v[2:3], v[2:3], 0, v[164:165]
	v_lshlrev_b32_e32 v12, 2, v9
	v_mad_i64_i32 v[8:9], s[0:1], v8, s93, v[6:7]
	v_mov_b32_e32 v31, v165
	v_add_co_u32_e32 v2, vcc, s67, v2
	v_lshl_add_u64 v[8:9], v[8:9], 0, v[30:31]
	s_nop 0
	v_addc_co_u32_e32 v3, vcc, 0, v3, vcc
	v_lshl_add_u64 v[8:9], v[8:9], 0, v[164:165]
	v_add_co_u32_e32 v8, vcc, s67, v8
	s_mul_i32 s0, s7, 3
	s_nop 0
	v_addc_co_u32_e32 v9, vcc, 0, v9, vcc
	v_add_u32_e32 v27, s0, v21
	v_cmp_gt_i32_e32 vcc, s6, v27
	v_lshl_add_u64 v[10:11], s[18:19], 0, v[10:11]
	v_mov_b32_e32 v13, v165
	v_cndmask_b32_e32 v36, v21, v27, vcc
	v_mov_b32_e32 v29, v165
	v_lshl_add_u64 v[10:11], v[10:11], 0, v[12:13]
	v_ashrrev_i32_e32 v30, 2, v36
	v_lshl_add_u64 v[4:5], v[4:5], 0, v[28:29]
	v_lshl_add_u64 v[14:15], v[10:11], 0, v[28:29]
	v_ashrrev_i32_e32 v31, 31, v30
	global_load_dwordx4 v[10:13], v[14:15], off
	s_nop 0
	global_load_dwordx4 v[14:17], v[14:15], off offset:1024
	v_lshlrev_b64 v[32:33], 13, v[30:31]
	v_lshlrev_b32_e32 v31, 9, v36
	global_load_dwordx2 v[36:37], v[2:3], off offset:2048
	global_load_dwordx4 v[54:57], v[4:5], off offset:1024
	global_load_dwordx4 v[58:61], v[4:5], off
	v_and_b32_e32 v62, 0x600, v31
	v_mad_i64_i32 v[6:7], s[0:1], v30, s93, v[6:7]
	v_mov_b32_e32 v63, v165
	v_or_b32_e32 v31, v62, v45
	v_lshl_add_u64 v[6:7], v[6:7], 0, v[62:63]
	v_lshl_add_u64 v[32:33], s[18:19], 0, v[32:33]
	v_lshlrev_b32_e32 v64, 2, v31
	v_mov_b32_e32 v65, v165
	v_lshl_add_u64 v[6:7], v[6:7], 0, v[164:165]
	v_lshl_add_u64 v[2:3], v[32:33], 0, v[64:65]
	v_add_co_u32_e64 v30, s[0:1], s67, v6
	v_lshl_add_u64 v[64:65], v[2:3], 0, v[28:29]
	s_nop 0
	v_addc_co_u32_e64 v31, s[0:1], 0, v7, s[0:1]
	global_load_dwordx2 v[32:33], v[8:9], off offset:2048
	global_load_dwordx4 v[2:5], v[64:65], off
	s_nop 0
	global_load_dwordx4 v[6:9], v[64:65], off offset:1024
	s_nop 0
	global_load_dwordx2 v[30:31], v[30:31], off offset:2048
	s_waitcnt vmcnt(10)
	v_mov_b32_e32 v64, v38
	s_waitcnt vmcnt(9)
	v_mov_b32_e32 v62, v50
	v_mov_b32_e32 v63, v52
	v_mov_b32_e32 v65, v40
	v_mov_b32_e32 v52, v51
	v_mov_b32_e32 v40, v39
	v_pk_fma_f32 v[62:63], v[18:19], v[62:63], v[64:65] neg_lo:[1,0,0] neg_hi:[1,0,0]
	v_pk_fma_f32 v[64:65], v[18:19], v[52:53], v[40:41] neg_lo:[1,0,0] neg_hi:[1,0,0]
	v_mov_b32_e32 v38, v62
	v_mov_b32_e32 v39, v64
	v_pk_mul_f32 v[38:39], v[38:39], v[38:39]
	v_mov_b32_e32 v40, v63
	v_mov_b32_e32 v41, v65
	v_pk_mul_f32 v[40:41], v[40:41], v[40:41]
	v_add_f32_e32 v29, v38, v39
	v_add_f32_e32 v29, v29, v40
	v_cmp_lt_i32_e64 s[0:1], v178, v172
	v_add_f32_e32 v38, v29, v41
	v_lshlrev_b64 v[42:43], 12, v[42:43]
	v_cndmask_b32_e64 v29, v171, v178, s[0:1]
	v_lshlrev_b32_e32 v29, 2, v29
	v_cmp_lt_i32_e64 s[0:1], v177, v172
	v_lshl_add_u64 v[40:41], s[24:25], 0, v[42:43]
	v_xor_b32_e32 v52, 16, v171
	v_cndmask_b32_e64 v42, v171, v177, s[0:1]
	v_lshlrev_b32_e32 v49, 2, v42
	s_waitcnt lgkmcnt(0)
	s_nop 1
	v_add_f32_dpp v38, v38, v38 quad_perm:[1,0,3,2] row_mask:0xf bank_mask:0xf
	v_cmp_lt_i32_e64 s[0:1], v176, v172
	v_and_b32_e32 v42, 0x300, v46
	v_xor_b32_e32 v53, 32, v171
	v_cndmask_b32_e64 v43, v171, v176, s[0:1]
	v_lshlrev_b32_e32 v50, 2, v43
	s_waitcnt lgkmcnt(0)
	s_nop 1
	v_add_f32_dpp v39, v38, v38 quad_perm:[2,3,0,1] row_mask:0xf bank_mask:0xf
	v_lshlrev_b32_e32 v38, 1, v42
	v_xor_b32_e32 v42, 8, v171
	v_cmp_lt_i32_e64 s[0:1], v42, v172
	v_and_b32_e32 v69, 0xffff0000, v35
	v_and_b32_e32 v68, 0xffff0000, v34
	v_cndmask_b32_e64 v42, v171, v42, s[0:1]
	v_lshlrev_b32_e32 v51, 2, v42
	s_waitcnt lgkmcnt(0)
	s_nop 1
	v_add_f32_dpp v42, v39, v39 row_half_mirror row_mask:0xf bank_mask:0xf
	v_cmp_lt_i32_e64 s[0:1], v52, v172
	v_mov_b32_e32 v39, v165
	v_lshl_add_u64 v[40:41], v[40:41], 0, v[38:39]
	v_cndmask_b32_e64 v52, v171, v52, s[0:1]
	v_lshlrev_b32_e32 v52, 2, v52
	s_waitcnt lgkmcnt(0)
	s_nop 1
	v_add_f32_dpp v42, v42, v42 row_mirror row_mask:0xf bank_mask:0xf
	v_cmp_lt_i32_e64 s[0:1], v53, v172
	v_lshl_add_u64 v[66:67], v[40:41], 0, v[164:165]
	v_lshlrev_b32_e32 v35, 16, v35
	v_cndmask_b32_e64 v53, v171, v53, s[0:1]
	v_lshlrev_b32_e32 v53, 2, v53
	s_waitcnt lgkmcnt(0)
; __device__ __forceinline__ unsigned pk2(float lo, float hi) { return f2bf(lo) | (f2bf(hi) << 16); }
; __device__ __forceinline__ float bflo(unsigned w) { return __uint_as_float(w << 16); }
; __device__ __forceinline__ float bfhi(unsigned w) { return __uint_as_float(w & 0xffff0000u); }
; __global__ void __launch_bounds__(512, 2) mega(Params p) {
;     ...
;                 for (int q = 0; q < 4; ++q) { const int it = it0 + q * apn; const int row = it >> 2, h = it & 3;
;                     const float d0 = o0[q].x - lam * o1[q].x, d1 = o0[q].y - lam * o1[q].y, d2 = o0[q].z - lam * o1[q].z, d3 = o0[q].w - lam * o1[q].w;
;                     const float rs = rsqrtf(wave_sum(d0 * d0 + d1 * d1 + d2 * d2 + d3 * d3) * (1.f / 256.f) + EPS) * li1;
;                     uint2 o; o.x = pk2(d0 * rs * s4.x * bflo(zw[q].x), d1 * rs * s4.y * bfhi(zw[q].x)); o.y = pk2(d2 * rs * s4.z * bflo(zw[q].y), d3 * rs * s4.w * bfhi(zw[q].y));
;                     if (it < lim) *(uint2*)(Y + (size_t)row * DM + 1024 + h * 256 + lane * 4) = o; } } } }
	v_mov_b32_e32 v43, v42
	s_nop 1
	v_permlane16_swap_b32_e32 v42, v43
	v_add_f32_e32 v42, v42, v43
	v_lshlrev_b32_e32 v34, 16, v34
	s_waitcnt lgkmcnt(0)
	v_mov_b32_e32 v40, v42
	v_mov_b32_e32 v43, v42
	s_nop 1
	v_permlane32_swap_b32_e32 v40, v43
	v_add_f32_e32 v40, v40, v43
	v_fmamk_f32 v40, v40, 0x3b800000, v179
	v_mul_f32_e32 v41, 0x4b800000, v40
	v_cmp_gt_f32_e64 s[0:1], s91, v40
	s_waitcnt vmcnt(4)
	v_mov_b32_e32 v42, v58
	v_mov_b32_e32 v43, v60
	v_cndmask_b32_e64 v40, v40, v41, s[0:1]
	v_rsq_f32_e32 v70, v40
	v_mov_b32_e32 v40, v54
	v_mov_b32_e32 v41, v56
	v_mov_b32_e32 v56, v55
	v_mov_b32_e32 v60, v59
	v_pk_fma_f32 v[40:41], v[18:19], v[40:41], v[42:43] neg_lo:[1,0,0] neg_hi:[1,0,0]
	v_pk_fma_f32 v[42:43], v[18:19], v[56:57], v[60:61] neg_lo:[1,0,0] neg_hi:[1,0,0]
	v_pk_mul_f32 v[54:55], v[40:41], v[40:41]
	v_pk_mul_f32 v[56:57], v[42:43], v[42:43]
	s_nop 0
	v_add_f32_e32 v54, v54, v56
	v_add_f32_e32 v54, v54, v55
	v_add_f32_e32 v54, v54, v57
	v_mul_f32_e32 v56, 0x45800000, v70
	v_cndmask_b32_e64 v56, v70, v56, s[0:1]
	s_waitcnt lgkmcnt(0)
	s_nop 1
	v_add_f32_dpp v55, v54, v54 quad_perm:[1,0,3,2] row_mask:0xf bank_mask:0xf
	v_mul_f32_e32 v54, v44, v56
	v_pk_mul_f32 v[56:57], v[64:65], v[54:55] op_sel_hi:[1,0]
	s_waitcnt lgkmcnt(0)
	s_nop 1
	v_add_f32_dpp v55, v55, v55 quad_perm:[2,3,0,1] row_mask:0xf bank_mask:0xf
	v_pk_mul_f32 v[56:57], v[22:23], v[56:57]
	s_waitcnt lgkmcnt(0)
	s_nop 1
	v_add_f32_dpp v58, v55, v55 row_half_mirror row_mask:0xf bank_mask:0xf
	v_pk_mul_f32 v[56:57], v[56:57], v[68:69]
	v_pk_mul_f32 v[54:55], v[62:63], v[54:55] op_sel_hi:[1,0]
	v_and_b32_sdwa v59, v57, v180 dst_sel:DWORD dst_unused:UNUSED_PAD src0_sel:WORD_1 src1_sel:DWORD
	v_add3_u32 v57, v57, v59, s3
	v_pk_mul_f32 v[54:55], v[0:1], v[54:55]
	v_and_b32_sdwa v60, v56, v180 dst_sel:DWORD dst_unused:UNUSED_PAD src0_sel:WORD_1 src1_sel:DWORD
	v_pk_mul_f32 v[54:55], v[54:55], v[34:35]
	v_add3_u32 v56, v56, v60, s3
	s_waitcnt lgkmcnt(0)
	s_nop 1
	v_add_f32_dpp v58, v58, v58 row_mirror row_mask:0xf bank_mask:0xf
	v_and_b32_sdwa v34, v54, v180 dst_sel:DWORD dst_unused:UNUSED_PAD src0_sel:WORD_1 src1_sel:DWORD
	v_add3_u32 v54, v54, v34, s3
	v_and_b32_sdwa v60, v55, v180 dst_sel:DWORD dst_unused:UNUSED_PAD src0_sel:WORD_1 src1_sel:DWORD
	v_and_b32_e32 v57, 0xffff0000, v57
	s_waitcnt lgkmcnt(0)
	v_mov_b32_e32 v34, v58
	v_mov_b32_e32 v59, v58
	s_nop 1
	v_permlane16_swap_b32_e32 v34, v59
	v_add_f32_e32 v34, v34, v59
	ds_bpermute_b32 v35, v53, v34
	v_and_b32_e32 v56, 0xffff0000, v56
	v_add3_u32 v55, v55, v60, s3
	v_or_b32_sdwa v55, v57, v55 dst_sel:DWORD dst_unused:UNUSED_PAD src0_sel:DWORD src1_sel:WORD_1
	v_or_b32_sdwa v54, v56, v54 dst_sel:DWORD dst_unused:UNUSED_PAD src0_sel:DWORD src1_sel:WORD_1
	global_store_dwordx2 v[66:67], v[54:55], off offset:2048
	s_and_saveexec_b64 s[44:45], s[40:41]
	s_cbranch_execz .LBB0_1176
	s_waitcnt lgkmcnt(0)
	v_add_f32_e32 v34, v34, v35
	v_fmamk_f32 v34, v34, 0x3b800000, v179
	v_mul_f32_e32 v35, 0x4b800000, v34
	v_cmp_gt_f32_e64 s[0:1], s91, v34
	s_nop 1
	v_cndmask_b32_e64 v34, v34, v35, s[0:1]
	v_rsq_f32_e32 v54, v34
	v_ashrrev_i32_e32 v34, 2, v47
	v_ashrrev_i32_e32 v35, 31, v34
	v_lshlrev_b64 v[34:35], 12, v[34:35]
	v_mul_f32_e32 v47, 0x45800000, v54
	v_cndmask_b32_e64 v47, v54, v47, s[0:1]
	v_mul_f32_e32 v54, v44, v47
	v_lshl_add_u64 v[34:35], s[24:25], 0, v[34:35]
	v_lshl_add_u64 v[34:35], v[34:35], 0, v[38:39]
	v_pk_mul_f32 v[38:39], v[42:43], v[54:55] op_sel_hi:[1,0]
	v_and_b32_e32 v43, 0xffff0000, v37
	v_pk_mul_f32 v[38:39], v[22:23], v[38:39]
	v_and_b32_e32 v42, 0xffff0000, v36
	v_pk_mul_f32 v[38:39], v[38:39], v[42:43]
	v_lshlrev_b32_e32 v37, 16, v37
	v_and_b32_sdwa v42, v39, v180 dst_sel:DWORD dst_unused:UNUSED_PAD src0_sel:WORD_1 src1_sel:DWORD
	v_and_b32_sdwa v43, v38, v180 dst_sel:DWORD dst_unused:UNUSED_PAD src0_sel:WORD_1 src1_sel:DWORD
	v_add3_u32 v39, v39, v42, s3
	v_add3_u32 v38, v38, v43, s3
	v_and_b32_e32 v42, 0xffff0000, v39
	v_and_b32_e32 v43, 0xffff0000, v38
	v_pk_mul_f32 v[38:39], v[40:41], v[54:55] op_sel_hi:[1,0]
	v_lshlrev_b32_e32 v36, 16, v36
	v_pk_mul_f32 v[38:39], v[0:1], v[38:39]
	v_lshl_add_u64 v[34:35], v[34:35], 0, v[164:165]
	v_pk_mul_f32 v[36:37], v[38:39], v[36:37]
	s_nop 0
	v_and_b32_sdwa v38, v37, v180 dst_sel:DWORD dst_unused:UNUSED_PAD src0_sel:WORD_1 src1_sel:DWORD
	v_and_b32_sdwa v39, v36, v180 dst_sel:DWORD dst_unused:UNUSED_PAD src0_sel:WORD_1 src1_sel:DWORD
	v_add3_u32 v36, v36, v39, s3
	v_add3_u32 v37, v37, v38, s3
	v_or_b32_sdwa v37, v42, v37 dst_sel:DWORD dst_unused:UNUSED_PAD src0_sel:DWORD src1_sel:WORD_1
	v_or_b32_sdwa v36, v43, v36 dst_sel:DWORD dst_unused:UNUSED_PAD src0_sel:DWORD src1_sel:WORD_1
	global_store_dwordx2 v[34:35], v[36:37], off offset:2048
; __device__ __forceinline__ unsigned pk2(float lo, float hi) { return f2bf(lo) | (f2bf(hi) << 16); }
; __device__ __forceinline__ float bflo(unsigned w) { return __uint_as_float(w << 16); }
; __device__ __forceinline__ float bfhi(unsigned w) { return __uint_as_float(w & 0xffff0000u); }
; __global__ void __launch_bounds__(512, 2) mega(Params p) {
;     ...
;                 for (int q = 0; q < 4; ++q) { const int it = it0 + q * apn; const int row = it >> 2, h = it & 3;
;                     const float d0 = o0[q].x - lam * o1[q].x, d1 = o0[q].y - lam * o1[q].y, d2 = o0[q].z - lam * o1[q].z, d3 = o0[q].w - lam * o1[q].w;
;                     const float rs = rsqrtf(wave_sum(d0 * d0 + d1 * d1 + d2 * d2 + d3 * d3) * (1.f / 256.f) + EPS) * li1;
;                     uint2 o; o.x = pk2(d0 * rs * s4.x * bflo(zw[q].x), d1 * rs * s4.y * bfhi(zw[q].x)); o.y = pk2(d2 * rs * s4.z * bflo(zw[q].y), d3 * rs * s4.w * bfhi(zw[q].y));
;                     if (it < lim) *(uint2*)(Y + (size_t)row * DM + 1024 + h * 256 + lane * 4) = o; } } } }
.LBB0_1176:
	s_or_b64 exec, exec, s[44:45]
	v_mov_b32_e32 v34, v14
	s_waitcnt lgkmcnt(0)
	v_mov_b32_e32 v35, v16
	v_mov_b32_e32 v16, v15
	v_mov_b32_e32 v14, v10
	v_mov_b32_e32 v15, v12
	v_mov_b32_e32 v12, v11
	v_pk_fma_f32 v[14:15], v[18:19], v[34:35], v[14:15] neg_lo:[1,0,0] neg_hi:[1,0,0]
	v_pk_fma_f32 v[10:11], v[18:19], v[16:17], v[12:13] neg_lo:[1,0,0] neg_hi:[1,0,0]
	v_pk_mul_f32 v[12:13], v[14:15], v[14:15]
	v_pk_mul_f32 v[16:17], v[10:11], v[10:11]
	s_nop 0
	v_add_f32_e32 v12, v12, v16
	v_add_f32_e32 v12, v12, v13
	v_add_f32_e32 v12, v12, v17
	s_waitcnt lgkmcnt(0)
	s_nop 1
	v_add_f32_dpp v12, v12, v12 quad_perm:[1,0,3,2] row_mask:0xf bank_mask:0xf
	s_waitcnt lgkmcnt(0)
	s_nop 1
	v_add_f32_dpp v12, v12, v12 quad_perm:[2,3,0,1] row_mask:0xf bank_mask:0xf
	s_waitcnt lgkmcnt(0)
	s_nop 1
	v_add_f32_dpp v12, v12, v12 row_half_mirror row_mask:0xf bank_mask:0xf
	s_waitcnt lgkmcnt(0)
	s_nop 1
	v_add_f32_dpp v12, v12, v12 row_mirror row_mask:0xf bank_mask:0xf
	s_waitcnt lgkmcnt(0)
	v_mov_b32_e32 v13, v12
	s_nop 1
	v_permlane16_swap_b32_e32 v12, v13
	v_add_f32_e32 v12, v12, v13
	ds_bpermute_b32 v13, v53, v12
	s_and_saveexec_b64 s[40:41], s[38:39]
	s_cbranch_execz .LBB0_1178
	s_waitcnt lgkmcnt(0)
	v_add_f32_e32 v12, v12, v13
	v_fmamk_f32 v12, v12, 0x3b800000, v179
	v_mul_f32_e32 v13, 0x4b800000, v12
	v_cmp_gt_f32_e64 s[0:1], s91, v12
	v_mov_b32_e32 v35, v165
	s_nop 0
	v_cndmask_b32_e64 v12, v12, v13, s[0:1]
	v_rsq_f32_e32 v16, v12
	v_ashrrev_i32_e32 v12, 2, v48
	v_ashrrev_i32_e32 v13, 31, v12
	v_lshlrev_b64 v[12:13], 12, v[12:13]
	v_mul_f32_e32 v17, 0x45800000, v16
	v_cndmask_b32_e64 v16, v16, v17, s[0:1]
	v_add_u32_e32 v17, s16, v46
	v_mul_f32_e32 v16, v44, v16
	v_and_b32_e32 v17, 0x300, v17
	v_lshl_add_u64 v[12:13], s[24:25], 0, v[12:13]
	v_lshlrev_b32_e32 v34, 1, v17
	v_pk_mul_f32 v[10:11], v[10:11], v[16:17] op_sel_hi:[1,0]
	v_lshl_add_u64 v[12:13], v[12:13], 0, v[34:35]
	v_pk_mul_f32 v[10:11], v[22:23], v[10:11]
	s_waitcnt vmcnt(4)
	v_and_b32_e32 v35, 0xffff0000, v33
	v_and_b32_e32 v34, 0xffff0000, v32
	v_pk_mul_f32 v[10:11], v[10:11], v[34:35]
	v_lshl_add_u64 v[12:13], v[12:13], 0, v[164:165]
	v_and_b32_sdwa v17, v11, v180 dst_sel:DWORD dst_unused:UNUSED_PAD src0_sel:WORD_1 src1_sel:DWORD
	v_and_b32_sdwa v34, v10, v180 dst_sel:DWORD dst_unused:UNUSED_PAD src0_sel:WORD_1 src1_sel:DWORD
	v_add3_u32 v11, v11, v17, s3
	v_add3_u32 v10, v10, v34, s3
	v_and_b32_e32 v17, 0xffff0000, v11
	v_and_b32_e32 v34, 0xffff0000, v10
	v_pk_mul_f32 v[10:11], v[14:15], v[16:17] op_sel_hi:[1,0]
	v_lshlrev_b32_e32 v15, 16, v33
	v_pk_mul_f32 v[10:11], v[0:1], v[10:11]
	v_lshlrev_b32_e32 v14, 16, v32
	v_pk_mul_f32 v[10:11], v[10:11], v[14:15]
	s_nop 0
	v_and_b32_sdwa v14, v11, v180 dst_sel:DWORD dst_unused:UNUSED_PAD src0_sel:WORD_1 src1_sel:DWORD
	v_and_b32_sdwa v15, v10, v180 dst_sel:DWORD dst_unused:UNUSED_PAD src0_sel:WORD_1 src1_sel:DWORD
	v_add3_u32 v10, v10, v15, s3
	v_add3_u32 v11, v11, v14, s3
	v_or_b32_sdwa v11, v17, v11 dst_sel:DWORD dst_unused:UNUSED_PAD src0_sel:DWORD src1_sel:WORD_1
	v_or_b32_sdwa v10, v34, v10 dst_sel:DWORD dst_unused:UNUSED_PAD src0_sel:DWORD src1_sel:WORD_1
	global_store_dwordx2 v[12:13], v[10:11], off offset:2048
.LBB0_1178:
	s_or_b64 exec, exec, s[40:41]
	s_waitcnt vmcnt(2)
	v_mov_b32_e32 v10, v6
	v_mov_b32_e32 v11, v8
	v_mov_b32_e32 v8, v7
	v_mov_b32_e32 v6, v2
	v_mov_b32_e32 v7, v4
	v_mov_b32_e32 v4, v3
	v_pk_fma_f32 v[6:7], v[18:19], v[10:11], v[6:7] neg_lo:[1,0,0] neg_hi:[1,0,0]
	v_pk_fma_f32 v[2:3], v[18:19], v[8:9], v[4:5] neg_lo:[1,0,0] neg_hi:[1,0,0]
	v_pk_mul_f32 v[4:5], v[6:7], v[6:7]
	v_pk_mul_f32 v[8:9], v[2:3], v[2:3]
	s_nop 0
	v_add_f32_e32 v4, v4, v8
	v_add_f32_e32 v4, v4, v5
	v_add_f32_e32 v4, v4, v9
	s_waitcnt lgkmcnt(0)
	s_nop 1
	v_add_f32_dpp v4, v4, v4 quad_perm:[1,0,3,2] row_mask:0xf bank_mask:0xf
	s_waitcnt lgkmcnt(0)
	s_nop 1
	v_add_f32_dpp v4, v4, v4 quad_perm:[2,3,0,1] row_mask:0xf bank_mask:0xf
	s_waitcnt lgkmcnt(0)
	s_nop 1
	v_add_f32_dpp v4, v4, v4 row_half_mirror row_mask:0xf bank_mask:0xf
	s_waitcnt lgkmcnt(0)
	s_nop 1
	v_add_f32_dpp v4, v4, v4 row_mirror row_mask:0xf bank_mask:0xf
	s_waitcnt lgkmcnt(0)
	v_mov_b32_e32 v5, v4
	s_nop 1
	v_permlane16_swap_b32_e32 v4, v5
	v_add_f32_e32 v4, v4, v5
	ds_bpermute_b32 v5, v53, v4
	s_and_saveexec_b64 s[0:1], vcc
	s_cbranch_execz .LBB0_1173
	s_waitcnt lgkmcnt(0)
	v_add_f32_e32 v4, v4, v5
	v_fmamk_f32 v4, v4, 0x3b800000, v179
	v_mul_f32_e32 v5, 0x4b800000, v4
	v_cmp_gt_f32_e32 vcc, s91, v4
	s_mul_i32 s17, s7, 0x300
	v_mov_b32_e32 v11, v165
	v_cndmask_b32_e32 v4, v4, v5, vcc
	v_rsq_f32_e32 v8, v4
	v_ashrrev_i32_e32 v4, 2, v27
	v_ashrrev_i32_e32 v5, 31, v4
	v_lshlrev_b64 v[4:5], 12, v[4:5]
	v_mul_f32_e32 v9, 0x45800000, v8
	v_cndmask_b32_e32 v8, v8, v9, vcc
	v_add_u32_e32 v9, s17, v46
	v_mul_f32_e32 v8, v44, v8
	v_and_b32_e32 v9, 0x300, v9
	v_lshl_add_u64 v[4:5], s[24:25], 0, v[4:5]
	v_lshlrev_b32_e32 v10, 1, v9
	v_pk_mul_f32 v[2:3], v[2:3], v[8:9] op_sel_hi:[1,0]
	v_lshl_add_u64 v[4:5], v[4:5], 0, v[10:11]
	v_pk_mul_f32 v[2:3], v[22:23], v[2:3]
	s_waitcnt vmcnt(1)
	v_and_b32_e32 v11, 0xffff0000, v31
	v_and_b32_e32 v10, 0xffff0000, v30
	v_pk_mul_f32 v[2:3], v[2:3], v[10:11]
	v_lshl_add_u64 v[4:5], v[4:5], 0, v[164:165]
	v_and_b32_sdwa v9, v3, v180 dst_sel:DWORD dst_unused:UNUSED_PAD src0_sel:WORD_1 src1_sel:DWORD
	v_and_b32_sdwa v10, v2, v180 dst_sel:DWORD dst_unused:UNUSED_PAD src0_sel:WORD_1 src1_sel:DWORD
	v_add3_u32 v3, v3, v9, s3
	v_add3_u32 v2, v2, v10, s3
	v_and_b32_e32 v9, 0xffff0000, v3
	v_and_b32_e32 v10, 0xffff0000, v2
	v_pk_mul_f32 v[2:3], v[6:7], v[8:9] op_sel_hi:[1,0]
	v_lshlrev_b32_e32 v7, 16, v31
	v_pk_mul_f32 v[2:3], v[0:1], v[2:3]
	v_lshlrev_b32_e32 v6, 16, v30
	v_pk_mul_f32 v[2:3], v[2:3], v[6:7]
	s_nop 0
	v_and_b32_sdwa v6, v3, v180 dst_sel:DWORD dst_unused:UNUSED_PAD src0_sel:WORD_1 src1_sel:DWORD
	v_and_b32_sdwa v7, v2, v180 dst_sel:DWORD dst_unused:UNUSED_PAD src0_sel:WORD_1 src1_sel:DWORD
	v_add3_u32 v2, v2, v7, s3
	v_add3_u32 v3, v3, v6, s3
	v_or_b32_sdwa v3, v9, v3 dst_sel:DWORD dst_unused:UNUSED_PAD src0_sel:DWORD src1_sel:WORD_1
	v_or_b32_sdwa v2, v10, v2 dst_sel:DWORD dst_unused:UNUSED_PAD src0_sel:DWORD src1_sel:WORD_1
	global_store_dwordx2 v[4:5], v[2:3], off offset:2048
	s_branch .LBB0_1173

; #define RETID() do { tid = tidx(); lane = tid & 63; wave = tid >> 6; gw = bid * 8 + wave; } while (0)
; __device__ __forceinline__ void final_rows(const float* X, const float* fw, float* out, int row0, int nrows, int wave, int lane) {
;     for (int row = row0 + wave; row < row0 + nrows; row += 8) {
;         const float4* xr = (const float4*)(X + (size_t)row * DM) + lane; float4 v[8]; float ss = 0.f;
; #pragma unroll
;         for (int j = 0; j < 8; ++j) { v[j] = xr[64 * j]; ss += v[j].x * v[j].x + v[j].y * v[j].y + v[j].z * v[j].z + v[j].w * v[j].w; }
;         const float r = rsqrtf(wave_sum(ss) * (1.f / DM) + EPS);
;         float4* op = (float4*)(out + (size_t)row * DM) + lane;
; #pragma unroll
;         for (int j = 0; j < 8; ++j) { const float4 w4 = *(const float4*)(fw + 4 * (lane + 64 * j)); op[64 * j] = make_float4(v[j].x * r * w4.x, v[j].y * r * w4.y, v[j].z * r * w4.z, v[j].w * r * w4.w); } }
; }
; __global__ void __launch_bounds__(512, 2) mega(Params p) {
;     ...
;           __syncthreads();
;           if (l < 3) { const float* mod1 = MOD + (size_t)(l + 1) * 2 * 6144; const float* nw1 = p.in[6] + (size_t)(l + 1) * DM;
;               norm_rows(X, nw1, mod1, H, pm * 256 + pn * 32, 32, wave, lane);
;               if (myslot < 4) { split_wait((unsigned*)(ws + WS_CTL) + CW_SPLIT2 + l * 17 * 64, bst[1], tid); RETID();
;                   norm_rows(X, nw1, mod1 + 6144, H, TL + ((int)xbar.x * 4 + myslot) * 8, 8, wave, lane); } }
;           else final_rows(X, p.in[17], p.out, pm * 256 + pn * 32, 32, wave, lane); }
.LBB0_1289:
	s_or_b64 exec, exec, s[34:35]
	v_ashrrev_i32_e32 v71, 6, v0
	v_and_b32_e32 v70, 63, v0
	s_mov_b64 s[6:7], -1
	s_and_b64 vcc, exec, s[0:1]
	v_cmp_gt_i32_e64 s[0:1], 32, v71
	s_barrier
	s_cbranch_vccz .LBB0_1294
	s_and_saveexec_b64 s[34:35], s[0:1]
	v_readlane_b32 s6, v253, 25
	s_cbranch_execz .LBB0_1293
	v_cmp_lt_i32_e32 vcc, v178, v172
	v_readlane_b32 s40, v254, 16
	v_lshlrev_b32_e32 v164, 4, v70
	v_cndmask_b32_e32 v0, v171, v178, vcc
	v_cmp_lt_i32_e32 vcc, v177, v172
	v_lshlrev_b32_e32 v72, 2, v0
	v_readlane_b32 s42, v254, 18
	v_cndmask_b32_e32 v0, v171, v177, vcc
	v_cmp_lt_i32_e32 vcc, v176, v172
	v_lshlrev_b32_e32 v73, 2, v0
	v_readlane_b32 s43, v254, 19
	v_cndmask_b32_e32 v0, v171, v176, vcc
	v_lshlrev_b32_e32 v74, 2, v0
	v_xor_b32_e32 v0, 8, v171
	v_cmp_lt_i32_e32 vcc, v0, v172
	v_lshl_add_u64 v[36:37], s[42:43], 0, v[164:165]
	s_mov_b64 s[0:1], 0x1000
	v_cndmask_b32_e32 v0, v171, v0, vcc
	v_lshlrev_b32_e32 v75, 2, v0
	v_xor_b32_e32 v0, 16, v171
	v_cmp_lt_i32_e32 vcc, v0, v172
	v_lshl_add_u64 v[38:39], v[36:37], 0, s[0:1]
	s_mov_b64 s[0:1], 0x1400
	v_cndmask_b32_e32 v0, v171, v0, vcc
	v_lshl_add_u64 v[40:41], v[36:37], 0, s[0:1]
	s_mov_b64 s[0:1], 0x1800
	v_lshlrev_b32_e32 v76, 2, v0
	v_xor_b32_e32 v0, 32, v171
	v_lshl_add_u64 v[42:43], v[36:37], 0, s[0:1]
	s_mov_b64 s[0:1], 0x1c00
	v_cmp_lt_i32_e32 vcc, v0, v172
	v_lshl_add_u64 v[44:45], v[36:37], 0, s[0:1]
	v_readlane_b32 s0, v254, 33
	v_cndmask_b32_e32 v0, v171, v0, vcc
	v_lshlrev_b32_e32 v77, 2, v0
	v_add_u32_e32 v78, s0, v71
	v_readlane_b32 s0, v254, 32
	v_readlane_b32 s44, v254, 20
	v_readlane_b32 s45, v254, 21
	v_add_u32_e32 v0, s0, v71
	v_ashrrev_i32_e32 v1, 31, v0
	v_readlane_b32 s46, v254, 22
	v_readlane_b32 s47, v254, 23
	v_lshlrev_b64 v[0:1], 13, v[0:1]
	v_lshl_add_u64 v[48:49], s[44:45], 0, v[0:1]
	v_lshl_add_u64 v[46:47], s[46:47], 0, v[0:1]
	s_mov_b64 s[0:1], 0
	v_readlane_b32 s41, v254, 17
	global_load_dwordx4 v[182:185], v[36:37], off
	global_load_dwordx4 v[186:189], v[36:37], off offset:1024
	global_load_dwordx4 v[190:193], v[36:37], off offset:2048
	global_load_dwordx4 v[194:197], v[36:37], off offset:3072
	global_load_dwordx4 v[198:201], v[38:39], off
	global_load_dwordx4 v[202:205], v[40:41], off
	global_load_dwordx4 v[206:209], v[42:43], off
	global_load_dwordx4 v[210:213], v[44:45], off
	v_lshl_add_u64 v[80:81], v[46:47], 0, v[164:165]
	v_add_co_u32_e32 v84, vcc, s17, v80
	s_nop 1
	v_addc_co_u32_e32 v85, vcc, 0, v81, vcc
	v_add_co_u32_e32 v82, vcc, 0xa000000, v80
	s_nop 1
	v_addc_co_u32_e32 v83, vcc, 0, v81, vcc
	global_load_dwordx4 v[100:103], v[82:83], off
	global_load_dwordx4 v[104:107], v[82:83], off offset:1024
	global_load_dwordx4 v[108:111], v[82:83], off offset:2048
	global_load_dwordx4 v[112:115], v[82:83], off offset:3072
	global_load_dwordx4 v[116:119], v[84:85], off
	global_load_dwordx4 v[120:123], v[84:85], off offset:1024
	global_load_dwordx4 v[124:127], v[84:85], off offset:2048
	global_load_dwordx4 v[128:131], v[84:85], off offset:3072
	v_lshl_add_u64 v[86:87], v[48:49], 0, v[164:165]
	v_add_co_u32_e32 v88, vcc, s16, v86
	s_nop 1
	v_addc_co_u32_e32 v89, vcc, 0, v87, vcc
	v_lshl_add_u64 v[46:47], v[46:47], 0, s[18:19]
	v_lshl_add_u64 v[48:49], v[48:49], 0, s[18:19]
	v_lshl_add_u64 v[80:81], v[46:47], 0, v[164:165]
	v_add_co_u32_e32 v84, vcc, s17, v80
	s_nop 1
	v_addc_co_u32_e32 v85, vcc, 0, v81, vcc
	v_add_co_u32_e32 v82, vcc, 0xa000000, v80
	s_nop 1
	v_addc_co_u32_e32 v83, vcc, 0, v81, vcc
	global_load_dwordx4 v[132:135], v[82:83], off
	global_load_dwordx4 v[136:139], v[82:83], off offset:1024
	global_load_dwordx4 v[140:143], v[82:83], off offset:2048
	global_load_dwordx4 v[144:147], v[82:83], off offset:3072
	global_load_dwordx4 v[148:151], v[84:85], off
	global_load_dwordx4 v[152:155], v[84:85], off offset:1024
	global_load_dwordx4 v[156:159], v[84:85], off offset:2048
	global_load_dwordx4 v[160:163], v[84:85], off offset:3072
	s_waitcnt vmcnt(8)
	v_mul_f32_e32 v9, v100, v100
	v_mul_f32_e32 v10, v101, v101
	v_mul_f32_e32 v11, v102, v102
	v_mul_f32_e32 v12, v103, v103
	v_add_f32_e32 v9, v9, v10
	v_add_f32_e32 v9, v9, v11
	v_add_f32_e32 v9, v9, v12
	v_mul_f32_e32 v8, v104, v104
	v_mul_f32_e32 v10, v105, v105
	v_mul_f32_e32 v11, v106, v106
	v_mul_f32_e32 v12, v107, v107
	v_add_f32_e32 v8, v8, v10
	v_add_f32_e32 v8, v8, v11
	v_add_f32_e32 v8, v8, v12
	v_add_f32_e32 v9, v9, v8
	v_mul_f32_e32 v8, v108, v108
	v_mul_f32_e32 v10, v109, v109
	v_mul_f32_e32 v11, v110, v110
	v_mul_f32_e32 v12, v111, v111
	v_add_f32_e32 v8, v8, v10
	v_add_f32_e32 v8, v8, v11
	v_add_f32_e32 v8, v8, v12
	v_add_f32_e32 v9, v9, v8
	v_mul_f32_e32 v8, v112, v112
	v_mul_f32_e32 v10, v113, v113
	v_mul_f32_e32 v11, v114, v114
	v_mul_f32_e32 v12, v115, v115
	v_add_f32_e32 v8, v8, v10
	v_add_f32_e32 v8, v8, v11
	v_add_f32_e32 v8, v8, v12
	v_add_f32_e32 v9, v9, v8
	v_mul_f32_e32 v8, v117, v117
	v_fmac_f32_e32 v8, v116, v116
	v_fmac_f32_e32 v8, v118, v118
	v_fmac_f32_e32 v8, v119, v119
	v_add_f32_e32 v9, v9, v8
	v_mul_f32_e32 v8, v121, v121
	v_fmac_f32_e32 v8, v120, v120
	v_fmac_f32_e32 v8, v122, v122
	v_fmac_f32_e32 v8, v123, v123
	v_add_f32_e32 v9, v9, v8
	v_mul_f32_e32 v8, v125, v125
	v_fmac_f32_e32 v8, v124, v124
	v_fmac_f32_e32 v8, v126, v126
	v_fmac_f32_e32 v8, v127, v127
	v_add_f32_e32 v9, v9, v8
	v_mul_f32_e32 v8, v129, v129
	v_fmac_f32_e32 v8, v128, v128
	v_fmac_f32_e32 v8, v130, v130
	v_fmac_f32_e32 v8, v131, v131
	v_add_f32_e32 v9, v9, v8
	s_waitcnt lgkmcnt(0)
	s_nop 1
	v_add_f32_dpp v9, v9, v9 quad_perm:[1,0,3,2] row_mask:0xf bank_mask:0xf
	s_waitcnt lgkmcnt(0)
	s_nop 1
	v_add_f32_dpp v9, v9, v9 quad_perm:[2,3,0,1] row_mask:0xf bank_mask:0xf
	s_waitcnt lgkmcnt(0)
; __device__ __forceinline__ void final_rows(const float* X, const float* fw, float* out, int row0, int nrows, int wave, int lane) {
;     for (int row = row0 + wave; row < row0 + nrows; row += 8) {
;         const float4* xr = (const float4*)(X + (size_t)row * DM) + lane; float4 v[8]; float ss = 0.f;
; #pragma unroll
;         for (int j = 0; j < 8; ++j) { v[j] = xr[64 * j]; ss += v[j].x * v[j].x + v[j].y * v[j].y + v[j].z * v[j].z + v[j].w * v[j].w; }
;         const float r = rsqrtf(wave_sum(ss) * (1.f / DM) + EPS);
;         float4* op = (float4*)(out + (size_t)row * DM) + lane;
; #pragma unroll
;         for (int j = 0; j < 8; ++j) { const float4 w4 = *(const float4*)(fw + 4 * (lane + 64 * j)); op[64 * j] = make_float4(v[j].x * r * w4.x, v[j].y * r * w4.y, v[j].z * r * w4.z, v[j].w * r * w4.w); } }
	s_nop 1
	v_add_f32_dpp v9, v9, v9 row_half_mirror row_mask:0xf bank_mask:0xf
	s_waitcnt lgkmcnt(0)
	s_nop 1
	v_add_f32_dpp v9, v9, v9 row_mirror row_mask:0xf bank_mask:0xf
	s_waitcnt lgkmcnt(0)
	v_mov_b32_e32 v8, v9
	s_nop 1
	v_permlane16_swap_b32_e32 v9, v8
	v_add_f32_e32 v9, v9, v8
	s_waitcnt lgkmcnt(0)
	v_mov_b32_e32 v8, v9
	s_nop 1
	v_permlane32_swap_b32_e32 v9, v8
	v_add_f32_e32 v9, v9, v8
	v_fmamk_f32 v9, v9, 0x3a000000, v179
	v_cmp_gt_f32_e32 vcc, s91, v9
	v_mul_f32_e32 v8, 0x4b800000, v9
	s_nop 0
	v_cndmask_b32_e32 v9, v9, v8, vcc
	v_rsq_f32_e32 v9, v9
	s_nop 0
	v_mul_f32_e32 v8, 0x45800000, v9
	v_cndmask_b32_e32 v13, v9, v8, vcc
	v_mul_f32_e32 v0, v100, v13
	v_mul_f32_e32 v1, v101, v13
	v_mul_f32_e32 v2, v102, v13
	v_mul_f32_e32 v3, v103, v13
	v_mul_f32_e32 v0, v182, v0
	v_mul_f32_e32 v1, v183, v1
	v_mul_f32_e32 v2, v184, v2
	v_mul_f32_e32 v3, v185, v3
	global_store_dwordx4 v[86:87], v[0:3], off
	v_mul_f32_e32 v4, v104, v13
	v_mul_f32_e32 v5, v105, v13
	v_mul_f32_e32 v6, v106, v13
	v_mul_f32_e32 v7, v107, v13
	v_mul_f32_e32 v4, v186, v4
	v_mul_f32_e32 v5, v187, v5
	v_mul_f32_e32 v6, v188, v6
	v_mul_f32_e32 v7, v189, v7
	global_store_dwordx4 v[86:87], v[4:7], off offset:1024
	v_mul_f32_e32 v0, v108, v13
	v_mul_f32_e32 v1, v109, v13
	v_mul_f32_e32 v2, v110, v13
	v_mul_f32_e32 v3, v111, v13
	v_mul_f32_e32 v0, v190, v0
	v_mul_f32_e32 v1, v191, v1
	v_mul_f32_e32 v2, v192, v2
	v_mul_f32_e32 v3, v193, v3
	global_store_dwordx4 v[86:87], v[0:3], off offset:2048
	v_mul_f32_e32 v4, v112, v13
	v_mul_f32_e32 v5, v113, v13
	v_mul_f32_e32 v6, v114, v13
	v_mul_f32_e32 v7, v115, v13
	v_mul_f32_e32 v4, v194, v4
	v_mul_f32_e32 v5, v195, v5
	v_mul_f32_e32 v6, v196, v6
	v_mul_f32_e32 v7, v197, v7
	global_store_dwordx4 v[86:87], v[4:7], off offset:3072
	v_mul_f32_e32 v0, v116, v13
	v_mul_f32_e32 v1, v117, v13
	v_mul_f32_e32 v2, v118, v13
	v_mul_f32_e32 v3, v119, v13
	v_mul_f32_e32 v0, v198, v0
	v_mul_f32_e32 v1, v199, v1
	v_mul_f32_e32 v2, v200, v2
	v_mul_f32_e32 v3, v201, v3
	global_store_dwordx4 v[88:89], v[0:3], off
	v_mul_f32_e32 v4, v120, v13
	v_mul_f32_e32 v5, v121, v13
	v_mul_f32_e32 v6, v122, v13
	v_mul_f32_e32 v7, v123, v13
	v_mul_f32_e32 v4, v202, v4
	v_mul_f32_e32 v5, v203, v5
	v_mul_f32_e32 v6, v204, v6
	v_mul_f32_e32 v7, v205, v7
	global_store_dwordx4 v[88:89], v[4:7], off offset:1024
	v_mul_f32_e32 v0, v124, v13
	v_mul_f32_e32 v1, v125, v13
	v_mul_f32_e32 v2, v126, v13
	v_mul_f32_e32 v3, v127, v13
	v_mul_f32_e32 v0, v206, v0
	v_mul_f32_e32 v1, v207, v1
	v_mul_f32_e32 v2, v208, v2
	v_mul_f32_e32 v3, v209, v3
	global_store_dwordx4 v[88:89], v[0:3], off offset:2048
	v_mul_f32_e32 v4, v128, v13
	v_mul_f32_e32 v5, v129, v13
	v_mul_f32_e32 v6, v130, v13
	v_mul_f32_e32 v7, v131, v13
	v_mul_f32_e32 v4, v210, v4
	v_mul_f32_e32 v5, v211, v5
	v_mul_f32_e32 v6, v212, v6
	v_mul_f32_e32 v7, v213, v7
	global_store_dwordx4 v[88:89], v[4:7], off offset:3072
	v_lshl_add_u64 v[86:87], v[48:49], 0, v[164:165]
	v_add_co_u32_e32 v88, vcc, s16, v86
	s_nop 1
	v_addc_co_u32_e32 v89, vcc, 0, v87, vcc
	v_lshl_add_u64 v[46:47], v[46:47], 0, s[18:19]
	v_lshl_add_u64 v[48:49], v[48:49], 0, s[18:19]
	v_lshl_add_u64 v[80:81], v[46:47], 0, v[164:165]
	v_add_co_u32_e32 v84, vcc, s17, v80
	s_nop 1
	v_addc_co_u32_e32 v85, vcc, 0, v81, vcc
	v_add_co_u32_e32 v82, vcc, 0xa000000, v80
	s_nop 1
	v_addc_co_u32_e32 v83, vcc, 0, v81, vcc
	global_load_dwordx4 v[100:103], v[82:83], off
	global_load_dwordx4 v[104:107], v[82:83], off offset:1024
	global_load_dwordx4 v[108:111], v[82:83], off offset:2048
	global_load_dwordx4 v[112:115], v[82:83], off offset:3072
	global_load_dwordx4 v[116:119], v[84:85], off
	global_load_dwordx4 v[120:123], v[84:85], off offset:1024
	global_load_dwordx4 v[124:127], v[84:85], off offset:2048
	global_load_dwordx4 v[128:131], v[84:85], off offset:3072
	s_waitcnt vmcnt(16)
	v_mul_f32_e32 v9, v132, v132
	v_mul_f32_e32 v10, v133, v133
	v_mul_f32_e32 v11, v134, v134
	v_mul_f32_e32 v12, v135, v135
	v_add_f32_e32 v9, v9, v10
	v_add_f32_e32 v9, v9, v11
	v_add_f32_e32 v9, v9, v12
	v_mul_f32_e32 v8, v136, v136
	v_mul_f32_e32 v10, v137, v137
	v_mul_f32_e32 v11, v138, v138
	v_mul_f32_e32 v12, v139, v139
	v_add_f32_e32 v8, v8, v10
	v_add_f32_e32 v8, v8, v11
	v_add_f32_e32 v8, v8, v12
	v_add_f32_e32 v9, v9, v8
	v_mul_f32_e32 v8, v140, v140
	v_mul_f32_e32 v10, v141, v141
	v_mul_f32_e32 v11, v142, v142
	v_mul_f32_e32 v12, v143, v143
	v_add_f32_e32 v8, v8, v10
	v_add_f32_e32 v8, v8, v11
	v_add_f32_e32 v8, v8, v12
	v_add_f32_e32 v9, v9, v8
	v_mul_f32_e32 v8, v144, v144
	v_mul_f32_e32 v10, v145, v145
	v_mul_f32_e32 v11, v146, v146
	v_mul_f32_e32 v12, v147, v147
	v_add_f32_e32 v8, v8, v10
	v_add_f32_e32 v8, v8, v11
	v_add_f32_e32 v8, v8, v12
	v_add_f32_e32 v9, v9, v8
	v_mul_f32_e32 v8, v149, v149
	v_fmac_f32_e32 v8, v148, v148
	v_fmac_f32_e32 v8, v150, v150
	v_fmac_f32_e32 v8, v151, v151
	v_add_f32_e32 v9, v9, v8
	v_mul_f32_e32 v8, v153, v153
	v_fmac_f32_e32 v8, v152, v152
	v_fmac_f32_e32 v8, v154, v154
	v_fmac_f32_e32 v8, v155, v155
	v_add_f32_e32 v9, v9, v8
	v_mul_f32_e32 v8, v157, v157
	v_fmac_f32_e32 v8, v156, v156
	v_fmac_f32_e32 v8, v158, v158
	v_fmac_f32_e32 v8, v159, v159
	v_add_f32_e32 v9, v9, v8
	v_mul_f32_e32 v8, v161, v161
	v_fmac_f32_e32 v8, v160, v160
	v_fmac_f32_e32 v8, v162, v162
	v_fmac_f32_e32 v8, v163, v163
	v_add_f32_e32 v9, v9, v8
	s_waitcnt lgkmcnt(0)
	s_nop 1
	v_add_f32_dpp v9, v9, v9 quad_perm:[1,0,3,2] row_mask:0xf bank_mask:0xf
	s_waitcnt lgkmcnt(0)
	s_nop 1
	v_add_f32_dpp v9, v9, v9 quad_perm:[2,3,0,1] row_mask:0xf bank_mask:0xf
	s_waitcnt lgkmcnt(0)
	s_nop 1
	v_add_f32_dpp v9, v9, v9 row_half_mirror row_mask:0xf bank_mask:0xf
	s_waitcnt lgkmcnt(0)
; __device__ __forceinline__ void final_rows(const float* X, const float* fw, float* out, int row0, int nrows, int wave, int lane) {
;     for (int row = row0 + wave; row < row0 + nrows; row += 8) {
;         const float4* xr = (const float4*)(X + (size_t)row * DM) + lane; float4 v[8]; float ss = 0.f;
; #pragma unroll
;         for (int j = 0; j < 8; ++j) { v[j] = xr[64 * j]; ss += v[j].x * v[j].x + v[j].y * v[j].y + v[j].z * v[j].z + v[j].w * v[j].w; }
;         const float r = rsqrtf(wave_sum(ss) * (1.f / DM) + EPS);
;         float4* op = (float4*)(out + (size_t)row * DM) + lane;
; #pragma unroll
;         for (int j = 0; j < 8; ++j) { const float4 w4 = *(const float4*)(fw + 4 * (lane + 64 * j)); op[64 * j] = make_float4(v[j].x * r * w4.x, v[j].y * r * w4.y, v[j].z * r * w4.z, v[j].w * r * w4.w); } }
	s_nop 1
	v_add_f32_dpp v9, v9, v9 row_mirror row_mask:0xf bank_mask:0xf
	s_waitcnt lgkmcnt(0)
	v_mov_b32_e32 v8, v9
	s_nop 1
	v_permlane16_swap_b32_e32 v9, v8
	v_add_f32_e32 v9, v9, v8
	s_waitcnt lgkmcnt(0)
	v_mov_b32_e32 v8, v9
	s_nop 1
	v_permlane32_swap_b32_e32 v9, v8
	v_add_f32_e32 v9, v9, v8
	v_fmamk_f32 v9, v9, 0x3a000000, v179
	v_cmp_gt_f32_e32 vcc, s91, v9
	v_mul_f32_e32 v8, 0x4b800000, v9
	s_nop 0
	v_cndmask_b32_e32 v9, v9, v8, vcc
	v_rsq_f32_e32 v9, v9
	s_nop 0
	v_mul_f32_e32 v8, 0x45800000, v9
	v_cndmask_b32_e32 v13, v9, v8, vcc
	v_mul_f32_e32 v0, v132, v13
	v_mul_f32_e32 v1, v133, v13
	v_mul_f32_e32 v2, v134, v13
	v_mul_f32_e32 v3, v135, v13
	v_mul_f32_e32 v0, v182, v0
	v_mul_f32_e32 v1, v183, v1
	v_mul_f32_e32 v2, v184, v2
	v_mul_f32_e32 v3, v185, v3
	global_store_dwordx4 v[86:87], v[0:3], off
	v_mul_f32_e32 v4, v136, v13
	v_mul_f32_e32 v5, v137, v13
	v_mul_f32_e32 v6, v138, v13
	v_mul_f32_e32 v7, v139, v13
	v_mul_f32_e32 v4, v186, v4
	v_mul_f32_e32 v5, v187, v5
	v_mul_f32_e32 v6, v188, v6
	v_mul_f32_e32 v7, v189, v7
	global_store_dwordx4 v[86:87], v[4:7], off offset:1024
	v_mul_f32_e32 v0, v140, v13
	v_mul_f32_e32 v1, v141, v13
	v_mul_f32_e32 v2, v142, v13
	v_mul_f32_e32 v3, v143, v13
	v_mul_f32_e32 v0, v190, v0
	v_mul_f32_e32 v1, v191, v1
	v_mul_f32_e32 v2, v192, v2
	v_mul_f32_e32 v3, v193, v3
	global_store_dwordx4 v[86:87], v[0:3], off offset:2048
	v_mul_f32_e32 v4, v144, v13
	v_mul_f32_e32 v5, v145, v13
	v_mul_f32_e32 v6, v146, v13
	v_mul_f32_e32 v7, v147, v13
	v_mul_f32_e32 v4, v194, v4
	v_mul_f32_e32 v5, v195, v5
	v_mul_f32_e32 v6, v196, v6
	v_mul_f32_e32 v7, v197, v7
	global_store_dwordx4 v[86:87], v[4:7], off offset:3072
	v_mul_f32_e32 v0, v148, v13
	v_mul_f32_e32 v1, v149, v13
	v_mul_f32_e32 v2, v150, v13
	v_mul_f32_e32 v3, v151, v13
	v_mul_f32_e32 v0, v198, v0
	v_mul_f32_e32 v1, v199, v1
	v_mul_f32_e32 v2, v200, v2
	v_mul_f32_e32 v3, v201, v3
	global_store_dwordx4 v[88:89], v[0:3], off
	v_mul_f32_e32 v4, v152, v13
	v_mul_f32_e32 v5, v153, v13
	v_mul_f32_e32 v6, v154, v13
	v_mul_f32_e32 v7, v155, v13
	v_mul_f32_e32 v4, v202, v4
	v_mul_f32_e32 v5, v203, v5
	v_mul_f32_e32 v6, v204, v6
	v_mul_f32_e32 v7, v205, v7
	global_store_dwordx4 v[88:89], v[4:7], off offset:1024
	v_mul_f32_e32 v0, v156, v13
	v_mul_f32_e32 v1, v157, v13
	v_mul_f32_e32 v2, v158, v13
	v_mul_f32_e32 v3, v159, v13
	v_mul_f32_e32 v0, v206, v0
	v_mul_f32_e32 v1, v207, v1
	v_mul_f32_e32 v2, v208, v2
	v_mul_f32_e32 v3, v209, v3
	global_store_dwordx4 v[88:89], v[0:3], off offset:2048
	v_mul_f32_e32 v4, v160, v13
	v_mul_f32_e32 v5, v161, v13
	v_mul_f32_e32 v6, v162, v13
	v_mul_f32_e32 v7, v163, v13
	v_mul_f32_e32 v4, v210, v4
	v_mul_f32_e32 v5, v211, v5
	v_mul_f32_e32 v6, v212, v6
	v_mul_f32_e32 v7, v213, v7
	global_store_dwordx4 v[88:89], v[4:7], off offset:3072
	v_lshl_add_u64 v[86:87], v[48:49], 0, v[164:165]
	v_add_co_u32_e32 v88, vcc, s16, v86
	s_nop 1
	v_addc_co_u32_e32 v89, vcc, 0, v87, vcc
	v_lshl_add_u64 v[46:47], v[46:47], 0, s[18:19]
	v_lshl_add_u64 v[48:49], v[48:49], 0, s[18:19]
	v_lshl_add_u64 v[80:81], v[46:47], 0, v[164:165]
	v_add_co_u32_e32 v84, vcc, s17, v80
	s_nop 1
	v_addc_co_u32_e32 v85, vcc, 0, v81, vcc
	v_add_co_u32_e32 v82, vcc, 0xa000000, v80
	s_nop 1
	v_addc_co_u32_e32 v83, vcc, 0, v81, vcc
	global_load_dwordx4 v[132:135], v[82:83], off
	global_load_dwordx4 v[136:139], v[82:83], off offset:1024
	global_load_dwordx4 v[140:143], v[82:83], off offset:2048
	global_load_dwordx4 v[144:147], v[82:83], off offset:3072
	global_load_dwordx4 v[148:151], v[84:85], off
	global_load_dwordx4 v[152:155], v[84:85], off offset:1024
	global_load_dwordx4 v[156:159], v[84:85], off offset:2048
	global_load_dwordx4 v[160:163], v[84:85], off offset:3072
	s_waitcnt vmcnt(16)
	v_mul_f32_e32 v9, v100, v100
	v_mul_f32_e32 v10, v101, v101
	v_mul_f32_e32 v11, v102, v102
	v_mul_f32_e32 v12, v103, v103
	v_add_f32_e32 v9, v9, v10
	v_add_f32_e32 v9, v9, v11
	v_add_f32_e32 v9, v9, v12
	v_mul_f32_e32 v8, v104, v104
	v_mul_f32_e32 v10, v105, v105
	v_mul_f32_e32 v11, v106, v106
	v_mul_f32_e32 v12, v107, v107
	v_add_f32_e32 v8, v8, v10
	v_add_f32_e32 v8, v8, v11
	v_add_f32_e32 v8, v8, v12
	v_add_f32_e32 v9, v9, v8
	v_mul_f32_e32 v8, v108, v108
	v_mul_f32_e32 v10, v109, v109
	v_mul_f32_e32 v11, v110, v110
	v_mul_f32_e32 v12, v111, v111
	v_add_f32_e32 v8, v8, v10
	v_add_f32_e32 v8, v8, v11
	v_add_f32_e32 v8, v8, v12
	v_add_f32_e32 v9, v9, v8
	v_mul_f32_e32 v8, v112, v112
	v_mul_f32_e32 v10, v113, v113
	v_mul_f32_e32 v11, v114, v114
	v_mul_f32_e32 v12, v115, v115
	v_add_f32_e32 v8, v8, v10
	v_add_f32_e32 v8, v8, v11
	v_add_f32_e32 v8, v8, v12
	v_add_f32_e32 v9, v9, v8
	v_mul_f32_e32 v8, v117, v117
	v_fmac_f32_e32 v8, v116, v116
	v_fmac_f32_e32 v8, v118, v118
	v_fmac_f32_e32 v8, v119, v119
	v_add_f32_e32 v9, v9, v8
	v_mul_f32_e32 v8, v121, v121
	v_fmac_f32_e32 v8, v120, v120
	v_fmac_f32_e32 v8, v122, v122
	v_fmac_f32_e32 v8, v123, v123
	v_add_f32_e32 v9, v9, v8
	v_mul_f32_e32 v8, v125, v125
	v_fmac_f32_e32 v8, v124, v124
	v_fmac_f32_e32 v8, v126, v126
	v_fmac_f32_e32 v8, v127, v127
	v_add_f32_e32 v9, v9, v8
	v_mul_f32_e32 v8, v129, v129
	v_fmac_f32_e32 v8, v128, v128
	v_fmac_f32_e32 v8, v130, v130
	v_fmac_f32_e32 v8, v131, v131
	v_add_f32_e32 v9, v9, v8
	s_waitcnt lgkmcnt(0)
	s_nop 1
	v_add_f32_dpp v9, v9, v9 quad_perm:[1,0,3,2] row_mask:0xf bank_mask:0xf
	s_waitcnt lgkmcnt(0)
	s_nop 1
	v_add_f32_dpp v9, v9, v9 quad_perm:[2,3,0,1] row_mask:0xf bank_mask:0xf
	s_waitcnt lgkmcnt(0)
	s_nop 1
	v_add_f32_dpp v9, v9, v9 row_half_mirror row_mask:0xf bank_mask:0xf
	s_waitcnt lgkmcnt(0)
	s_nop 1
	v_add_f32_dpp v9, v9, v9 row_mirror row_mask:0xf bank_mask:0xf
	s_waitcnt lgkmcnt(0)
; __device__ __forceinline__ void final_rows(const float* X, const float* fw, float* out, int row0, int nrows, int wave, int lane) {
;     for (int row = row0 + wave; row < row0 + nrows; row += 8) {
;         const float4* xr = (const float4*)(X + (size_t)row * DM) + lane; float4 v[8]; float ss = 0.f;
; #pragma unroll
;         for (int j = 0; j < 8; ++j) { v[j] = xr[64 * j]; ss += v[j].x * v[j].x + v[j].y * v[j].y + v[j].z * v[j].z + v[j].w * v[j].w; }
;         const float r = rsqrtf(wave_sum(ss) * (1.f / DM) + EPS);
;         float4* op = (float4*)(out + (size_t)row * DM) + lane;
; #pragma unroll
;         for (int j = 0; j < 8; ++j) { const float4 w4 = *(const float4*)(fw + 4 * (lane + 64 * j)); op[64 * j] = make_float4(v[j].x * r * w4.x, v[j].y * r * w4.y, v[j].z * r * w4.z, v[j].w * r * w4.w); } }
	v_mov_b32_e32 v8, v9
	s_nop 1
	v_permlane16_swap_b32_e32 v9, v8
	v_add_f32_e32 v9, v9, v8
	s_waitcnt lgkmcnt(0)
	v_mov_b32_e32 v8, v9
	s_nop 1
	v_permlane32_swap_b32_e32 v9, v8
	v_add_f32_e32 v9, v9, v8
	v_fmamk_f32 v9, v9, 0x3a000000, v179
	v_cmp_gt_f32_e32 vcc, s91, v9
	v_mul_f32_e32 v8, 0x4b800000, v9
	s_nop 0
	v_cndmask_b32_e32 v9, v9, v8, vcc
	v_rsq_f32_e32 v9, v9
	s_nop 0
	v_mul_f32_e32 v8, 0x45800000, v9
	v_cndmask_b32_e32 v13, v9, v8, vcc
	v_mul_f32_e32 v0, v100, v13
	v_mul_f32_e32 v1, v101, v13
	v_mul_f32_e32 v2, v102, v13
	v_mul_f32_e32 v3, v103, v13
	v_mul_f32_e32 v0, v182, v0
	v_mul_f32_e32 v1, v183, v1
	v_mul_f32_e32 v2, v184, v2
	v_mul_f32_e32 v3, v185, v3
	global_store_dwordx4 v[86:87], v[0:3], off
	v_mul_f32_e32 v4, v104, v13
	v_mul_f32_e32 v5, v105, v13
	v_mul_f32_e32 v6, v106, v13
	v_mul_f32_e32 v7, v107, v13
	v_mul_f32_e32 v4, v186, v4
	v_mul_f32_e32 v5, v187, v5
	v_mul_f32_e32 v6, v188, v6
	v_mul_f32_e32 v7, v189, v7
	global_store_dwordx4 v[86:87], v[4:7], off offset:1024
	v_mul_f32_e32 v0, v108, v13
	v_mul_f32_e32 v1, v109, v13
	v_mul_f32_e32 v2, v110, v13
	v_mul_f32_e32 v3, v111, v13
	v_mul_f32_e32 v0, v190, v0
	v_mul_f32_e32 v1, v191, v1
	v_mul_f32_e32 v2, v192, v2
	v_mul_f32_e32 v3, v193, v3
	global_store_dwordx4 v[86:87], v[0:3], off offset:2048
	v_mul_f32_e32 v4, v112, v13
	v_mul_f32_e32 v5, v113, v13
	v_mul_f32_e32 v6, v114, v13
	v_mul_f32_e32 v7, v115, v13
	v_mul_f32_e32 v4, v194, v4
	v_mul_f32_e32 v5, v195, v5
	v_mul_f32_e32 v6, v196, v6
	v_mul_f32_e32 v7, v197, v7
	global_store_dwordx4 v[86:87], v[4:7], off offset:3072
	v_mul_f32_e32 v0, v116, v13
	v_mul_f32_e32 v1, v117, v13
	v_mul_f32_e32 v2, v118, v13
	v_mul_f32_e32 v3, v119, v13
	v_mul_f32_e32 v0, v198, v0
	v_mul_f32_e32 v1, v199, v1
	v_mul_f32_e32 v2, v200, v2
	v_mul_f32_e32 v3, v201, v3
	global_store_dwordx4 v[88:89], v[0:3], off
	v_mul_f32_e32 v4, v120, v13
	v_mul_f32_e32 v5, v121, v13
	v_mul_f32_e32 v6, v122, v13
	v_mul_f32_e32 v7, v123, v13
	v_mul_f32_e32 v4, v202, v4
	v_mul_f32_e32 v5, v203, v5
	v_mul_f32_e32 v6, v204, v6
	v_mul_f32_e32 v7, v205, v7
	global_store_dwordx4 v[88:89], v[4:7], off offset:1024
	v_mul_f32_e32 v0, v124, v13
	v_mul_f32_e32 v1, v125, v13
	v_mul_f32_e32 v2, v126, v13
	v_mul_f32_e32 v3, v127, v13
	v_mul_f32_e32 v0, v206, v0
	v_mul_f32_e32 v1, v207, v1
	v_mul_f32_e32 v2, v208, v2
	v_mul_f32_e32 v3, v209, v3
	global_store_dwordx4 v[88:89], v[0:3], off offset:2048
	v_mul_f32_e32 v4, v128, v13
	v_mul_f32_e32 v5, v129, v13
	v_mul_f32_e32 v6, v130, v13
	v_mul_f32_e32 v7, v131, v13
	v_mul_f32_e32 v4, v210, v4
	v_mul_f32_e32 v5, v211, v5
	v_mul_f32_e32 v6, v212, v6
	v_mul_f32_e32 v7, v213, v7
	global_store_dwordx4 v[88:89], v[4:7], off offset:3072
	v_lshl_add_u64 v[86:87], v[48:49], 0, v[164:165]
	v_add_co_u32_e32 v88, vcc, s16, v86
	s_nop 1
	v_addc_co_u32_e32 v89, vcc, 0, v87, vcc
	s_waitcnt vmcnt(8)
	v_mul_f32_e32 v9, v132, v132
	v_mul_f32_e32 v10, v133, v133
	v_mul_f32_e32 v11, v134, v134
	v_mul_f32_e32 v12, v135, v135
	v_add_f32_e32 v9, v9, v10
	v_add_f32_e32 v9, v9, v11
	v_add_f32_e32 v9, v9, v12
	v_mul_f32_e32 v8, v136, v136
	v_mul_f32_e32 v10, v137, v137
	v_mul_f32_e32 v11, v138, v138
	v_mul_f32_e32 v12, v139, v139
	v_add_f32_e32 v8, v8, v10
	v_add_f32_e32 v8, v8, v11
	v_add_f32_e32 v8, v8, v12
	v_add_f32_e32 v9, v9, v8
	v_mul_f32_e32 v8, v140, v140
	v_mul_f32_e32 v10, v141, v141
	v_mul_f32_e32 v11, v142, v142
	v_mul_f32_e32 v12, v143, v143
	v_add_f32_e32 v8, v8, v10
	v_add_f32_e32 v8, v8, v11
	v_add_f32_e32 v8, v8, v12
	v_add_f32_e32 v9, v9, v8
	v_mul_f32_e32 v8, v144, v144
	v_mul_f32_e32 v10, v145, v145
	v_mul_f32_e32 v11, v146, v146
	v_mul_f32_e32 v12, v147, v147
	v_add_f32_e32 v8, v8, v10
	v_add_f32_e32 v8, v8, v11
	v_add_f32_e32 v8, v8, v12
	v_add_f32_e32 v9, v9, v8
	v_mul_f32_e32 v8, v149, v149
	v_fmac_f32_e32 v8, v148, v148
	v_fmac_f32_e32 v8, v150, v150
	v_fmac_f32_e32 v8, v151, v151
	v_add_f32_e32 v9, v9, v8
	v_mul_f32_e32 v8, v153, v153
	v_fmac_f32_e32 v8, v152, v152
	v_fmac_f32_e32 v8, v154, v154
	v_fmac_f32_e32 v8, v155, v155
	v_add_f32_e32 v9, v9, v8
	v_mul_f32_e32 v8, v157, v157
	v_fmac_f32_e32 v8, v156, v156
	v_fmac_f32_e32 v8, v158, v158
	v_fmac_f32_e32 v8, v159, v159
	v_add_f32_e32 v9, v9, v8
	v_mul_f32_e32 v8, v161, v161
	v_fmac_f32_e32 v8, v160, v160
	v_fmac_f32_e32 v8, v162, v162
	v_fmac_f32_e32 v8, v163, v163
	v_add_f32_e32 v9, v9, v8
	s_waitcnt lgkmcnt(0)
; __device__ __forceinline__ void final_rows(const float* X, const float* fw, float* out, int row0, int nrows, int wave, int lane) {
;     for (int row = row0 + wave; row < row0 + nrows; row += 8) {
;         const float4* xr = (const float4*)(X + (size_t)row * DM) + lane; float4 v[8]; float ss = 0.f;
; #pragma unroll
;         for (int j = 0; j < 8; ++j) { v[j] = xr[64 * j]; ss += v[j].x * v[j].x + v[j].y * v[j].y + v[j].z * v[j].z + v[j].w * v[j].w; }
;         const float r = rsqrtf(wave_sum(ss) * (1.f / DM) + EPS);
;         float4* op = (float4*)(out + (size_t)row * DM) + lane;
; #pragma unroll
;         for (int j = 0; j < 8; ++j) { const float4 w4 = *(const float4*)(fw + 4 * (lane + 64 * j)); op[64 * j] = make_float4(v[j].x * r * w4.x, v[j].y * r * w4.y, v[j].z * r * w4.z, v[j].w * r * w4.w); } }
	s_nop 1
	v_add_f32_dpp v9, v9, v9 quad_perm:[1,0,3,2] row_mask:0xf bank_mask:0xf
	s_waitcnt lgkmcnt(0)
	s_nop 1
	v_add_f32_dpp v9, v9, v9 quad_perm:[2,3,0,1] row_mask:0xf bank_mask:0xf
	s_waitcnt lgkmcnt(0)
	s_nop 1
	v_add_f32_dpp v9, v9, v9 row_half_mirror row_mask:0xf bank_mask:0xf
	s_waitcnt lgkmcnt(0)
	s_nop 1
	v_add_f32_dpp v9, v9, v9 row_mirror row_mask:0xf bank_mask:0xf
	s_waitcnt lgkmcnt(0)
	v_mov_b32_e32 v8, v9
	s_nop 1
	v_permlane16_swap_b32_e32 v9, v8
	v_add_f32_e32 v9, v9, v8
	s_waitcnt lgkmcnt(0)
	v_mov_b32_e32 v8, v9
	s_nop 1
	v_permlane32_swap_b32_e32 v9, v8
	v_add_f32_e32 v9, v9, v8
	v_fmamk_f32 v9, v9, 0x3a000000, v179
	v_cmp_gt_f32_e32 vcc, s91, v9
	v_mul_f32_e32 v8, 0x4b800000, v9
	s_nop 0
	v_cndmask_b32_e32 v9, v9, v8, vcc
	v_rsq_f32_e32 v9, v9
	s_nop 0
	v_mul_f32_e32 v8, 0x45800000, v9
	v_cndmask_b32_e32 v13, v9, v8, vcc
	v_mul_f32_e32 v0, v132, v13
	v_mul_f32_e32 v1, v133, v13
	v_mul_f32_e32 v2, v134, v13
	v_mul_f32_e32 v3, v135, v13
	v_mul_f32_e32 v0, v182, v0
	v_mul_f32_e32 v1, v183, v1
	v_mul_f32_e32 v2, v184, v2
	v_mul_f32_e32 v3, v185, v3
	global_store_dwordx4 v[86:87], v[0:3], off
	v_mul_f32_e32 v4, v136, v13
	v_mul_f32_e32 v5, v137, v13
	v_mul_f32_e32 v6, v138, v13
	v_mul_f32_e32 v7, v139, v13
	v_mul_f32_e32 v4, v186, v4
	v_mul_f32_e32 v5, v187, v5
	v_mul_f32_e32 v6, v188, v6
	v_mul_f32_e32 v7, v189, v7
	global_store_dwordx4 v[86:87], v[4:7], off offset:1024
	v_mul_f32_e32 v0, v140, v13
	v_mul_f32_e32 v1, v141, v13
	v_mul_f32_e32 v2, v142, v13
	v_mul_f32_e32 v3, v143, v13
	v_mul_f32_e32 v0, v190, v0
	v_mul_f32_e32 v1, v191, v1
	v_mul_f32_e32 v2, v192, v2
	v_mul_f32_e32 v3, v193, v3
	global_store_dwordx4 v[86:87], v[0:3], off offset:2048
	v_mul_f32_e32 v4, v144, v13
	v_mul_f32_e32 v5, v145, v13
	v_mul_f32_e32 v6, v146, v13
	v_mul_f32_e32 v7, v147, v13
	v_mul_f32_e32 v4, v194, v4
	v_mul_f32_e32 v5, v195, v5
	v_mul_f32_e32 v6, v196, v6
	v_mul_f32_e32 v7, v197, v7
	global_store_dwordx4 v[86:87], v[4:7], off offset:3072
	v_mul_f32_e32 v0, v148, v13
	v_mul_f32_e32 v1, v149, v13
	v_mul_f32_e32 v2, v150, v13
	v_mul_f32_e32 v3, v151, v13
	v_mul_f32_e32 v0, v198, v0
	v_mul_f32_e32 v1, v199, v1
	v_mul_f32_e32 v2, v200, v2
	v_mul_f32_e32 v3, v201, v3
	global_store_dwordx4 v[88:89], v[0:3], off
	v_mul_f32_e32 v4, v152, v13
	v_mul_f32_e32 v5, v153, v13
	v_mul_f32_e32 v6, v154, v13
	v_mul_f32_e32 v7, v155, v13
	v_mul_f32_e32 v4, v202, v4
	v_mul_f32_e32 v5, v203, v5
	v_mul_f32_e32 v6, v204, v6
	v_mul_f32_e32 v7, v205, v7
	global_store_dwordx4 v[88:89], v[4:7], off offset:1024
	v_mul_f32_e32 v0, v156, v13
	v_mul_f32_e32 v1, v157, v13
	v_mul_f32_e32 v2, v158, v13
	v_mul_f32_e32 v3, v159, v13
	v_mul_f32_e32 v0, v206, v0
	v_mul_f32_e32 v1, v207, v1
	v_mul_f32_e32 v2, v208, v2
	v_mul_f32_e32 v3, v209, v3
	global_store_dwordx4 v[88:89], v[0:3], off offset:2048
	v_mul_f32_e32 v4, v160, v13
	v_mul_f32_e32 v5, v161, v13
	v_mul_f32_e32 v6, v162, v13
	v_mul_f32_e32 v7, v163, v13
	v_mul_f32_e32 v4, v210, v4
	v_mul_f32_e32 v5, v211, v5
	v_mul_f32_e32 v6, v212, v6
	v_mul_f32_e32 v7, v213, v7
	global_store_dwordx4 v[88:89], v[4:7], off offset:3072

; __device__ __forceinline__ unsigned pk2(float lo, float hi) { return f2bf(lo) | (f2bf(hi) << 16); }
; #define RETID() do { tid = tidx(); lane = tid & 63; wave = tid >> 6; gw = bid * 8 + wave; } while (0)
; __device__ __forceinline__ void norm_rows(const float* X, const float* nw, const float* md, u16* H, int row0, int nrows, int wave, int lane) {
;     for (int row = row0 + wave; row < row0 + nrows; row += 8) {
;         const float4* xr = (const float4*)(X + (size_t)row * DM) + lane; float4 v[8]; float ss = 0.f;
; #pragma unroll
;         for (int j = 0; j < 8; ++j) { v[j] = xr[64 * j]; ss += v[j].x * v[j].x + v[j].y * v[j].y + v[j].z * v[j].z + v[j].w * v[j].w; }
;         const float r = rsqrtf(wave_sum(ss) * (1.f / DM) + EPS);
;         uint2* hp = (uint2*)(H + (size_t)row * DM) + lane;
; #pragma unroll
;         for (int j = 0; j < 8; ++j) { const int col = 4 * (lane + 64 * j); const float4 w4 = *(const float4*)(nw + col), sc = *(const float4*)(md + 2048 + col), sh = *(const float4*)(md + col);
;             uint2 o; o.x = pk2(v[j].x * r * w4.x * (1.f + sc.x) + sh.x, v[j].y * r * w4.y * (1.f + sc.y) + sh.y);
;             o.y = pk2(v[j].z * r * w4.z * (1.f + sc.z) + sh.z, v[j].w * r * w4.w * (1.f + sc.w) + sh.w); hp[64 * j] = o; } }
; __global__ void __launch_bounds__(512, 2) mega(Params p) {
;     ...
;           if (l < 3) { const float* mod1 = MOD + (size_t)(l + 1) * 2 * 6144; const float* nw1 = p.in[6] + (size_t)(l + 1) * DM;
;               norm_rows(X, nw1, mod1, H, pm * 256 + pn * 32, 32, wave, lane);
;               if (myslot < 4) { split_wait((unsigned*)(ws + WS_CTL) + CW_SPLIT2 + l * 17 * 64, bst[1], tid); RETID();
;                   norm_rows(X, nw1, mod1 + 6144, H, TL + ((int)xbar.x * 4 + myslot) * 8, 8, wave, lane); } }
.LBB0_1294:
	s_andn2_b64 vcc, exec, s[6:7]
	s_cbranch_vccnz .LBB0_1313
	v_readlane_b32 s0, v254, 59
	v_readlane_b32 s1, v254, 60
	s_add_i32 s84, s0, 1
	s_mul_i32 s1, s84, 0xc000
	v_readlane_b32 s6, v251, 36
	s_mul_hi_u32 s0, s84, 0xc000
	v_readlane_b32 s7, v251, 37
	s_add_u32 s34, s6, s1
	v_readlane_b32 s40, v251, 2
	s_addc_u32 s35, s7, s0
	s_lshl_b64 s[0:1], s[84:85], 13
	v_readlane_b32 s52, v251, 14
	v_readlane_b32 s53, v251, 15
	s_add_u32 s0, s52, s0
	v_readlane_b32 s41, v251, 3
	v_readlane_b32 s48, v251, 10
	v_readlane_b32 s49, v251, 11
	v_readlane_b32 s50, v251, 12
	v_readlane_b32 s51, v251, 13
	s_addc_u32 s1, s53, s1
	v_cmp_gt_i32_e32 vcc, 32, v71
	v_readlane_b32 s42, v251, 4
	v_readlane_b32 s43, v251, 5
	v_readlane_b32 s44, v251, 6
	v_readlane_b32 s45, v251, 7
	v_readlane_b32 s46, v251, 8
	v_readlane_b32 s47, v251, 9
	v_readlane_b32 s54, v251, 16
	v_readlane_b32 s55, v251, 17
	s_and_saveexec_b64 s[40:41], vcc
	v_readlane_b32 s44, v254, 16
	v_readlane_b32 s11, v253, 25
	s_mov_b32 s12, 0xa001000
	s_mov_b32 s13, 0xe200000
	s_mov_b64 s[16:17], 0x10000
	s_mov_b64 s[18:19], 0x8000
	v_readlane_b32 s48, v254, 20
	v_readlane_b32 s49, v254, 21
	v_readlane_b32 s50, v254, 22
	v_readlane_b32 s51, v254, 23
	v_readlane_b32 s45, v254, 17
	v_readlane_b32 s46, v254, 18
	v_readlane_b32 s47, v254, 19
	s_cbranch_execz .LBB0_1298
	v_cmp_lt_i32_e32 vcc, v178, v172
	s_add_u32 s6, s34, 0x2000
	v_lshlrev_b32_e32 v164, 4, v70
	v_cndmask_b32_e32 v0, v171, v178, vcc
	v_cmp_lt_i32_e32 vcc, v177, v172
	v_lshlrev_b32_e32 v65, 2, v0
	s_addc_u32 s7, s35, 0
	v_cndmask_b32_e32 v0, v171, v177, vcc
	v_cmp_lt_i32_e32 vcc, v176, v172
	v_lshlrev_b32_e32 v90, 2, v0
	v_mov_b32_e32 v1, v165
	v_cndmask_b32_e32 v0, v171, v176, vcc
	v_lshlrev_b32_e32 v91, 2, v0
	v_xor_b32_e32 v0, 8, v171
	v_cmp_lt_i32_e32 vcc, v0, v172
	v_lshl_add_u64 v[26:27], s[6:7], 0, v[164:165]
	s_mov_b64 s[44:45], s[48:49]
	v_cndmask_b32_e32 v0, v171, v0, vcc
	v_lshlrev_b32_e32 v92, 2, v0
	v_xor_b32_e32 v0, 16, v171
	v_cmp_lt_i32_e32 vcc, v0, v172
	s_mov_b64 s[46:47], s[50:51]
	v_lshl_add_u64 v[24:25], s[0:1], 0, v[164:165]
	v_cndmask_b32_e32 v0, v171, v0, vcc
	v_lshlrev_b32_e32 v93, 2, v0
	v_xor_b32_e32 v0, 32, v171
	v_cmp_lt_i32_e32 vcc, v0, v172
	v_lshl_add_u64 v[28:29], s[34:35], 0, v[164:165]
	s_mov_b64 s[42:43], 0
	v_cndmask_b32_e32 v0, v171, v0, vcc
	v_lshlrev_b32_e32 v94, 2, v0
	v_or_b32_e32 v0, 0x400, v164
	v_lshl_add_u64 v[30:31], s[6:7], 0, v[0:1]
	v_or_b32_e32 v0, 0x800, v164
	v_lshl_add_u64 v[32:33], s[6:7], 0, v[0:1]
	v_or_b32_e32 v0, 0xc00, v164
	v_lshl_add_u64 v[34:35], s[6:7], 0, v[0:1]
	v_or_b32_e32 v0, 0x1000, v164
	v_lshl_add_u64 v[36:37], s[0:1], 0, v[0:1]
	v_lshl_add_u64 v[38:39], s[6:7], 0, v[0:1]
	v_lshl_add_u64 v[40:41], s[34:35], 0, v[0:1]
	v_or_b32_e32 v0, 0x1400, v164
	v_lshl_add_u64 v[42:43], s[0:1], 0, v[0:1]
	v_lshl_add_u64 v[44:45], s[6:7], 0, v[0:1]
	v_lshl_add_u64 v[46:47], s[34:35], 0, v[0:1]
	v_or_b32_e32 v0, 0x1800, v164
	v_lshl_add_u64 v[48:49], s[0:1], 0, v[0:1]
	v_lshl_add_u64 v[50:51], s[6:7], 0, v[0:1]
	v_lshl_add_u64 v[52:53], s[34:35], 0, v[0:1]
	v_or_b32_e32 v0, 0x1c00, v164
	v_lshl_add_u64 v[56:57], s[6:7], 0, v[0:1]
	v_readlane_b32 s6, v254, 33
	v_lshl_add_u64 v[54:55], s[0:1], 0, v[0:1]
	v_lshl_add_u64 v[58:59], s[34:35], 0, v[0:1]
	v_add_u32_e32 v95, s6, v71
	v_readlane_b32 s6, v254, 32
	s_nop 1
	v_add_u32_e32 v0, s6, v71
	v_ashrrev_i32_e32 v1, 31, v0
	v_lshlrev_b64 v[60:61], 13, v[0:1]
	v_lshlrev_b64 v[62:63], 12, v[0:1]
	v_or_b32_e32 v60, v60, v164
	v_lshl_or_b32 v62, v70, 3, v62
	global_load_dwordx4 v[182:185], v[24:25], off
	global_load_dwordx4 v[186:189], v[24:25], off offset:1024
	global_load_dwordx4 v[190:193], v[24:25], off offset:2048
	global_load_dwordx4 v[194:197], v[24:25], off offset:3072
	global_load_dwordx4 v[198:201], v[36:37], off
	global_load_dwordx4 v[202:205], v[42:43], off
	global_load_dwordx4 v[206:209], v[48:49], off
	global_load_dwordx4 v[210:213], v[54:55], off
	global_load_dwordx4 v[214:217], v[26:27], off
	global_load_dwordx4 v[218:221], v[30:31], off
	global_load_dwordx4 v[222:225], v[32:33], off
	global_load_dwordx4 v[226:229], v[34:35], off
	global_load_dwordx4 v[230:233], v[38:39], off
	global_load_dwordx4 v[234:237], v[44:45], off
	global_load_dwordx4 v[238:241], v[50:51], off
	global_load_dwordx4 v[242:245], v[56:57], off
	global_load_dwordx4 v[0:3], v[28:29], off
	global_load_dwordx4 v[4:7], v[28:29], off offset:1024
	global_load_dwordx4 v[8:11], v[28:29], off offset:2048
	global_load_dwordx4 v[12:15], v[28:29], off offset:3072
	global_load_dwordx4 v[16:19], v[40:41], off
	global_load_dwordx4 v[20:23], v[46:47], off
	global_load_dwordx4 v[66:69], v[52:53], off
	global_load_dwordx4 v[70:73], v[58:59], off
	s_mov_b32 s101, 0x7060302
	v_lshl_add_u64 v[74:75], s[46:47], 0, v[60:61]
	v_add_co_u32_e32 v76, vcc, s12, v74
	s_nop 1
	v_addc_co_u32_e32 v77, vcc, 0, v75, vcc
	v_add_co_u32_e32 v74, vcc, 0xa000000, v74
	s_nop 1
	v_addc_co_u32_e32 v75, vcc, 0, v75, vcc
	global_load_dwordx4 v[100:103], v[74:75], off
	global_load_dwordx4 v[104:107], v[74:75], off offset:1024
	global_load_dwordx4 v[108:111], v[74:75], off offset:2048
	global_load_dwordx4 v[112:115], v[74:75], off offset:3072
	global_load_dwordx4 v[116:119], v[76:77], off
	global_load_dwordx4 v[120:123], v[76:77], off offset:1024
	global_load_dwordx4 v[124:127], v[76:77], off offset:2048
	global_load_dwordx4 v[128:131], v[76:77], off offset:3072
	v_lshl_add_u64 v[78:79], s[46:47], 0, v[62:63]
	v_add_co_u32_e32 v78, vcc, s13, v78
	s_nop 1
	v_addc_co_u32_e32 v79, vcc, 0, v79, vcc
	v_lshl_add_u64 v[60:61], v[60:61], 0, s[16:17]
	v_lshl_add_u64 v[62:63], v[62:63], 0, s[18:19]
	v_lshl_add_u64 v[74:75], s[46:47], 0, v[60:61]
	v_add_co_u32_e32 v76, vcc, s12, v74
	s_nop 1
	v_addc_co_u32_e32 v77, vcc, 0, v75, vcc
	v_add_co_u32_e32 v74, vcc, 0xa000000, v74
	s_nop 1
	v_addc_co_u32_e32 v75, vcc, 0, v75, vcc
	global_load_dwordx4 v[132:135], v[74:75], off
	global_load_dwordx4 v[136:139], v[74:75], off offset:1024
	global_load_dwordx4 v[140:143], v[74:75], off offset:2048
	global_load_dwordx4 v[144:147], v[74:75], off offset:3072
	global_load_dwordx4 v[148:151], v[76:77], off
	global_load_dwordx4 v[152:155], v[76:77], off offset:1024
	global_load_dwordx4 v[156:159], v[76:77], off offset:2048
	global_load_dwordx4 v[160:163], v[76:77], off offset:3072
	s_waitcnt vmcnt(8)
; __device__ __forceinline__ unsigned pk2(float lo, float hi) { return f2bf(lo) | (f2bf(hi) << 16); }
; __device__ __forceinline__ void norm_rows(const float* X, const float* nw, const float* md, u16* H, int row0, int nrows, int wave, int lane) {
;     for (int row = row0 + wave; row < row0 + nrows; row += 8) {
;         const float4* xr = (const float4*)(X + (size_t)row * DM) + lane; float4 v[8]; float ss = 0.f;
; #pragma unroll
;         for (int j = 0; j < 8; ++j) { v[j] = xr[64 * j]; ss += v[j].x * v[j].x + v[j].y * v[j].y + v[j].z * v[j].z + v[j].w * v[j].w; }
;         const float r = rsqrtf(wave_sum(ss) * (1.f / DM) + EPS);
;         uint2* hp = (uint2*)(H + (size_t)row * DM) + lane;
; #pragma unroll
;         for (int j = 0; j < 8; ++j) { const int col = 4 * (lane + 64 * j); const float4 w4 = *(const float4*)(nw + col), sc = *(const float4*)(md + 2048 + col), sh = *(const float4*)(md + col);
;             uint2 o; o.x = pk2(v[j].x * r * w4.x * (1.f + sc.x) + sh.x, v[j].y * r * w4.y * (1.f + sc.y) + sh.y);
;             o.y = pk2(v[j].z * r * w4.z * (1.f + sc.z) + sh.z, v[j].w * r * w4.w * (1.f + sc.w) + sh.w); hp[64 * j] = o; } }
	v_add_f32_e32 v214, 1.0, v214
	v_add_f32_e32 v215, 1.0, v215
	v_add_f32_e32 v216, 1.0, v216
	v_add_f32_e32 v217, 1.0, v217
	v_add_f32_e32 v218, 1.0, v218
	v_add_f32_e32 v219, 1.0, v219
	v_add_f32_e32 v220, 1.0, v220
	v_add_f32_e32 v221, 1.0, v221
	v_add_f32_e32 v222, 1.0, v222
	v_add_f32_e32 v223, 1.0, v223
	v_add_f32_e32 v224, 1.0, v224
	v_add_f32_e32 v225, 1.0, v225
	v_add_f32_e32 v226, 1.0, v226
	v_add_f32_e32 v227, 1.0, v227
	v_add_f32_e32 v228, 1.0, v228
	v_add_f32_e32 v229, 1.0, v229
	v_add_f32_e32 v230, 1.0, v230
	v_add_f32_e32 v231, 1.0, v231
	v_add_f32_e32 v232, 1.0, v232
	v_add_f32_e32 v233, 1.0, v233
	v_add_f32_e32 v234, 1.0, v234
	v_add_f32_e32 v235, 1.0, v235
	v_add_f32_e32 v236, 1.0, v236
	v_add_f32_e32 v237, 1.0, v237
	v_add_f32_e32 v238, 1.0, v238
	v_add_f32_e32 v239, 1.0, v239
	v_add_f32_e32 v240, 1.0, v240
	v_add_f32_e32 v241, 1.0, v241
	v_add_f32_e32 v242, 1.0, v242
	v_add_f32_e32 v243, 1.0, v243
	v_add_f32_e32 v244, 1.0, v244
	v_add_f32_e32 v245, 1.0, v245
	v_mul_f32_e32 v81, v101, v101
	v_fmac_f32_e32 v81, v100, v100
	v_fmac_f32_e32 v81, v102, v102
	v_fmac_f32_e32 v81, v103, v103
	v_mul_f32_e32 v80, v105, v105
	v_fmac_f32_e32 v80, v104, v104
	v_fmac_f32_e32 v80, v106, v106
	v_fmac_f32_e32 v80, v107, v107
	v_add_f32_e32 v81, v81, v80
	v_mul_f32_e32 v80, v109, v109
	v_fmac_f32_e32 v80, v108, v108
	v_fmac_f32_e32 v80, v110, v110
	v_fmac_f32_e32 v80, v111, v111
	v_add_f32_e32 v81, v81, v80
	v_mul_f32_e32 v80, v113, v113
	v_fmac_f32_e32 v80, v112, v112
	v_fmac_f32_e32 v80, v114, v114
	v_fmac_f32_e32 v80, v115, v115
	v_add_f32_e32 v81, v81, v80
	v_mul_f32_e32 v80, v117, v117
	v_fmac_f32_e32 v80, v116, v116
	v_fmac_f32_e32 v80, v118, v118
	v_fmac_f32_e32 v80, v119, v119
	v_add_f32_e32 v81, v81, v80
	v_mul_f32_e32 v80, v121, v121
	v_fmac_f32_e32 v80, v120, v120
	v_fmac_f32_e32 v80, v122, v122
	v_fmac_f32_e32 v80, v123, v123
	v_add_f32_e32 v81, v81, v80
	v_mul_f32_e32 v80, v125, v125
	v_fmac_f32_e32 v80, v124, v124
	v_fmac_f32_e32 v80, v126, v126
	v_fmac_f32_e32 v80, v127, v127
	v_add_f32_e32 v81, v81, v80
	v_mul_f32_e32 v80, v129, v129
	v_fmac_f32_e32 v80, v128, v128
	v_fmac_f32_e32 v80, v130, v130
	v_fmac_f32_e32 v80, v131, v131
	v_add_f32_e32 v81, v81, v80
	s_waitcnt lgkmcnt(0)
	s_nop 1
	v_add_f32_dpp v81, v81, v81 quad_perm:[1,0,3,2] row_mask:0xf bank_mask:0xf
	s_waitcnt lgkmcnt(0)
	s_nop 1
	v_add_f32_dpp v81, v81, v81 quad_perm:[2,3,0,1] row_mask:0xf bank_mask:0xf
	s_waitcnt lgkmcnt(0)
	s_nop 1
	v_add_f32_dpp v81, v81, v81 row_half_mirror row_mask:0xf bank_mask:0xf
	s_waitcnt lgkmcnt(0)
	s_nop 1
	v_add_f32_dpp v81, v81, v81 row_mirror row_mask:0xf bank_mask:0xf
	s_waitcnt lgkmcnt(0)
	v_mov_b32_e32 v80, v81
	s_nop 1
	v_permlane16_swap_b32_e32 v81, v80
	v_add_f32_e32 v81, v81, v80
	s_waitcnt lgkmcnt(0)
	v_mov_b32_e32 v80, v81
	s_nop 1
	v_permlane32_swap_b32_e32 v81, v80
	v_add_f32_e32 v81, v81, v80
	v_fmamk_f32 v81, v81, 0x3a000000, v179
	v_cmp_gt_f32_e32 vcc, s91, v81
	v_mul_f32_e32 v80, 0x4b800000, v81
	s_nop 0
	v_cndmask_b32_e32 v81, v81, v80, vcc
	v_rsq_f32_e32 v81, v81
	s_nop 0
	v_mul_f32_e32 v80, 0x45800000, v81
	v_cndmask_b32_e32 v82, v81, v80, vcc
	v_mul_f32_e32 v84, v100, v82
	v_mul_f32_e32 v85, v101, v82
	v_mul_f32_e32 v86, v102, v82
	v_mul_f32_e32 v87, v103, v82
	v_mul_f32_e32 v84, v182, v84
	v_mul_f32_e32 v85, v183, v85
	v_mul_f32_e32 v86, v184, v86
	v_mul_f32_e32 v87, v185, v87
	v_fma_f32 v84, v214, v84, v0
	v_fma_f32 v85, v215, v85, v1
	v_fma_f32 v86, v216, v86, v2
	v_fma_f32 v87, v217, v87, v3
	v_bfe_u32 v88, v84, 16, 1
	v_bfe_u32 v89, v85, 16, 1
	v_bfe_u32 v96, v86, 16, 1
	v_bfe_u32 v97, v87, 16, 1
	v_add3_u32 v84, v84, v88, s3
	v_add3_u32 v85, v85, v89, s3
	v_add3_u32 v86, v86, v96, s3
	v_add3_u32 v87, v87, v97, s3
	v_perm_b32 v98, v85, v84, s101
	v_perm_b32 v99, v87, v86, s101
	global_store_dwordx2 v[78:79], v[98:99], off
	v_mul_f32_e32 v84, v104, v82
	v_mul_f32_e32 v85, v105, v82
	v_mul_f32_e32 v86, v106, v82
	v_mul_f32_e32 v87, v107, v82
	v_mul_f32_e32 v84, v186, v84
	v_mul_f32_e32 v85, v187, v85
	v_mul_f32_e32 v86, v188, v86
	v_mul_f32_e32 v87, v189, v87
	v_fma_f32 v84, v218, v84, v4
	v_fma_f32 v85, v219, v85, v5
	v_fma_f32 v86, v220, v86, v6
	v_fma_f32 v87, v221, v87, v7
	v_bfe_u32 v88, v84, 16, 1
	v_bfe_u32 v89, v85, 16, 1
	v_bfe_u32 v96, v86, 16, 1
	v_bfe_u32 v97, v87, 16, 1
	v_add3_u32 v84, v84, v88, s3
	v_add3_u32 v85, v85, v89, s3
	v_add3_u32 v86, v86, v96, s3
	v_add3_u32 v87, v87, v97, s3
	v_perm_b32 v248, v85, v84, s101
	v_perm_b32 v249, v87, v86, s101
	global_store_dwordx2 v[78:79], v[248:249], off offset:512
	v_mul_f32_e32 v84, v108, v82
	v_mul_f32_e32 v85, v109, v82
	v_mul_f32_e32 v86, v110, v82
	v_mul_f32_e32 v87, v111, v82
	v_mul_f32_e32 v84, v190, v84
	v_mul_f32_e32 v85, v191, v85
	v_mul_f32_e32 v86, v192, v86
	v_mul_f32_e32 v87, v193, v87
	v_fma_f32 v84, v222, v84, v8
	v_fma_f32 v85, v223, v85, v9
	v_fma_f32 v86, v224, v86, v10
	v_fma_f32 v87, v225, v87, v11
	v_bfe_u32 v88, v84, 16, 1
	v_bfe_u32 v89, v85, 16, 1
	v_bfe_u32 v96, v86, 16, 1
	v_bfe_u32 v97, v87, 16, 1
	v_add3_u32 v84, v84, v88, s3
	v_add3_u32 v85, v85, v89, s3
	v_add3_u32 v86, v86, v96, s3
	v_add3_u32 v87, v87, v97, s3
	v_perm_b32 v98, v85, v84, s101
	v_perm_b32 v99, v87, v86, s101
	global_store_dwordx2 v[78:79], v[98:99], off offset:1024
	v_mul_f32_e32 v84, v112, v82
	v_mul_f32_e32 v85, v113, v82
	v_mul_f32_e32 v86, v114, v82
	v_mul_f32_e32 v87, v115, v82
	v_mul_f32_e32 v84, v194, v84
	v_mul_f32_e32 v85, v195, v85
	v_mul_f32_e32 v86, v196, v86
	v_mul_f32_e32 v87, v197, v87
	v_fma_f32 v84, v226, v84, v12
	v_fma_f32 v85, v227, v85, v13
	v_fma_f32 v86, v228, v86, v14
	v_fma_f32 v87, v229, v87, v15
	v_bfe_u32 v88, v84, 16, 1
; __device__ __forceinline__ unsigned pk2(float lo, float hi) { return f2bf(lo) | (f2bf(hi) << 16); }
; __device__ __forceinline__ void norm_rows(const float* X, const float* nw, const float* md, u16* H, int row0, int nrows, int wave, int lane) {
;     for (int row = row0 + wave; row < row0 + nrows; row += 8) {
;         const float4* xr = (const float4*)(X + (size_t)row * DM) + lane; float4 v[8]; float ss = 0.f;
; #pragma unroll
;         for (int j = 0; j < 8; ++j) { v[j] = xr[64 * j]; ss += v[j].x * v[j].x + v[j].y * v[j].y + v[j].z * v[j].z + v[j].w * v[j].w; }
;         const float r = rsqrtf(wave_sum(ss) * (1.f / DM) + EPS);
;         uint2* hp = (uint2*)(H + (size_t)row * DM) + lane;
; #pragma unroll
;         for (int j = 0; j < 8; ++j) { const int col = 4 * (lane + 64 * j); const float4 w4 = *(const float4*)(nw + col), sc = *(const float4*)(md + 2048 + col), sh = *(const float4*)(md + col);
;             uint2 o; o.x = pk2(v[j].x * r * w4.x * (1.f + sc.x) + sh.x, v[j].y * r * w4.y * (1.f + sc.y) + sh.y);
;             o.y = pk2(v[j].z * r * w4.z * (1.f + sc.z) + sh.z, v[j].w * r * w4.w * (1.f + sc.w) + sh.w); hp[64 * j] = o; } }
	v_bfe_u32 v89, v85, 16, 1
	v_bfe_u32 v96, v86, 16, 1
	v_bfe_u32 v97, v87, 16, 1
	v_add3_u32 v84, v84, v88, s3
	v_add3_u32 v85, v85, v89, s3
	v_add3_u32 v86, v86, v96, s3
	v_add3_u32 v87, v87, v97, s3
	v_perm_b32 v248, v85, v84, s101
	v_perm_b32 v249, v87, v86, s101
	global_store_dwordx2 v[78:79], v[248:249], off offset:1536
	v_mul_f32_e32 v84, v116, v82
	v_mul_f32_e32 v85, v117, v82
	v_mul_f32_e32 v86, v118, v82
	v_mul_f32_e32 v87, v119, v82
	v_mul_f32_e32 v84, v198, v84
	v_mul_f32_e32 v85, v199, v85
	v_mul_f32_e32 v86, v200, v86
	v_mul_f32_e32 v87, v201, v87
	v_fma_f32 v84, v230, v84, v16
	v_fma_f32 v85, v231, v85, v17
	v_fma_f32 v86, v232, v86, v18
	v_fma_f32 v87, v233, v87, v19
	v_bfe_u32 v88, v84, 16, 1
	v_bfe_u32 v89, v85, 16, 1
	v_bfe_u32 v96, v86, 16, 1
	v_bfe_u32 v97, v87, 16, 1
	v_add3_u32 v84, v84, v88, s3
	v_add3_u32 v85, v85, v89, s3
	v_add3_u32 v86, v86, v96, s3
	v_add3_u32 v87, v87, v97, s3
	v_perm_b32 v98, v85, v84, s101
	v_perm_b32 v99, v87, v86, s101
	global_store_dwordx2 v[78:79], v[98:99], off offset:2048
	v_mul_f32_e32 v84, v120, v82
	v_mul_f32_e32 v85, v121, v82
	v_mul_f32_e32 v86, v122, v82
	v_mul_f32_e32 v87, v123, v82
	v_mul_f32_e32 v84, v202, v84
	v_mul_f32_e32 v85, v203, v85
	v_mul_f32_e32 v86, v204, v86
	v_mul_f32_e32 v87, v205, v87
	v_fma_f32 v84, v234, v84, v20
	v_fma_f32 v85, v235, v85, v21
	v_fma_f32 v86, v236, v86, v22
	v_fma_f32 v87, v237, v87, v23
	v_bfe_u32 v88, v84, 16, 1
	v_bfe_u32 v89, v85, 16, 1
	v_bfe_u32 v96, v86, 16, 1
	v_bfe_u32 v97, v87, 16, 1
	v_add3_u32 v84, v84, v88, s3
	v_add3_u32 v85, v85, v89, s3
	v_add3_u32 v86, v86, v96, s3
	v_add3_u32 v87, v87, v97, s3
	v_perm_b32 v248, v85, v84, s101
	v_perm_b32 v249, v87, v86, s101
	global_store_dwordx2 v[78:79], v[248:249], off offset:2560
	v_mul_f32_e32 v84, v124, v82
	v_mul_f32_e32 v85, v125, v82
	v_mul_f32_e32 v86, v126, v82
	v_mul_f32_e32 v87, v127, v82
	v_mul_f32_e32 v84, v206, v84
	v_mul_f32_e32 v85, v207, v85
	v_mul_f32_e32 v86, v208, v86
	v_mul_f32_e32 v87, v209, v87
	v_fma_f32 v84, v238, v84, v66
	v_fma_f32 v85, v239, v85, v67
	v_fma_f32 v86, v240, v86, v68
	v_fma_f32 v87, v241, v87, v69
	v_bfe_u32 v88, v84, 16, 1
	v_bfe_u32 v89, v85, 16, 1
	v_bfe_u32 v96, v86, 16, 1
	v_bfe_u32 v97, v87, 16, 1
	v_add3_u32 v84, v84, v88, s3
	v_add3_u32 v85, v85, v89, s3
	v_add3_u32 v86, v86, v96, s3
	v_add3_u32 v87, v87, v97, s3
	v_perm_b32 v98, v85, v84, s101
	v_perm_b32 v99, v87, v86, s101
	global_store_dwordx2 v[78:79], v[98:99], off offset:3072
	v_mul_f32_e32 v84, v128, v82
	v_mul_f32_e32 v85, v129, v82
	v_mul_f32_e32 v86, v130, v82
	v_mul_f32_e32 v87, v131, v82
	v_mul_f32_e32 v84, v210, v84
	v_mul_f32_e32 v85, v211, v85
	v_mul_f32_e32 v86, v212, v86
	v_mul_f32_e32 v87, v213, v87
	v_fma_f32 v84, v242, v84, v70
	v_fma_f32 v85, v243, v85, v71
	v_fma_f32 v86, v244, v86, v72
	v_fma_f32 v87, v245, v87, v73
	v_bfe_u32 v88, v84, 16, 1
	v_bfe_u32 v89, v85, 16, 1
	v_bfe_u32 v96, v86, 16, 1
	v_bfe_u32 v97, v87, 16, 1
	v_add3_u32 v84, v84, v88, s3
	v_add3_u32 v85, v85, v89, s3
	v_add3_u32 v86, v86, v96, s3
	v_add3_u32 v87, v87, v97, s3
	v_perm_b32 v248, v85, v84, s101
	v_perm_b32 v249, v87, v86, s101
	global_store_dwordx2 v[78:79], v[248:249], off offset:3584
	v_lshl_add_u64 v[78:79], s[46:47], 0, v[62:63]
	v_add_co_u32_e32 v78, vcc, s13, v78
	s_nop 1
	v_addc_co_u32_e32 v79, vcc, 0, v79, vcc
	v_lshl_add_u64 v[60:61], v[60:61], 0, s[16:17]
	v_lshl_add_u64 v[62:63], v[62:63], 0, s[18:19]
	v_lshl_add_u64 v[74:75], s[46:47], 0, v[60:61]
	v_add_co_u32_e32 v76, vcc, s12, v74
	s_nop 1
	v_addc_co_u32_e32 v77, vcc, 0, v75, vcc
	v_add_co_u32_e32 v74, vcc, 0xa000000, v74
	s_nop 1
	v_addc_co_u32_e32 v75, vcc, 0, v75, vcc
	global_load_dwordx4 v[100:103], v[74:75], off
	global_load_dwordx4 v[104:107], v[74:75], off offset:1024
	global_load_dwordx4 v[108:111], v[74:75], off offset:2048
	global_load_dwordx4 v[112:115], v[74:75], off offset:3072
	global_load_dwordx4 v[116:119], v[76:77], off
	global_load_dwordx4 v[120:123], v[76:77], off offset:1024
	global_load_dwordx4 v[124:127], v[76:77], off offset:2048
	global_load_dwordx4 v[128:131], v[76:77], off offset:3072
	s_waitcnt vmcnt(16)
	v_mul_f32_e32 v81, v133, v133
	v_fmac_f32_e32 v81, v132, v132
	v_fmac_f32_e32 v81, v134, v134
	v_fmac_f32_e32 v81, v135, v135
	v_mul_f32_e32 v80, v137, v137
	v_fmac_f32_e32 v80, v136, v136
	v_fmac_f32_e32 v80, v138, v138
	v_fmac_f32_e32 v80, v139, v139
	v_add_f32_e32 v81, v81, v80
	v_mul_f32_e32 v80, v141, v141
	v_fmac_f32_e32 v80, v140, v140
	v_fmac_f32_e32 v80, v142, v142
	v_fmac_f32_e32 v80, v143, v143
	v_add_f32_e32 v81, v81, v80
	v_mul_f32_e32 v80, v145, v145
	v_fmac_f32_e32 v80, v144, v144
	v_fmac_f32_e32 v80, v146, v146
	v_fmac_f32_e32 v80, v147, v147
	v_add_f32_e32 v81, v81, v80
	v_mul_f32_e32 v80, v149, v149
	v_fmac_f32_e32 v80, v148, v148
	v_fmac_f32_e32 v80, v150, v150
	v_fmac_f32_e32 v80, v151, v151
	v_add_f32_e32 v81, v81, v80
	v_mul_f32_e32 v80, v153, v153
	v_fmac_f32_e32 v80, v152, v152
	v_fmac_f32_e32 v80, v154, v154
	v_fmac_f32_e32 v80, v155, v155
	v_add_f32_e32 v81, v81, v80
	v_mul_f32_e32 v80, v157, v157
	v_fmac_f32_e32 v80, v156, v156
	v_fmac_f32_e32 v80, v158, v158
	v_fmac_f32_e32 v80, v159, v159
	v_add_f32_e32 v81, v81, v80
	v_mul_f32_e32 v80, v161, v161
	v_fmac_f32_e32 v80, v160, v160
	v_fmac_f32_e32 v80, v162, v162
	v_fmac_f32_e32 v80, v163, v163
	v_add_f32_e32 v81, v81, v80
	s_waitcnt lgkmcnt(0)
	s_nop 1
	v_add_f32_dpp v81, v81, v81 quad_perm:[1,0,3,2] row_mask:0xf bank_mask:0xf
	s_waitcnt lgkmcnt(0)
	s_nop 1
	v_add_f32_dpp v81, v81, v81 quad_perm:[2,3,0,1] row_mask:0xf bank_mask:0xf
	s_waitcnt lgkmcnt(0)
	s_nop 1
	v_add_f32_dpp v81, v81, v81 row_half_mirror row_mask:0xf bank_mask:0xf
	s_waitcnt lgkmcnt(0)
; __device__ __forceinline__ unsigned pk2(float lo, float hi) { return f2bf(lo) | (f2bf(hi) << 16); }
; __device__ __forceinline__ void norm_rows(const float* X, const float* nw, const float* md, u16* H, int row0, int nrows, int wave, int lane) {
;     for (int row = row0 + wave; row < row0 + nrows; row += 8) {
;         const float4* xr = (const float4*)(X + (size_t)row * DM) + lane; float4 v[8]; float ss = 0.f;
; #pragma unroll
;         for (int j = 0; j < 8; ++j) { v[j] = xr[64 * j]; ss += v[j].x * v[j].x + v[j].y * v[j].y + v[j].z * v[j].z + v[j].w * v[j].w; }
;         const float r = rsqrtf(wave_sum(ss) * (1.f / DM) + EPS);
;         uint2* hp = (uint2*)(H + (size_t)row * DM) + lane;
; #pragma unroll
;         for (int j = 0; j < 8; ++j) { const int col = 4 * (lane + 64 * j); const float4 w4 = *(const float4*)(nw + col), sc = *(const float4*)(md + 2048 + col), sh = *(const float4*)(md + col);
;             uint2 o; o.x = pk2(v[j].x * r * w4.x * (1.f + sc.x) + sh.x, v[j].y * r * w4.y * (1.f + sc.y) + sh.y);
;             o.y = pk2(v[j].z * r * w4.z * (1.f + sc.z) + sh.z, v[j].w * r * w4.w * (1.f + sc.w) + sh.w); hp[64 * j] = o; } }
	s_nop 1
	v_add_f32_dpp v81, v81, v81 row_mirror row_mask:0xf bank_mask:0xf
	s_waitcnt lgkmcnt(0)
	v_mov_b32_e32 v80, v81
	s_nop 1
	v_permlane16_swap_b32_e32 v81, v80
	v_add_f32_e32 v81, v81, v80
	s_waitcnt lgkmcnt(0)
	v_mov_b32_e32 v80, v81
	s_nop 1
	v_permlane32_swap_b32_e32 v81, v80
	v_add_f32_e32 v81, v81, v80
	v_fmamk_f32 v81, v81, 0x3a000000, v179
	v_cmp_gt_f32_e32 vcc, s91, v81
	v_mul_f32_e32 v80, 0x4b800000, v81
	s_nop 0
	v_cndmask_b32_e32 v81, v81, v80, vcc
	v_rsq_f32_e32 v81, v81
	s_nop 0
	v_mul_f32_e32 v80, 0x45800000, v81
	v_cndmask_b32_e32 v82, v81, v80, vcc
	v_mul_f32_e32 v84, v132, v82
	v_mul_f32_e32 v85, v133, v82
	v_mul_f32_e32 v86, v134, v82
	v_mul_f32_e32 v87, v135, v82
	v_mul_f32_e32 v84, v182, v84
	v_mul_f32_e32 v85, v183, v85
	v_mul_f32_e32 v86, v184, v86
	v_mul_f32_e32 v87, v185, v87
	v_fma_f32 v84, v214, v84, v0
	v_fma_f32 v85, v215, v85, v1
	v_fma_f32 v86, v216, v86, v2
	v_fma_f32 v87, v217, v87, v3
	v_bfe_u32 v88, v84, 16, 1
	v_bfe_u32 v89, v85, 16, 1
	v_bfe_u32 v96, v86, 16, 1
	v_bfe_u32 v97, v87, 16, 1
	v_add3_u32 v84, v84, v88, s3
	v_add3_u32 v85, v85, v89, s3
	v_add3_u32 v86, v86, v96, s3
	v_add3_u32 v87, v87, v97, s3
	v_perm_b32 v98, v85, v84, s101
	v_perm_b32 v99, v87, v86, s101
	global_store_dwordx2 v[78:79], v[98:99], off
	v_mul_f32_e32 v84, v136, v82
	v_mul_f32_e32 v85, v137, v82
	v_mul_f32_e32 v86, v138, v82
	v_mul_f32_e32 v87, v139, v82
	v_mul_f32_e32 v84, v186, v84
	v_mul_f32_e32 v85, v187, v85
	v_mul_f32_e32 v86, v188, v86
	v_mul_f32_e32 v87, v189, v87
	v_fma_f32 v84, v218, v84, v4
	v_fma_f32 v85, v219, v85, v5
	v_fma_f32 v86, v220, v86, v6
	v_fma_f32 v87, v221, v87, v7
	v_bfe_u32 v88, v84, 16, 1
	v_bfe_u32 v89, v85, 16, 1
	v_bfe_u32 v96, v86, 16, 1
	v_bfe_u32 v97, v87, 16, 1
	v_add3_u32 v84, v84, v88, s3
	v_add3_u32 v85, v85, v89, s3
	v_add3_u32 v86, v86, v96, s3
	v_add3_u32 v87, v87, v97, s3
	v_perm_b32 v248, v85, v84, s101
	v_perm_b32 v249, v87, v86, s101
	global_store_dwordx2 v[78:79], v[248:249], off offset:512
	v_mul_f32_e32 v84, v140, v82
	v_mul_f32_e32 v85, v141, v82
	v_mul_f32_e32 v86, v142, v82
	v_mul_f32_e32 v87, v143, v82
	v_mul_f32_e32 v84, v190, v84
	v_mul_f32_e32 v85, v191, v85
	v_mul_f32_e32 v86, v192, v86
	v_mul_f32_e32 v87, v193, v87
	v_fma_f32 v84, v222, v84, v8
	v_fma_f32 v85, v223, v85, v9
	v_fma_f32 v86, v224, v86, v10
	v_fma_f32 v87, v225, v87, v11
	v_bfe_u32 v88, v84, 16, 1
	v_bfe_u32 v89, v85, 16, 1
	v_bfe_u32 v96, v86, 16, 1
	v_bfe_u32 v97, v87, 16, 1
	v_add3_u32 v84, v84, v88, s3
	v_add3_u32 v85, v85, v89, s3
	v_add3_u32 v86, v86, v96, s3
	v_add3_u32 v87, v87, v97, s3
	v_perm_b32 v98, v85, v84, s101
	v_perm_b32 v99, v87, v86, s101
	global_store_dwordx2 v[78:79], v[98:99], off offset:1024
	v_mul_f32_e32 v84, v144, v82
	v_mul_f32_e32 v85, v145, v82
	v_mul_f32_e32 v86, v146, v82
	v_mul_f32_e32 v87, v147, v82
	v_mul_f32_e32 v84, v194, v84
	v_mul_f32_e32 v85, v195, v85
	v_mul_f32_e32 v86, v196, v86
	v_mul_f32_e32 v87, v197, v87
	v_fma_f32 v84, v226, v84, v12
	v_fma_f32 v85, v227, v85, v13
	v_fma_f32 v86, v228, v86, v14
	v_fma_f32 v87, v229, v87, v15
	v_bfe_u32 v88, v84, 16, 1
	v_bfe_u32 v89, v85, 16, 1
	v_bfe_u32 v96, v86, 16, 1
	v_bfe_u32 v97, v87, 16, 1
	v_add3_u32 v84, v84, v88, s3
	v_add3_u32 v85, v85, v89, s3
	v_add3_u32 v86, v86, v96, s3
	v_add3_u32 v87, v87, v97, s3
	v_perm_b32 v248, v85, v84, s101
	v_perm_b32 v249, v87, v86, s101
	global_store_dwordx2 v[78:79], v[248:249], off offset:1536
	v_mul_f32_e32 v84, v148, v82
	v_mul_f32_e32 v85, v149, v82
	v_mul_f32_e32 v86, v150, v82
	v_mul_f32_e32 v87, v151, v82
	v_mul_f32_e32 v84, v198, v84
	v_mul_f32_e32 v85, v199, v85
	v_mul_f32_e32 v86, v200, v86
	v_mul_f32_e32 v87, v201, v87
	v_fma_f32 v84, v230, v84, v16
	v_fma_f32 v85, v231, v85, v17
	v_fma_f32 v86, v232, v86, v18
	v_fma_f32 v87, v233, v87, v19
	v_bfe_u32 v88, v84, 16, 1
	v_bfe_u32 v89, v85, 16, 1
	v_bfe_u32 v96, v86, 16, 1
	v_bfe_u32 v97, v87, 16, 1
	v_add3_u32 v84, v84, v88, s3
	v_add3_u32 v85, v85, v89, s3
	v_add3_u32 v86, v86, v96, s3
	v_add3_u32 v87, v87, v97, s3
	v_perm_b32 v98, v85, v84, s101
	v_perm_b32 v99, v87, v86, s101
	global_store_dwordx2 v[78:79], v[98:99], off offset:2048
	v_mul_f32_e32 v84, v152, v82
	v_mul_f32_e32 v85, v153, v82
	v_mul_f32_e32 v86, v154, v82
	v_mul_f32_e32 v87, v155, v82
	v_mul_f32_e32 v84, v202, v84
	v_mul_f32_e32 v85, v203, v85
	v_mul_f32_e32 v86, v204, v86
	v_mul_f32_e32 v87, v205, v87
	v_fma_f32 v84, v234, v84, v20
	v_fma_f32 v85, v235, v85, v21
	v_fma_f32 v86, v236, v86, v22
	v_fma_f32 v87, v237, v87, v23
	v_bfe_u32 v88, v84, 16, 1
	v_bfe_u32 v89, v85, 16, 1
	v_bfe_u32 v96, v86, 16, 1
	v_bfe_u32 v97, v87, 16, 1
	v_add3_u32 v84, v84, v88, s3
	v_add3_u32 v85, v85, v89, s3
	v_add3_u32 v86, v86, v96, s3
	v_add3_u32 v87, v87, v97, s3
	v_perm_b32 v248, v85, v84, s101
	v_perm_b32 v249, v87, v86, s101
	global_store_dwordx2 v[78:79], v[248:249], off offset:2560
	v_mul_f32_e32 v84, v156, v82
	v_mul_f32_e32 v85, v157, v82
	v_mul_f32_e32 v86, v158, v82
	v_mul_f32_e32 v87, v159, v82
	v_mul_f32_e32 v84, v206, v84
	v_mul_f32_e32 v85, v207, v85
	v_mul_f32_e32 v86, v208, v86
	v_mul_f32_e32 v87, v209, v87
	v_fma_f32 v84, v238, v84, v66
	v_fma_f32 v85, v239, v85, v67
	v_fma_f32 v86, v240, v86, v68
	v_fma_f32 v87, v241, v87, v69
	v_bfe_u32 v88, v84, 16, 1
	v_bfe_u32 v89, v85, 16, 1
	v_bfe_u32 v96, v86, 16, 1
	v_bfe_u32 v97, v87, 16, 1
	v_add3_u32 v84, v84, v88, s3
	v_add3_u32 v85, v85, v89, s3
	v_add3_u32 v86, v86, v96, s3
	v_add3_u32 v87, v87, v97, s3
	v_perm_b32 v98, v85, v84, s101
	v_perm_b32 v99, v87, v86, s101
	global_store_dwordx2 v[78:79], v[98:99], off offset:3072
	v_mul_f32_e32 v84, v160, v82
	v_mul_f32_e32 v85, v161, v82
; __device__ __forceinline__ unsigned pk2(float lo, float hi) { return f2bf(lo) | (f2bf(hi) << 16); }
; __device__ __forceinline__ void norm_rows(const float* X, const float* nw, const float* md, u16* H, int row0, int nrows, int wave, int lane) {
;     for (int row = row0 + wave; row < row0 + nrows; row += 8) {
;         const float4* xr = (const float4*)(X + (size_t)row * DM) + lane; float4 v[8]; float ss = 0.f;
; #pragma unroll
;         for (int j = 0; j < 8; ++j) { v[j] = xr[64 * j]; ss += v[j].x * v[j].x + v[j].y * v[j].y + v[j].z * v[j].z + v[j].w * v[j].w; }
;         const float r = rsqrtf(wave_sum(ss) * (1.f / DM) + EPS);
;         uint2* hp = (uint2*)(H + (size_t)row * DM) + lane;
; #pragma unroll
;         for (int j = 0; j < 8; ++j) { const int col = 4 * (lane + 64 * j); const float4 w4 = *(const float4*)(nw + col), sc = *(const float4*)(md + 2048 + col), sh = *(const float4*)(md + col);
;             uint2 o; o.x = pk2(v[j].x * r * w4.x * (1.f + sc.x) + sh.x, v[j].y * r * w4.y * (1.f + sc.y) + sh.y);
;             o.y = pk2(v[j].z * r * w4.z * (1.f + sc.z) + sh.z, v[j].w * r * w4.w * (1.f + sc.w) + sh.w); hp[64 * j] = o; } }
	v_mul_f32_e32 v86, v162, v82
	v_mul_f32_e32 v87, v163, v82
	v_mul_f32_e32 v84, v210, v84
	v_mul_f32_e32 v85, v211, v85
	v_mul_f32_e32 v86, v212, v86
	v_mul_f32_e32 v87, v213, v87
	v_fma_f32 v84, v242, v84, v70
	v_fma_f32 v85, v243, v85, v71
	v_fma_f32 v86, v244, v86, v72
	v_fma_f32 v87, v245, v87, v73
	v_bfe_u32 v88, v84, 16, 1
	v_bfe_u32 v89, v85, 16, 1
	v_bfe_u32 v96, v86, 16, 1
	v_bfe_u32 v97, v87, 16, 1
	v_add3_u32 v84, v84, v88, s3
	v_add3_u32 v85, v85, v89, s3
	v_add3_u32 v86, v86, v96, s3
	v_add3_u32 v87, v87, v97, s3
	v_perm_b32 v248, v85, v84, s101
	v_perm_b32 v249, v87, v86, s101
	global_store_dwordx2 v[78:79], v[248:249], off offset:3584
	v_lshl_add_u64 v[78:79], s[46:47], 0, v[62:63]
	v_add_co_u32_e32 v78, vcc, s13, v78
	s_nop 1
	v_addc_co_u32_e32 v79, vcc, 0, v79, vcc
	v_lshl_add_u64 v[60:61], v[60:61], 0, s[16:17]
	v_lshl_add_u64 v[62:63], v[62:63], 0, s[18:19]
	v_lshl_add_u64 v[74:75], s[46:47], 0, v[60:61]
	v_add_co_u32_e32 v76, vcc, s12, v74
	s_nop 1
	v_addc_co_u32_e32 v77, vcc, 0, v75, vcc
	v_add_co_u32_e32 v74, vcc, 0xa000000, v74
	s_nop 1
	v_addc_co_u32_e32 v75, vcc, 0, v75, vcc
	global_load_dwordx4 v[132:135], v[74:75], off
	global_load_dwordx4 v[136:139], v[74:75], off offset:1024
	global_load_dwordx4 v[140:143], v[74:75], off offset:2048
	global_load_dwordx4 v[144:147], v[74:75], off offset:3072
	global_load_dwordx4 v[148:151], v[76:77], off
	global_load_dwordx4 v[152:155], v[76:77], off offset:1024
	global_load_dwordx4 v[156:159], v[76:77], off offset:2048
	global_load_dwordx4 v[160:163], v[76:77], off offset:3072
	s_waitcnt vmcnt(16)
	v_mul_f32_e32 v81, v101, v101
	v_fmac_f32_e32 v81, v100, v100
	v_fmac_f32_e32 v81, v102, v102
	v_fmac_f32_e32 v81, v103, v103
	v_mul_f32_e32 v80, v105, v105
	v_fmac_f32_e32 v80, v104, v104
	v_fmac_f32_e32 v80, v106, v106
	v_fmac_f32_e32 v80, v107, v107
	v_add_f32_e32 v81, v81, v80
	v_mul_f32_e32 v80, v109, v109
	v_fmac_f32_e32 v80, v108, v108
	v_fmac_f32_e32 v80, v110, v110
	v_fmac_f32_e32 v80, v111, v111
	v_add_f32_e32 v81, v81, v80
	v_mul_f32_e32 v80, v113, v113
	v_fmac_f32_e32 v80, v112, v112
	v_fmac_f32_e32 v80, v114, v114
	v_fmac_f32_e32 v80, v115, v115
	v_add_f32_e32 v81, v81, v80
	v_mul_f32_e32 v80, v117, v117
	v_fmac_f32_e32 v80, v116, v116
	v_fmac_f32_e32 v80, v118, v118
	v_fmac_f32_e32 v80, v119, v119
	v_add_f32_e32 v81, v81, v80
	v_mul_f32_e32 v80, v121, v121
	v_fmac_f32_e32 v80, v120, v120
	v_fmac_f32_e32 v80, v122, v122
	v_fmac_f32_e32 v80, v123, v123
	v_add_f32_e32 v81, v81, v80
	v_mul_f32_e32 v80, v125, v125
	v_fmac_f32_e32 v80, v124, v124
	v_fmac_f32_e32 v80, v126, v126
	v_fmac_f32_e32 v80, v127, v127
	v_add_f32_e32 v81, v81, v80
	v_mul_f32_e32 v80, v129, v129
	v_fmac_f32_e32 v80, v128, v128
	v_fmac_f32_e32 v80, v130, v130
	v_fmac_f32_e32 v80, v131, v131
	v_add_f32_e32 v81, v81, v80
	s_waitcnt lgkmcnt(0)
	s_nop 1
	v_add_f32_dpp v81, v81, v81 quad_perm:[1,0,3,2] row_mask:0xf bank_mask:0xf
	s_waitcnt lgkmcnt(0)
	s_nop 1
	v_add_f32_dpp v81, v81, v81 quad_perm:[2,3,0,1] row_mask:0xf bank_mask:0xf
	s_waitcnt lgkmcnt(0)
	s_nop 1
	v_add_f32_dpp v81, v81, v81 row_half_mirror row_mask:0xf bank_mask:0xf
	s_waitcnt lgkmcnt(0)
	s_nop 1
	v_add_f32_dpp v81, v81, v81 row_mirror row_mask:0xf bank_mask:0xf
	s_waitcnt lgkmcnt(0)
	v_mov_b32_e32 v80, v81
	s_nop 1
	v_permlane16_swap_b32_e32 v81, v80
	v_add_f32_e32 v81, v81, v80
	s_waitcnt lgkmcnt(0)
	v_mov_b32_e32 v80, v81
	s_nop 1
	v_permlane32_swap_b32_e32 v81, v80
	v_add_f32_e32 v81, v81, v80
	v_fmamk_f32 v81, v81, 0x3a000000, v179
	v_cmp_gt_f32_e32 vcc, s91, v81
	v_mul_f32_e32 v80, 0x4b800000, v81
	s_nop 0
	v_cndmask_b32_e32 v81, v81, v80, vcc
	v_rsq_f32_e32 v81, v81
	s_nop 0
	v_mul_f32_e32 v80, 0x45800000, v81
	v_cndmask_b32_e32 v82, v81, v80, vcc
	v_mul_f32_e32 v84, v100, v82
	v_mul_f32_e32 v85, v101, v82
	v_mul_f32_e32 v86, v102, v82
	v_mul_f32_e32 v87, v103, v82
	v_mul_f32_e32 v84, v182, v84
	v_mul_f32_e32 v85, v183, v85
	v_mul_f32_e32 v86, v184, v86
	v_mul_f32_e32 v87, v185, v87
	v_fma_f32 v84, v214, v84, v0
	v_fma_f32 v85, v215, v85, v1
	v_fma_f32 v86, v216, v86, v2
	v_fma_f32 v87, v217, v87, v3
	v_bfe_u32 v88, v84, 16, 1
	v_bfe_u32 v89, v85, 16, 1
	v_bfe_u32 v96, v86, 16, 1
	v_bfe_u32 v97, v87, 16, 1
	v_add3_u32 v84, v84, v88, s3
	v_add3_u32 v85, v85, v89, s3
	v_add3_u32 v86, v86, v96, s3
	v_add3_u32 v87, v87, v97, s3
	v_perm_b32 v98, v85, v84, s101
	v_perm_b32 v99, v87, v86, s101
	global_store_dwordx2 v[78:79], v[98:99], off
	v_mul_f32_e32 v84, v104, v82
	v_mul_f32_e32 v85, v105, v82
	v_mul_f32_e32 v86, v106, v82
	v_mul_f32_e32 v87, v107, v82
	v_mul_f32_e32 v84, v186, v84
	v_mul_f32_e32 v85, v187, v85
	v_mul_f32_e32 v86, v188, v86
	v_mul_f32_e32 v87, v189, v87
	v_fma_f32 v84, v218, v84, v4
	v_fma_f32 v85, v219, v85, v5
	v_fma_f32 v86, v220, v86, v6
	v_fma_f32 v87, v221, v87, v7
	v_bfe_u32 v88, v84, 16, 1
	v_bfe_u32 v89, v85, 16, 1
	v_bfe_u32 v96, v86, 16, 1
	v_bfe_u32 v97, v87, 16, 1
	v_add3_u32 v84, v84, v88, s3
	v_add3_u32 v85, v85, v89, s3
	v_add3_u32 v86, v86, v96, s3
	v_add3_u32 v87, v87, v97, s3
	v_perm_b32 v248, v85, v84, s101
	v_perm_b32 v249, v87, v86, s101
	global_store_dwordx2 v[78:79], v[248:249], off offset:512
	v_mul_f32_e32 v84, v108, v82
	v_mul_f32_e32 v85, v109, v82
	v_mul_f32_e32 v86, v110, v82
	v_mul_f32_e32 v87, v111, v82
	v_mul_f32_e32 v84, v190, v84
	v_mul_f32_e32 v85, v191, v85
	v_mul_f32_e32 v86, v192, v86
	v_mul_f32_e32 v87, v193, v87
	v_fma_f32 v84, v222, v84, v8
	v_fma_f32 v85, v223, v85, v9
	v_fma_f32 v86, v224, v86, v10
	v_fma_f32 v87, v225, v87, v11
	v_bfe_u32 v88, v84, 16, 1
	v_bfe_u32 v89, v85, 16, 1
	v_bfe_u32 v96, v86, 16, 1
	v_bfe_u32 v97, v87, 16, 1
	v_add3_u32 v84, v84, v88, s3
; __device__ __forceinline__ unsigned pk2(float lo, float hi) { return f2bf(lo) | (f2bf(hi) << 16); }
; __device__ __forceinline__ void norm_rows(const float* X, const float* nw, const float* md, u16* H, int row0, int nrows, int wave, int lane) {
;     for (int row = row0 + wave; row < row0 + nrows; row += 8) {
;         const float4* xr = (const float4*)(X + (size_t)row * DM) + lane; float4 v[8]; float ss = 0.f;
; #pragma unroll
;         for (int j = 0; j < 8; ++j) { v[j] = xr[64 * j]; ss += v[j].x * v[j].x + v[j].y * v[j].y + v[j].z * v[j].z + v[j].w * v[j].w; }
;         const float r = rsqrtf(wave_sum(ss) * (1.f / DM) + EPS);
;         uint2* hp = (uint2*)(H + (size_t)row * DM) + lane;
; #pragma unroll
;         for (int j = 0; j < 8; ++j) { const int col = 4 * (lane + 64 * j); const float4 w4 = *(const float4*)(nw + col), sc = *(const float4*)(md + 2048 + col), sh = *(const float4*)(md + col);
;             uint2 o; o.x = pk2(v[j].x * r * w4.x * (1.f + sc.x) + sh.x, v[j].y * r * w4.y * (1.f + sc.y) + sh.y);
;             o.y = pk2(v[j].z * r * w4.z * (1.f + sc.z) + sh.z, v[j].w * r * w4.w * (1.f + sc.w) + sh.w); hp[64 * j] = o; } }
	v_add3_u32 v85, v85, v89, s3
	v_add3_u32 v86, v86, v96, s3
	v_add3_u32 v87, v87, v97, s3
	v_perm_b32 v98, v85, v84, s101
	v_perm_b32 v99, v87, v86, s101
	global_store_dwordx2 v[78:79], v[98:99], off offset:1024
	v_mul_f32_e32 v84, v112, v82
	v_mul_f32_e32 v85, v113, v82
	v_mul_f32_e32 v86, v114, v82
	v_mul_f32_e32 v87, v115, v82
	v_mul_f32_e32 v84, v194, v84
	v_mul_f32_e32 v85, v195, v85
	v_mul_f32_e32 v86, v196, v86
	v_mul_f32_e32 v87, v197, v87
	v_fma_f32 v84, v226, v84, v12
	v_fma_f32 v85, v227, v85, v13
	v_fma_f32 v86, v228, v86, v14
	v_fma_f32 v87, v229, v87, v15
	v_bfe_u32 v88, v84, 16, 1
	v_bfe_u32 v89, v85, 16, 1
	v_bfe_u32 v96, v86, 16, 1
	v_bfe_u32 v97, v87, 16, 1
	v_add3_u32 v84, v84, v88, s3
	v_add3_u32 v85, v85, v89, s3
	v_add3_u32 v86, v86, v96, s3
	v_add3_u32 v87, v87, v97, s3
	v_perm_b32 v248, v85, v84, s101
	v_perm_b32 v249, v87, v86, s101
	global_store_dwordx2 v[78:79], v[248:249], off offset:1536
	v_mul_f32_e32 v84, v116, v82
	v_mul_f32_e32 v85, v117, v82
	v_mul_f32_e32 v86, v118, v82
	v_mul_f32_e32 v87, v119, v82
	v_mul_f32_e32 v84, v198, v84
	v_mul_f32_e32 v85, v199, v85
	v_mul_f32_e32 v86, v200, v86
	v_mul_f32_e32 v87, v201, v87
	v_fma_f32 v84, v230, v84, v16
	v_fma_f32 v85, v231, v85, v17
	v_fma_f32 v86, v232, v86, v18
	v_fma_f32 v87, v233, v87, v19
	v_bfe_u32 v88, v84, 16, 1
	v_bfe_u32 v89, v85, 16, 1
	v_bfe_u32 v96, v86, 16, 1
	v_bfe_u32 v97, v87, 16, 1
	v_add3_u32 v84, v84, v88, s3
	v_add3_u32 v85, v85, v89, s3
	v_add3_u32 v86, v86, v96, s3
	v_add3_u32 v87, v87, v97, s3
	v_perm_b32 v98, v85, v84, s101
	v_perm_b32 v99, v87, v86, s101
	global_store_dwordx2 v[78:79], v[98:99], off offset:2048
	v_mul_f32_e32 v84, v120, v82
	v_mul_f32_e32 v85, v121, v82
	v_mul_f32_e32 v86, v122, v82
	v_mul_f32_e32 v87, v123, v82
	v_mul_f32_e32 v84, v202, v84
	v_mul_f32_e32 v85, v203, v85
	v_mul_f32_e32 v86, v204, v86
	v_mul_f32_e32 v87, v205, v87
	v_fma_f32 v84, v234, v84, v20
	v_fma_f32 v85, v235, v85, v21
	v_fma_f32 v86, v236, v86, v22
	v_fma_f32 v87, v237, v87, v23
	v_bfe_u32 v88, v84, 16, 1
	v_bfe_u32 v89, v85, 16, 1
	v_bfe_u32 v96, v86, 16, 1
	v_bfe_u32 v97, v87, 16, 1
	v_add3_u32 v84, v84, v88, s3
	v_add3_u32 v85, v85, v89, s3
	v_add3_u32 v86, v86, v96, s3
	v_add3_u32 v87, v87, v97, s3
	v_perm_b32 v248, v85, v84, s101
	v_perm_b32 v249, v87, v86, s101
	global_store_dwordx2 v[78:79], v[248:249], off offset:2560
	v_mul_f32_e32 v84, v124, v82
	v_mul_f32_e32 v85, v125, v82
	v_mul_f32_e32 v86, v126, v82
	v_mul_f32_e32 v87, v127, v82
	v_mul_f32_e32 v84, v206, v84
	v_mul_f32_e32 v85, v207, v85
	v_mul_f32_e32 v86, v208, v86
	v_mul_f32_e32 v87, v209, v87
	v_fma_f32 v84, v238, v84, v66
	v_fma_f32 v85, v239, v85, v67
	v_fma_f32 v86, v240, v86, v68
	v_fma_f32 v87, v241, v87, v69
	v_bfe_u32 v88, v84, 16, 1
	v_bfe_u32 v89, v85, 16, 1
	v_bfe_u32 v96, v86, 16, 1
	v_bfe_u32 v97, v87, 16, 1
	v_add3_u32 v84, v84, v88, s3
	v_add3_u32 v85, v85, v89, s3
	v_add3_u32 v86, v86, v96, s3
	v_add3_u32 v87, v87, v97, s3
	v_perm_b32 v98, v85, v84, s101
	v_perm_b32 v99, v87, v86, s101
	global_store_dwordx2 v[78:79], v[98:99], off offset:3072
	v_mul_f32_e32 v84, v128, v82
	v_mul_f32_e32 v85, v129, v82
	v_mul_f32_e32 v86, v130, v82
	v_mul_f32_e32 v87, v131, v82
	v_mul_f32_e32 v84, v210, v84
	v_mul_f32_e32 v85, v211, v85
	v_mul_f32_e32 v86, v212, v86
	v_mul_f32_e32 v87, v213, v87
	v_fma_f32 v84, v242, v84, v70
	v_fma_f32 v85, v243, v85, v71
	v_fma_f32 v86, v244, v86, v72
	v_fma_f32 v87, v245, v87, v73
	v_bfe_u32 v88, v84, 16, 1
	v_bfe_u32 v89, v85, 16, 1
	v_bfe_u32 v96, v86, 16, 1
	v_bfe_u32 v97, v87, 16, 1
	v_add3_u32 v84, v84, v88, s3
	v_add3_u32 v85, v85, v89, s3
	v_add3_u32 v86, v86, v96, s3
	v_add3_u32 v87, v87, v97, s3
	v_perm_b32 v248, v85, v84, s101
	v_perm_b32 v249, v87, v86, s101
	global_store_dwordx2 v[78:79], v[248:249], off offset:3584
	v_lshl_add_u64 v[78:79], s[46:47], 0, v[62:63]
	v_add_co_u32_e32 v78, vcc, s13, v78
	s_nop 1
	v_addc_co_u32_e32 v79, vcc, 0, v79, vcc
	s_waitcnt vmcnt(8)
	v_mul_f32_e32 v81, v133, v133
	v_fmac_f32_e32 v81, v132, v132
	v_fmac_f32_e32 v81, v134, v134
	v_fmac_f32_e32 v81, v135, v135
	v_mul_f32_e32 v80, v137, v137
	v_fmac_f32_e32 v80, v136, v136
	v_fmac_f32_e32 v80, v138, v138
	v_fmac_f32_e32 v80, v139, v139
	v_add_f32_e32 v81, v81, v80
	v_mul_f32_e32 v80, v141, v141
	v_fmac_f32_e32 v80, v140, v140
	v_fmac_f32_e32 v80, v142, v142
	v_fmac_f32_e32 v80, v143, v143
	v_add_f32_e32 v81, v81, v80
	v_mul_f32_e32 v80, v145, v145
	v_fmac_f32_e32 v80, v144, v144
	v_fmac_f32_e32 v80, v146, v146
	v_fmac_f32_e32 v80, v147, v147
	v_add_f32_e32 v81, v81, v80
	v_mul_f32_e32 v80, v149, v149
	v_fmac_f32_e32 v80, v148, v148
	v_fmac_f32_e32 v80, v150, v150
	v_fmac_f32_e32 v80, v151, v151
	v_add_f32_e32 v81, v81, v80
	v_mul_f32_e32 v80, v153, v153
	v_fmac_f32_e32 v80, v152, v152
	v_fmac_f32_e32 v80, v154, v154
	v_fmac_f32_e32 v80, v155, v155
	v_add_f32_e32 v81, v81, v80
	v_mul_f32_e32 v80, v157, v157
	v_fmac_f32_e32 v80, v156, v156
	v_fmac_f32_e32 v80, v158, v158
	v_fmac_f32_e32 v80, v159, v159
	v_add_f32_e32 v81, v81, v80
	v_mul_f32_e32 v80, v161, v161
	v_fmac_f32_e32 v80, v160, v160
	v_fmac_f32_e32 v80, v162, v162
	v_fmac_f32_e32 v80, v163, v163
	v_add_f32_e32 v81, v81, v80
	s_waitcnt lgkmcnt(0)
	s_nop 1
	v_add_f32_dpp v81, v81, v81 quad_perm:[1,0,3,2] row_mask:0xf bank_mask:0xf
	s_waitcnt lgkmcnt(0)
	s_nop 1
	v_add_f32_dpp v81, v81, v81 quad_perm:[2,3,0,1] row_mask:0xf bank_mask:0xf
	s_waitcnt lgkmcnt(0)
	s_nop 1
	v_add_f32_dpp v81, v81, v81 row_half_mirror row_mask:0xf bank_mask:0xf
	s_waitcnt lgkmcnt(0)
	s_nop 1
	v_add_f32_dpp v81, v81, v81 row_mirror row_mask:0xf bank_mask:0xf
	s_waitcnt lgkmcnt(0)
; __device__ __forceinline__ unsigned pk2(float lo, float hi) { return f2bf(lo) | (f2bf(hi) << 16); }
; __device__ __forceinline__ void norm_rows(const float* X, const float* nw, const float* md, u16* H, int row0, int nrows, int wave, int lane) {
;     for (int row = row0 + wave; row < row0 + nrows; row += 8) {
;         const float4* xr = (const float4*)(X + (size_t)row * DM) + lane; float4 v[8]; float ss = 0.f;
; #pragma unroll
;         for (int j = 0; j < 8; ++j) { v[j] = xr[64 * j]; ss += v[j].x * v[j].x + v[j].y * v[j].y + v[j].z * v[j].z + v[j].w * v[j].w; }
;         const float r = rsqrtf(wave_sum(ss) * (1.f / DM) + EPS);
;         uint2* hp = (uint2*)(H + (size_t)row * DM) + lane;
; #pragma unroll
;         for (int j = 0; j < 8; ++j) { const int col = 4 * (lane + 64 * j); const float4 w4 = *(const float4*)(nw + col), sc = *(const float4*)(md + 2048 + col), sh = *(const float4*)(md + col);
;             uint2 o; o.x = pk2(v[j].x * r * w4.x * (1.f + sc.x) + sh.x, v[j].y * r * w4.y * (1.f + sc.y) + sh.y);
;             o.y = pk2(v[j].z * r * w4.z * (1.f + sc.z) + sh.z, v[j].w * r * w4.w * (1.f + sc.w) + sh.w); hp[64 * j] = o; } }
	v_mov_b32_e32 v80, v81
	s_nop 1
	v_permlane16_swap_b32_e32 v81, v80
	v_add_f32_e32 v81, v81, v80
	s_waitcnt lgkmcnt(0)
	v_mov_b32_e32 v80, v81
	s_nop 1
	v_permlane32_swap_b32_e32 v81, v80
	v_add_f32_e32 v81, v81, v80
	v_fmamk_f32 v81, v81, 0x3a000000, v179
	v_cmp_gt_f32_e32 vcc, s91, v81
	v_mul_f32_e32 v80, 0x4b800000, v81
	s_nop 0
	v_cndmask_b32_e32 v81, v81, v80, vcc
	v_rsq_f32_e32 v81, v81
	s_nop 0
	v_mul_f32_e32 v80, 0x45800000, v81
	v_cndmask_b32_e32 v82, v81, v80, vcc
	v_mul_f32_e32 v84, v132, v82
	v_mul_f32_e32 v85, v133, v82
	v_mul_f32_e32 v86, v134, v82
	v_mul_f32_e32 v87, v135, v82
	v_mul_f32_e32 v84, v182, v84
	v_mul_f32_e32 v85, v183, v85
	v_mul_f32_e32 v86, v184, v86
	v_mul_f32_e32 v87, v185, v87
	v_fma_f32 v84, v214, v84, v0
	v_fma_f32 v85, v215, v85, v1
	v_fma_f32 v86, v216, v86, v2
	v_fma_f32 v87, v217, v87, v3
	v_bfe_u32 v88, v84, 16, 1
	v_bfe_u32 v89, v85, 16, 1
	v_bfe_u32 v96, v86, 16, 1
	v_bfe_u32 v97, v87, 16, 1
	v_add3_u32 v84, v84, v88, s3
	v_add3_u32 v85, v85, v89, s3
	v_add3_u32 v86, v86, v96, s3
	v_add3_u32 v87, v87, v97, s3
	v_perm_b32 v98, v85, v84, s101
	v_perm_b32 v99, v87, v86, s101
	global_store_dwordx2 v[78:79], v[98:99], off
	v_mul_f32_e32 v84, v136, v82
	v_mul_f32_e32 v85, v137, v82
	v_mul_f32_e32 v86, v138, v82
	v_mul_f32_e32 v87, v139, v82
	v_mul_f32_e32 v84, v186, v84
	v_mul_f32_e32 v85, v187, v85
	v_mul_f32_e32 v86, v188, v86
	v_mul_f32_e32 v87, v189, v87
	v_fma_f32 v84, v218, v84, v4
	v_fma_f32 v85, v219, v85, v5
	v_fma_f32 v86, v220, v86, v6
	v_fma_f32 v87, v221, v87, v7
	v_bfe_u32 v88, v84, 16, 1
	v_bfe_u32 v89, v85, 16, 1
	v_bfe_u32 v96, v86, 16, 1
	v_bfe_u32 v97, v87, 16, 1
	v_add3_u32 v84, v84, v88, s3
	v_add3_u32 v85, v85, v89, s3
	v_add3_u32 v86, v86, v96, s3
	v_add3_u32 v87, v87, v97, s3
	v_perm_b32 v248, v85, v84, s101
	v_perm_b32 v249, v87, v86, s101
	global_store_dwordx2 v[78:79], v[248:249], off offset:512
	v_mul_f32_e32 v84, v140, v82
	v_mul_f32_e32 v85, v141, v82
	v_mul_f32_e32 v86, v142, v82
	v_mul_f32_e32 v87, v143, v82
	v_mul_f32_e32 v84, v190, v84
	v_mul_f32_e32 v85, v191, v85
	v_mul_f32_e32 v86, v192, v86
	v_mul_f32_e32 v87, v193, v87
	v_fma_f32 v84, v222, v84, v8
	v_fma_f32 v85, v223, v85, v9
	v_fma_f32 v86, v224, v86, v10
	v_fma_f32 v87, v225, v87, v11
	v_bfe_u32 v88, v84, 16, 1
	v_bfe_u32 v89, v85, 16, 1
	v_bfe_u32 v96, v86, 16, 1
	v_bfe_u32 v97, v87, 16, 1
	v_add3_u32 v84, v84, v88, s3
	v_add3_u32 v85, v85, v89, s3
	v_add3_u32 v86, v86, v96, s3
	v_add3_u32 v87, v87, v97, s3
	v_perm_b32 v98, v85, v84, s101
	v_perm_b32 v99, v87, v86, s101
	global_store_dwordx2 v[78:79], v[98:99], off offset:1024
	v_mul_f32_e32 v84, v144, v82
	v_mul_f32_e32 v85, v145, v82
	v_mul_f32_e32 v86, v146, v82
	v_mul_f32_e32 v87, v147, v82
	v_mul_f32_e32 v84, v194, v84
	v_mul_f32_e32 v85, v195, v85
	v_mul_f32_e32 v86, v196, v86
	v_mul_f32_e32 v87, v197, v87
	v_fma_f32 v84, v226, v84, v12
	v_fma_f32 v85, v227, v85, v13
	v_fma_f32 v86, v228, v86, v14
	v_fma_f32 v87, v229, v87, v15
	v_bfe_u32 v88, v84, 16, 1
	v_bfe_u32 v89, v85, 16, 1
	v_bfe_u32 v96, v86, 16, 1
	v_bfe_u32 v97, v87, 16, 1
	v_add3_u32 v84, v84, v88, s3
	v_add3_u32 v85, v85, v89, s3
	v_add3_u32 v86, v86, v96, s3
	v_add3_u32 v87, v87, v97, s3
	v_perm_b32 v248, v85, v84, s101
	v_perm_b32 v249, v87, v86, s101
	global_store_dwordx2 v[78:79], v[248:249], off offset:1536
	v_mul_f32_e32 v84, v148, v82
	v_mul_f32_e32 v85, v149, v82
	v_mul_f32_e32 v86, v150, v82
	v_mul_f32_e32 v87, v151, v82
	v_mul_f32_e32 v84, v198, v84
	v_mul_f32_e32 v85, v199, v85
	v_mul_f32_e32 v86, v200, v86
	v_mul_f32_e32 v87, v201, v87
	v_fma_f32 v84, v230, v84, v16
	v_fma_f32 v85, v231, v85, v17
	v_fma_f32 v86, v232, v86, v18
	v_fma_f32 v87, v233, v87, v19
	v_bfe_u32 v88, v84, 16, 1
	v_bfe_u32 v89, v85, 16, 1
	v_bfe_u32 v96, v86, 16, 1
	v_bfe_u32 v97, v87, 16, 1
	v_add3_u32 v84, v84, v88, s3
	v_add3_u32 v85, v85, v89, s3
	v_add3_u32 v86, v86, v96, s3
	v_add3_u32 v87, v87, v97, s3
	v_perm_b32 v98, v85, v84, s101
	v_perm_b32 v99, v87, v86, s101
	global_store_dwordx2 v[78:79], v[98:99], off offset:2048
	v_mul_f32_e32 v84, v152, v82
	v_mul_f32_e32 v85, v153, v82
	v_mul_f32_e32 v86, v154, v82
	v_mul_f32_e32 v87, v155, v82
	v_mul_f32_e32 v84, v202, v84
	v_mul_f32_e32 v85, v203, v85
	v_mul_f32_e32 v86, v204, v86
	v_mul_f32_e32 v87, v205, v87
	v_fma_f32 v84, v234, v84, v20
	v_fma_f32 v85, v235, v85, v21
	v_fma_f32 v86, v236, v86, v22
	v_fma_f32 v87, v237, v87, v23
	v_bfe_u32 v88, v84, 16, 1
	v_bfe_u32 v89, v85, 16, 1
	v_bfe_u32 v96, v86, 16, 1
	v_bfe_u32 v97, v87, 16, 1
	v_add3_u32 v84, v84, v88, s3
	v_add3_u32 v85, v85, v89, s3
	v_add3_u32 v86, v86, v96, s3
	v_add3_u32 v87, v87, v97, s3
	v_perm_b32 v248, v85, v84, s101
	v_perm_b32 v249, v87, v86, s101
	global_store_dwordx2 v[78:79], v[248:249], off offset:2560
	v_mul_f32_e32 v84, v156, v82
	v_mul_f32_e32 v85, v157, v82
	v_mul_f32_e32 v86, v158, v82
	v_mul_f32_e32 v87, v159, v82
	v_mul_f32_e32 v84, v206, v84
	v_mul_f32_e32 v85, v207, v85
	v_mul_f32_e32 v86, v208, v86
	v_mul_f32_e32 v87, v209, v87
	v_fma_f32 v84, v238, v84, v66
	v_fma_f32 v85, v239, v85, v67
	v_fma_f32 v86, v240, v86, v68
	v_fma_f32 v87, v241, v87, v69
	v_bfe_u32 v88, v84, 16, 1
	v_bfe_u32 v89, v85, 16, 1
	v_bfe_u32 v96, v86, 16, 1
	v_bfe_u32 v97, v87, 16, 1
	v_add3_u32 v84, v84, v88, s3
	v_add3_u32 v85, v85, v89, s3
	v_add3_u32 v86, v86, v96, s3
	v_add3_u32 v87, v87, v97, s3
	v_perm_b32 v98, v85, v84, s101
	v_perm_b32 v99, v87, v86, s101
	global_store_dwordx2 v[78:79], v[98:99], off offset:3072
	v_mul_f32_e32 v84, v160, v82
	v_mul_f32_e32 v85, v161, v82
	v_mul_f32_e32 v86, v162, v82
	v_mul_f32_e32 v87, v163, v82
	v_mul_f32_e32 v84, v210, v84
	v_mul_f32_e32 v85, v211, v85
	v_mul_f32_e32 v86, v212, v86
	v_mul_f32_e32 v87, v213, v87
	v_fma_f32 v84, v242, v84, v70
	v_fma_f32 v85, v243, v85, v71
	v_fma_f32 v86, v244, v86, v72
	v_fma_f32 v87, v245, v87, v73
	v_bfe_u32 v88, v84, 16, 1
	v_bfe_u32 v89, v85, 16, 1
	v_bfe_u32 v96, v86, 16, 1
	v_bfe_u32 v97, v87, 16, 1
	v_add3_u32 v84, v84, v88, s3
	v_add3_u32 v85, v85, v89, s3
	v_add3_u32 v86, v86, v96, s3
	v_add3_u32 v87, v87, v97, s3
	v_perm_b32 v248, v85, v84, s101
	v_perm_b32 v249, v87, v86, s101
	global_store_dwordx2 v[78:79], v[248:249], off offset:3584

; __device__ __forceinline__ unsigned pk2(float lo, float hi) { return f2bf(lo) | (f2bf(hi) << 16); }
; #define RETID() do { tid = tidx(); lane = tid & 63; wave = tid >> 6; gw = bid * 8 + wave; } while (0)
; __device__ __forceinline__ void norm_rows(const float* X, const float* nw, const float* md, u16* H, int row0, int nrows, int wave, int lane) {
;     for (int row = row0 + wave; row < row0 + nrows; row += 8) {
;         const float4* xr = (const float4*)(X + (size_t)row * DM) + lane; float4 v[8]; float ss = 0.f;
; #pragma unroll
;         for (int j = 0; j < 8; ++j) { v[j] = xr[64 * j]; ss += v[j].x * v[j].x + v[j].y * v[j].y + v[j].z * v[j].z + v[j].w * v[j].w; }
;         const float r = rsqrtf(wave_sum(ss) * (1.f / DM) + EPS);
;         uint2* hp = (uint2*)(H + (size_t)row * DM) + lane;
; #pragma unroll
;         for (int j = 0; j < 8; ++j) { const int col = 4 * (lane + 64 * j); const float4 w4 = *(const float4*)(nw + col), sc = *(const float4*)(md + 2048 + col), sh = *(const float4*)(md + col);
;             uint2 o; o.x = pk2(v[j].x * r * w4.x * (1.f + sc.x) + sh.x, v[j].y * r * w4.y * (1.f + sc.y) + sh.y);
;             o.y = pk2(v[j].z * r * w4.z * (1.f + sc.z) + sh.z, v[j].w * r * w4.w * (1.f + sc.w) + sh.w); hp[64 * j] = o; } }
; __global__ void __launch_bounds__(512, 2) mega(Params p) {
;     ...
;               if (myslot < 4) { split_wait((unsigned*)(ws + WS_CTL) + CW_SPLIT2 + l * 17 * 64, bst[1], tid); RETID();
;                   norm_rows(X, nw1, mod1 + 6144, H, TL + ((int)xbar.x * 4 + myslot) * 8, 8, wave, lane); } }
.LBB0_1309:
	s_or_b64 exec, exec, s[40:41]
	v_mov_b32_e32 v1, v170
	s_waitcnt lgkmcnt(0)
	s_barrier
	s_nop 0
	v_ashrrev_i32_e32 v0, 6, v1
	v_cmp_gt_i32_e32 vcc, 8, v0
	s_and_saveexec_b64 s[38:39], vcc
	v_readlane_b32 s16, v254, 16
	v_readlane_b32 s20, v254, 20
	v_readlane_b32 s21, v254, 21
	v_readlane_b32 s22, v254, 22
	v_readlane_b32 s23, v254, 23
	v_readlane_b32 s17, v254, 17
	v_readlane_b32 s18, v254, 18
	v_readlane_b32 s19, v254, 19
	s_cbranch_execz .LBB0_1312
	v_cmp_lt_i32_e32 vcc, v178, v172
	s_add_u32 s6, s34, 0x6000
	s_addc_u32 s7, s35, 0
	v_cndmask_b32_e32 v3, v171, v178, vcc
	v_cmp_lt_i32_e32 vcc, v177, v172
	v_lshlrev_b32_e32 v71, 2, v3
	v_and_b32_e32 v1, 63, v1
	v_cndmask_b32_e32 v3, v171, v177, vcc
	v_cmp_lt_i32_e32 vcc, v176, v172
	v_lshlrev_b32_e32 v96, 2, v3
	s_add_u32 s12, s34, 0x8000
	v_cndmask_b32_e32 v3, v171, v176, vcc
	v_lshlrev_b32_e32 v97, 2, v3
	v_xor_b32_e32 v3, 8, v171
	v_cmp_lt_i32_e32 vcc, v3, v172
	v_lshlrev_b32_e32 v164, 4, v1
	s_addc_u32 s13, s35, 0
	v_cndmask_b32_e32 v3, v171, v3, vcc
	v_lshlrev_b32_e32 v98, 2, v3
	v_xor_b32_e32 v3, 16, v171
	v_or_b32_e32 v4, 0x400, v164
	v_mov_b32_e32 v5, v165
	v_cmp_lt_i32_e32 vcc, v3, v172
	v_lshl_add_u64 v[30:31], s[12:13], 0, v[4:5]
	v_lshl_add_u64 v[32:33], s[6:7], 0, v[4:5]
	v_or_b32_e32 v4, 0x800, v164
	v_cndmask_b32_e32 v3, v171, v3, vcc
	v_lshl_add_u64 v[34:35], s[12:13], 0, v[4:5]
	v_lshl_add_u64 v[36:37], s[6:7], 0, v[4:5]
	v_or_b32_e32 v4, 0xc00, v164
	v_lshlrev_b32_e32 v99, 2, v3
	v_xor_b32_e32 v3, 32, v171
	v_lshl_add_u64 v[38:39], s[12:13], 0, v[4:5]
	v_lshl_add_u64 v[40:41], s[6:7], 0, v[4:5]
	v_or_b32_e32 v4, 0x1000, v164
	v_cmp_lt_i32_e32 vcc, v3, v172
	v_lshl_add_u64 v[42:43], s[0:1], 0, v[4:5]
	v_lshl_add_u64 v[44:45], s[12:13], 0, v[4:5]
	v_lshl_add_u64 v[46:47], s[6:7], 0, v[4:5]
	v_or_b32_e32 v4, 0x1400, v164
	v_add_u32_e32 v2, s11, v0
	v_cndmask_b32_e32 v3, v171, v3, vcc
	v_lshl_add_u64 v[48:49], s[0:1], 0, v[4:5]
	v_lshl_add_u64 v[50:51], s[12:13], 0, v[4:5]
	v_lshl_add_u64 v[52:53], s[6:7], 0, v[4:5]
	v_or_b32_e32 v4, 0x1800, v164
	v_lshlrev_b32_e32 v100, 2, v3
	v_lshl_add_u64 v[54:55], s[0:1], 0, v[4:5]
	v_lshl_add_u64 v[56:57], s[12:13], 0, v[4:5]
	v_lshl_add_u64 v[58:59], s[6:7], 0, v[4:5]
	v_or_b32_e32 v4, 0x1c00, v164
	v_ashrrev_i32_e32 v3, 31, v2
	v_lshl_add_u64 v[24:25], s[0:1], 0, v[164:165]
	v_lshl_add_u64 v[60:61], s[0:1], 0, v[4:5]
	v_readlane_b32 s0, v254, 28
	v_lshlrev_b64 v[66:67], 13, v[2:3]
	v_lshlrev_b64 v[68:69], 12, v[2:3]
	s_mov_b64 s[54:55], s[22:23]
	v_lshl_add_u64 v[26:27], s[12:13], 0, v[164:165]
	v_lshl_add_u64 v[28:29], s[6:7], 0, v[164:165]
	v_lshl_add_u64 v[62:63], s[12:13], 0, v[4:5]
	v_lshl_add_u64 v[64:65], s[6:7], 0, v[4:5]
	v_add_u32_e32 v101, s0, v0
	v_or_b32_e32 v66, v66, v164
	v_lshl_or_b32 v68, v1, 3, v68
	s_mov_b64 s[0:1], 0
	s_mov_b64 s[52:53], s[20:21]
	global_load_dwordx4 v[182:185], v[24:25], off
	global_load_dwordx4 v[186:189], v[24:25], off offset:1024
	global_load_dwordx4 v[190:193], v[24:25], off offset:2048
	global_load_dwordx4 v[194:197], v[24:25], off offset:3072
	global_load_dwordx4 v[198:201], v[42:43], off
	global_load_dwordx4 v[202:205], v[48:49], off
	global_load_dwordx4 v[206:209], v[54:55], off
	global_load_dwordx4 v[210:213], v[60:61], off
	global_load_dwordx4 v[214:217], v[26:27], off
	global_load_dwordx4 v[218:221], v[30:31], off
	global_load_dwordx4 v[222:225], v[34:35], off
	global_load_dwordx4 v[226:229], v[38:39], off
	global_load_dwordx4 v[230:233], v[44:45], off
	global_load_dwordx4 v[234:237], v[50:51], off
	global_load_dwordx4 v[238:241], v[56:57], off
	global_load_dwordx4 v[242:245], v[62:63], off
	global_load_dwordx4 v[0:3], v[28:29], off
	global_load_dwordx4 v[4:7], v[32:33], off
	global_load_dwordx4 v[8:11], v[36:37], off
	global_load_dwordx4 v[12:15], v[40:41], off
	global_load_dwordx4 v[16:19], v[46:47], off
	global_load_dwordx4 v[20:23], v[52:53], off
	global_load_dwordx4 v[136:139], v[58:59], off
	global_load_dwordx4 v[140:143], v[64:65], off
	s_mov_b32 s101, 0x7060302
	v_lshl_add_u64 v[74:75], s[54:55], 0, v[66:67]
	v_add_co_u32_e32 v76, vcc, s64, v74
	s_nop 1
	v_addc_co_u32_e32 v77, vcc, 0, v75, vcc
	v_add_co_u32_e32 v74, vcc, 0xa000000, v74
	s_nop 1
	v_addc_co_u32_e32 v75, vcc, 0, v75, vcc
	global_load_dwordx4 v[104:107], v[74:75], off
	global_load_dwordx4 v[108:111], v[74:75], off offset:1024
	global_load_dwordx4 v[112:115], v[74:75], off offset:2048
	global_load_dwordx4 v[116:119], v[74:75], off offset:3072
	global_load_dwordx4 v[120:123], v[76:77], off
	global_load_dwordx4 v[124:127], v[76:77], off offset:1024
	global_load_dwordx4 v[128:131], v[76:77], off offset:2048
	global_load_dwordx4 v[132:135], v[76:77], off offset:3072
	v_lshl_add_u64 v[78:79], s[54:55], 0, v[68:69]
	v_add_co_u32_e32 v78, vcc, s66, v78
	s_nop 1
	v_addc_co_u32_e32 v79, vcc, 0, v79, vcc
	s_waitcnt vmcnt(0)
; __device__ __forceinline__ unsigned pk2(float lo, float hi) { return f2bf(lo) | (f2bf(hi) << 16); }
; __device__ __forceinline__ void norm_rows(const float* X, const float* nw, const float* md, u16* H, int row0, int nrows, int wave, int lane) {
;     for (int row = row0 + wave; row < row0 + nrows; row += 8) {
;         const float4* xr = (const float4*)(X + (size_t)row * DM) + lane; float4 v[8]; float ss = 0.f;
; #pragma unroll
;         for (int j = 0; j < 8; ++j) { v[j] = xr[64 * j]; ss += v[j].x * v[j].x + v[j].y * v[j].y + v[j].z * v[j].z + v[j].w * v[j].w; }
;         const float r = rsqrtf(wave_sum(ss) * (1.f / DM) + EPS);
;         uint2* hp = (uint2*)(H + (size_t)row * DM) + lane;
; #pragma unroll
;         for (int j = 0; j < 8; ++j) { const int col = 4 * (lane + 64 * j); const float4 w4 = *(const float4*)(nw + col), sc = *(const float4*)(md + 2048 + col), sh = *(const float4*)(md + col);
;             uint2 o; o.x = pk2(v[j].x * r * w4.x * (1.f + sc.x) + sh.x, v[j].y * r * w4.y * (1.f + sc.y) + sh.y);
;             o.y = pk2(v[j].z * r * w4.z * (1.f + sc.z) + sh.z, v[j].w * r * w4.w * (1.f + sc.w) + sh.w); hp[64 * j] = o; } }
	v_add_f32_e32 v214, 1.0, v214
	v_add_f32_e32 v215, 1.0, v215
	v_add_f32_e32 v216, 1.0, v216
	v_add_f32_e32 v217, 1.0, v217
	v_add_f32_e32 v218, 1.0, v218
	v_add_f32_e32 v219, 1.0, v219
	v_add_f32_e32 v220, 1.0, v220
	v_add_f32_e32 v221, 1.0, v221
	v_add_f32_e32 v222, 1.0, v222
	v_add_f32_e32 v223, 1.0, v223
	v_add_f32_e32 v224, 1.0, v224
	v_add_f32_e32 v225, 1.0, v225
	v_add_f32_e32 v226, 1.0, v226
	v_add_f32_e32 v227, 1.0, v227
	v_add_f32_e32 v228, 1.0, v228
	v_add_f32_e32 v229, 1.0, v229
	v_add_f32_e32 v230, 1.0, v230
	v_add_f32_e32 v231, 1.0, v231
	v_add_f32_e32 v232, 1.0, v232
	v_add_f32_e32 v233, 1.0, v233
	v_add_f32_e32 v234, 1.0, v234
	v_add_f32_e32 v235, 1.0, v235
	v_add_f32_e32 v236, 1.0, v236
	v_add_f32_e32 v237, 1.0, v237
	v_add_f32_e32 v238, 1.0, v238
	v_add_f32_e32 v239, 1.0, v239
	v_add_f32_e32 v240, 1.0, v240
	v_add_f32_e32 v241, 1.0, v241
	v_add_f32_e32 v242, 1.0, v242
	v_add_f32_e32 v243, 1.0, v243
	v_add_f32_e32 v244, 1.0, v244
	v_add_f32_e32 v245, 1.0, v245
	v_mul_f32_e32 v81, v105, v105
	v_fmac_f32_e32 v81, v104, v104
	v_fmac_f32_e32 v81, v106, v106
	v_fmac_f32_e32 v81, v107, v107
	v_mul_f32_e32 v80, v109, v109
	v_fmac_f32_e32 v80, v108, v108
	v_fmac_f32_e32 v80, v110, v110
	v_fmac_f32_e32 v80, v111, v111
	v_add_f32_e32 v81, v81, v80
	v_mul_f32_e32 v80, v113, v113
	v_fmac_f32_e32 v80, v112, v112
	v_fmac_f32_e32 v80, v114, v114
	v_fmac_f32_e32 v80, v115, v115
	v_add_f32_e32 v81, v81, v80
	v_mul_f32_e32 v80, v117, v117
	v_fmac_f32_e32 v80, v116, v116
	v_fmac_f32_e32 v80, v118, v118
	v_fmac_f32_e32 v80, v119, v119
	v_add_f32_e32 v81, v81, v80
	v_mul_f32_e32 v80, v121, v121
	v_fmac_f32_e32 v80, v120, v120
	v_fmac_f32_e32 v80, v122, v122
	v_fmac_f32_e32 v80, v123, v123
	v_add_f32_e32 v81, v81, v80
	v_mul_f32_e32 v80, v125, v125
	v_fmac_f32_e32 v80, v124, v124
	v_fmac_f32_e32 v80, v126, v126
	v_fmac_f32_e32 v80, v127, v127
	v_add_f32_e32 v81, v81, v80
	v_mul_f32_e32 v80, v129, v129
	v_fmac_f32_e32 v80, v128, v128
	v_fmac_f32_e32 v80, v130, v130
	v_fmac_f32_e32 v80, v131, v131
	v_add_f32_e32 v81, v81, v80
	v_mul_f32_e32 v80, v133, v133
	v_fmac_f32_e32 v80, v132, v132
	v_fmac_f32_e32 v80, v134, v134
	v_fmac_f32_e32 v80, v135, v135
	v_add_f32_e32 v81, v81, v80
	s_waitcnt lgkmcnt(0)
	s_nop 1
	v_add_f32_dpp v81, v81, v81 quad_perm:[1,0,3,2] row_mask:0xf bank_mask:0xf
	s_waitcnt lgkmcnt(0)
	s_nop 1
	v_add_f32_dpp v81, v81, v81 quad_perm:[2,3,0,1] row_mask:0xf bank_mask:0xf
	s_waitcnt lgkmcnt(0)
	s_nop 1
	v_add_f32_dpp v81, v81, v81 row_half_mirror row_mask:0xf bank_mask:0xf
	s_waitcnt lgkmcnt(0)
	s_nop 1
	v_add_f32_dpp v81, v81, v81 row_mirror row_mask:0xf bank_mask:0xf
	s_waitcnt lgkmcnt(0)
	v_mov_b32_e32 v80, v81
	s_nop 1
	v_permlane16_swap_b32_e32 v81, v80
	v_add_f32_e32 v81, v81, v80
	s_waitcnt lgkmcnt(0)
; __device__ __forceinline__ unsigned pk2(float lo, float hi) { return f2bf(lo) | (f2bf(hi) << 16); }
; __device__ __forceinline__ void norm_rows(const float* X, const float* nw, const float* md, u16* H, int row0, int nrows, int wave, int lane) {
;     for (int row = row0 + wave; row < row0 + nrows; row += 8) {
;         const float4* xr = (const float4*)(X + (size_t)row * DM) + lane; float4 v[8]; float ss = 0.f;
; #pragma unroll
;         for (int j = 0; j < 8; ++j) { v[j] = xr[64 * j]; ss += v[j].x * v[j].x + v[j].y * v[j].y + v[j].z * v[j].z + v[j].w * v[j].w; }
;         const float r = rsqrtf(wave_sum(ss) * (1.f / DM) + EPS);
;         uint2* hp = (uint2*)(H + (size_t)row * DM) + lane;
; #pragma unroll
;         for (int j = 0; j < 8; ++j) { const int col = 4 * (lane + 64 * j); const float4 w4 = *(const float4*)(nw + col), sc = *(const float4*)(md + 2048 + col), sh = *(const float4*)(md + col);
;             uint2 o; o.x = pk2(v[j].x * r * w4.x * (1.f + sc.x) + sh.x, v[j].y * r * w4.y * (1.f + sc.y) + sh.y);
;             o.y = pk2(v[j].z * r * w4.z * (1.f + sc.z) + sh.z, v[j].w * r * w4.w * (1.f + sc.w) + sh.w); hp[64 * j] = o; } }
	v_mov_b32_e32 v80, v81
	s_nop 1
	v_permlane32_swap_b32_e32 v81, v80
	v_add_f32_e32 v81, v81, v80
	v_fmamk_f32 v81, v81, 0x3a000000, v179
	v_cmp_gt_f32_e32 vcc, s91, v81
	v_mul_f32_e32 v80, 0x4b800000, v81
	s_nop 0
	v_cndmask_b32_e32 v81, v81, v80, vcc
	v_rsq_f32_e32 v81, v81
	s_nop 0
	v_mul_f32_e32 v80, 0x45800000, v81
	v_cndmask_b32_e32 v82, v81, v80, vcc
	v_mul_f32_e32 v84, v104, v82
	v_mul_f32_e32 v85, v105, v82
	v_mul_f32_e32 v86, v106, v82
	v_mul_f32_e32 v87, v107, v82
	v_mul_f32_e32 v84, v182, v84
	v_mul_f32_e32 v85, v183, v85
	v_mul_f32_e32 v86, v184, v86
	v_mul_f32_e32 v87, v185, v87
	v_fma_f32 v84, v214, v84, v0
	v_fma_f32 v85, v215, v85, v1
	v_fma_f32 v86, v216, v86, v2
	v_fma_f32 v87, v217, v87, v3
	v_bfe_u32 v88, v84, 16, 1
	v_bfe_u32 v89, v85, 16, 1
	v_bfe_u32 v144, v86, 16, 1
	v_bfe_u32 v145, v87, 16, 1
	v_add3_u32 v84, v84, v88, s3
	v_add3_u32 v85, v85, v89, s3
	v_add3_u32 v86, v86, v144, s3
	v_add3_u32 v87, v87, v145, s3
	v_perm_b32 v146, v85, v84, s101
	v_perm_b32 v147, v87, v86, s101
	global_store_dwordx2 v[78:79], v[146:147], off
	v_mul_f32_e32 v84, v108, v82
	v_mul_f32_e32 v85, v109, v82
	v_mul_f32_e32 v86, v110, v82
	v_mul_f32_e32 v87, v111, v82
	v_mul_f32_e32 v84, v186, v84
	v_mul_f32_e32 v85, v187, v85
	v_mul_f32_e32 v86, v188, v86
	v_mul_f32_e32 v87, v189, v87
	v_fma_f32 v84, v218, v84, v4
	v_fma_f32 v85, v219, v85, v5
	v_fma_f32 v86, v220, v86, v6
	v_fma_f32 v87, v221, v87, v7
	v_bfe_u32 v88, v84, 16, 1
	v_bfe_u32 v89, v85, 16, 1
	v_bfe_u32 v144, v86, 16, 1
	v_bfe_u32 v145, v87, 16, 1
	v_add3_u32 v84, v84, v88, s3
	v_add3_u32 v85, v85, v89, s3
	v_add3_u32 v86, v86, v144, s3
	v_add3_u32 v87, v87, v145, s3
	v_perm_b32 v148, v85, v84, s101
	v_perm_b32 v149, v87, v86, s101
	global_store_dwordx2 v[78:79], v[148:149], off offset:512
	v_mul_f32_e32 v84, v112, v82
	v_mul_f32_e32 v85, v113, v82
	v_mul_f32_e32 v86, v114, v82
	v_mul_f32_e32 v87, v115, v82
	v_mul_f32_e32 v84, v190, v84
	v_mul_f32_e32 v85, v191, v85
	v_mul_f32_e32 v86, v192, v86
	v_mul_f32_e32 v87, v193, v87
	v_fma_f32 v84, v222, v84, v8
	v_fma_f32 v85, v223, v85, v9
	v_fma_f32 v86, v224, v86, v10
	v_fma_f32 v87, v225, v87, v11
	v_bfe_u32 v88, v84, 16, 1
	v_bfe_u32 v89, v85, 16, 1
	v_bfe_u32 v144, v86, 16, 1
	v_bfe_u32 v145, v87, 16, 1
	v_add3_u32 v84, v84, v88, s3
	v_add3_u32 v85, v85, v89, s3
	v_add3_u32 v86, v86, v144, s3
	v_add3_u32 v87, v87, v145, s3
	v_perm_b32 v146, v85, v84, s101
	v_perm_b32 v147, v87, v86, s101
	global_store_dwordx2 v[78:79], v[146:147], off offset:1024
	v_mul_f32_e32 v84, v116, v82
	v_mul_f32_e32 v85, v117, v82
	v_mul_f32_e32 v86, v118, v82
	v_mul_f32_e32 v87, v119, v82
	v_mul_f32_e32 v84, v194, v84
	v_mul_f32_e32 v85, v195, v85
	v_mul_f32_e32 v86, v196, v86
	v_mul_f32_e32 v87, v197, v87
	v_fma_f32 v84, v226, v84, v12
	v_fma_f32 v85, v227, v85, v13
	v_fma_f32 v86, v228, v86, v14
	v_fma_f32 v87, v229, v87, v15
	v_bfe_u32 v88, v84, 16, 1
	v_bfe_u32 v89, v85, 16, 1
	v_bfe_u32 v144, v86, 16, 1
	v_bfe_u32 v145, v87, 16, 1
	v_add3_u32 v84, v84, v88, s3
	v_add3_u32 v85, v85, v89, s3
	v_add3_u32 v86, v86, v144, s3
	v_add3_u32 v87, v87, v145, s3
	v_perm_b32 v148, v85, v84, s101
	v_perm_b32 v149, v87, v86, s101
	global_store_dwordx2 v[78:79], v[148:149], off offset:1536
	v_mul_f32_e32 v84, v120, v82
	v_mul_f32_e32 v85, v121, v82
	v_mul_f32_e32 v86, v122, v82
	v_mul_f32_e32 v87, v123, v82
	v_mul_f32_e32 v84, v198, v84
	v_mul_f32_e32 v85, v199, v85
	v_mul_f32_e32 v86, v200, v86
	v_mul_f32_e32 v87, v201, v87
	v_fma_f32 v84, v230, v84, v16
	v_fma_f32 v85, v231, v85, v17
	v_fma_f32 v86, v232, v86, v18
	v_fma_f32 v87, v233, v87, v19
	v_bfe_u32 v88, v84, 16, 1
	v_bfe_u32 v89, v85, 16, 1
	v_bfe_u32 v144, v86, 16, 1
	v_bfe_u32 v145, v87, 16, 1
	v_add3_u32 v84, v84, v88, s3
	v_add3_u32 v85, v85, v89, s3
	v_add3_u32 v86, v86, v144, s3
	v_add3_u32 v87, v87, v145, s3
	v_perm_b32 v146, v85, v84, s101
	v_perm_b32 v147, v87, v86, s101
	global_store_dwordx2 v[78:79], v[146:147], off offset:2048
	v_mul_f32_e32 v84, v124, v82
	v_mul_f32_e32 v85, v125, v82
	v_mul_f32_e32 v86, v126, v82
	v_mul_f32_e32 v87, v127, v82
	v_mul_f32_e32 v84, v202, v84
	v_mul_f32_e32 v85, v203, v85
	v_mul_f32_e32 v86, v204, v86
	v_mul_f32_e32 v87, v205, v87
	v_fma_f32 v84, v234, v84, v20
	v_fma_f32 v85, v235, v85, v21
	v_fma_f32 v86, v236, v86, v22
	v_fma_f32 v87, v237, v87, v23
	v_bfe_u32 v88, v84, 16, 1
	v_bfe_u32 v89, v85, 16, 1
	v_bfe_u32 v144, v86, 16, 1
	v_bfe_u32 v145, v87, 16, 1
	v_add3_u32 v84, v84, v88, s3
	v_add3_u32 v85, v85, v89, s3
	v_add3_u32 v86, v86, v144, s3
	v_add3_u32 v87, v87, v145, s3
	v_perm_b32 v148, v85, v84, s101
	v_perm_b32 v149, v87, v86, s101
	global_store_dwordx2 v[78:79], v[148:149], off offset:2560
	v_mul_f32_e32 v84, v128, v82
	v_mul_f32_e32 v85, v129, v82
	v_mul_f32_e32 v86, v130, v82
	v_mul_f32_e32 v87, v131, v82
	v_mul_f32_e32 v84, v206, v84
	v_mul_f32_e32 v85, v207, v85
	v_mul_f32_e32 v86, v208, v86
	v_mul_f32_e32 v87, v209, v87
	v_fma_f32 v84, v238, v84, v136
	v_fma_f32 v85, v239, v85, v137
	v_fma_f32 v86, v240, v86, v138
	v_fma_f32 v87, v241, v87, v139
	v_bfe_u32 v88, v84, 16, 1
	v_bfe_u32 v89, v85, 16, 1
	v_bfe_u32 v144, v86, 16, 1
	v_bfe_u32 v145, v87, 16, 1
	v_add3_u32 v84, v84, v88, s3
	v_add3_u32 v85, v85, v89, s3
	v_add3_u32 v86, v86, v144, s3
	v_add3_u32 v87, v87, v145, s3
	v_perm_b32 v146, v85, v84, s101
	v_perm_b32 v147, v87, v86, s101
	global_store_dwordx2 v[78:79], v[146:147], off offset:3072
	v_mul_f32_e32 v84, v132, v82
	v_mul_f32_e32 v85, v133, v82
	v_mul_f32_e32 v86, v134, v82
	v_mul_f32_e32 v87, v135, v82
	v_mul_f32_e32 v84, v210, v84
	v_mul_f32_e32 v85, v211, v85
	v_mul_f32_e32 v86, v212, v86
	v_mul_f32_e32 v87, v213, v87
	v_fma_f32 v84, v242, v84, v140
	v_fma_f32 v85, v243, v85, v141
	v_fma_f32 v86, v244, v86, v142
	v_fma_f32 v87, v245, v87, v143
	v_bfe_u32 v88, v84, 16, 1
	v_bfe_u32 v89, v85, 16, 1
	v_bfe_u32 v144, v86, 16, 1
	v_bfe_u32 v145, v87, 16, 1
	v_add3_u32 v84, v84, v88, s3
	v_add3_u32 v85, v85, v89, s3
	v_add3_u32 v86, v86, v144, s3
	v_add3_u32 v87, v87, v145, s3
	v_perm_b32 v148, v85, v84, s101
	v_perm_b32 v149, v87, v86, s101
	global_store_dwordx2 v[78:79], v[148:149], off offset:3584

; __global__ void __launch_bounds__(512, 2) mega(Params p) {
;     ...
;       for (int row = gw; row < TL; row += ngw) {
;           const float4* xr = (const float4*)(X + (size_t)row * DM) + lane; float4 v[8]; float ss = 0.f;
; #pragma unroll
;           for (int j = 0; j < 8; ++j) { v[j] = xr[64 * j]; ss += v[j].x * v[j].x + v[j].y * v[j].y + v[j].z * v[j].z + v[j].w * v[j].w; }
;           const float r = rsqrtf(wave_sum(ss) * (1.f / DM) + EPS);
;           float4* op = (float4*)(p.out + (size_t)row * DM) + lane;
; #pragma unroll
;           for (int j = 0; j < 8; ++j) { const float4 w4 = *(const float4*)(fw + 4 * (lane + 64 * j)); op[64 * j] = make_float4(v[j].x * r * w4.x, v[j].y * r * w4.y, v[j].z * r * w4.z, v[j].w * r * w4.w); } } }
.LBB0_1367:
	v_lshl_add_u64 v[32:33], v[14:15], 0, v[0:1]
	v_add_co_u32_e64 v58, s[0:1], s4, v32
	v_add_co_u32_e32 v56, vcc, 0xa000000, v32
	s_nop 0
	v_addc_co_u32_e64 v59, s[0:1], 0, v33, s[0:1]
	global_load_dwordx4 v[24:27], v[58:59], off
	global_load_dwordx4 v[28:31], v[58:59], off offset:1024
	v_addc_co_u32_e32 v57, vcc, 0, v33, vcc
	global_load_dwordx4 v[32:35], v[58:59], off offset:2048
	global_load_dwordx4 v[36:39], v[56:57], off
	global_load_dwordx4 v[40:43], v[56:57], off offset:1024
	global_load_dwordx4 v[44:47], v[56:57], off offset:2048
	global_load_dwordx4 v[48:51], v[56:57], off offset:3072
	global_load_dwordx4 v[52:55], v[58:59], off offset:3072
	v_lshl_add_u64 v[60:61], v[12:13], 0, v[0:1]
	global_load_dwordx4 v[56:59], v[2:3], off
	v_add_u32_e32 v16, s62, v16
	v_lshl_add_u64 v[12:13], v[12:13], 0, s[8:9]
	v_lshl_add_u64 v[14:15], v[14:15], 0, s[8:9]
	s_waitcnt vmcnt(6)
	v_mov_b32_e32 v72, v33
	v_mov_b32_e32 v64, v25
	v_mov_b32_e32 v65, v29
	v_mov_b32_e32 v62, v24
	v_mov_b32_e32 v63, v28
	s_waitcnt vmcnt(1)
	v_mov_b32_e32 v73, v53
	v_mov_b32_e32 v70, v32
	v_mov_b32_e32 v71, v52
	v_pk_mul_f32 v[78:79], v[36:37], v[36:37]
	v_pk_mul_f32 v[82:83], v[40:41], v[40:41]
	v_pk_mul_f32 v[64:65], v[64:65], v[64:65]
	v_pk_mul_f32 v[72:73], v[72:73], v[72:73]
	v_mov_b32_e32 v66, v26
	v_mov_b32_e32 v67, v30
	v_pk_mul_f32 v[80:81], v[38:39], v[38:39]
	v_pk_mul_f32 v[84:85], v[42:43], v[42:43]
	v_pk_mul_f32 v[86:87], v[44:45], v[44:45]
	v_pk_fma_f32 v[62:63], v[62:63], v[62:63], v[64:65]
	v_pk_fma_f32 v[64:65], v[70:71], v[70:71], v[72:73]
	v_add_f32_e32 v70, v82, v83
	v_add_f32_e32 v71, v78, v79
	v_pk_mul_f32 v[88:89], v[46:47], v[46:47]
	v_pk_mul_f32 v[90:91], v[48:49], v[48:49]
	v_add_f32_e32 v72, v86, v87
	v_pk_fma_f32 v[62:63], v[66:67], v[66:67], v[62:63]
	v_add_f32_e32 v66, v70, v84
	v_add_f32_e32 v67, v71, v80
	v_mov_b32_e32 v68, v27
	v_mov_b32_e32 v69, v31
	v_pk_mul_f32 v[92:93], v[50:51], v[50:51]
	v_add_f32_e32 v73, v90, v91
	v_add_f32_e32 v70, v72, v88
	v_add_f32_e32 v66, v66, v85
	v_add_f32_e32 v67, v67, v81
	v_add_f32_e32 v71, v73, v92
	v_pk_fma_f32 v[62:63], v[68:69], v[68:69], v[62:63]
	v_add_f32_e32 v68, v70, v89
	v_add_f32_e32 v66, v67, v66
	v_add_f32_e32 v69, v71, v93
	v_add_f32_e32 v66, v66, v68
	v_mov_b32_e32 v74, v34
	v_mov_b32_e32 v75, v54
	v_add_f32_e32 v66, v66, v69
	v_mov_b32_e32 v76, v35
	v_mov_b32_e32 v77, v55
	v_pk_fma_f32 v[64:65], v[74:75], v[74:75], v[64:65]
	v_add_f32_e32 v62, v66, v62
	v_pk_fma_f32 v[64:65], v[76:77], v[76:77], v[64:65]
	v_add_f32_e32 v62, v62, v63
	v_add_f32_e32 v62, v62, v64
	v_add_f32_e32 v62, v62, v65
	s_waitcnt lgkmcnt(0)
	s_nop 1
	v_add_f32_dpp v62, v62, v62 quad_perm:[1,0,3,2] row_mask:0xf bank_mask:0xf
	s_waitcnt lgkmcnt(0)
	s_nop 1
	v_add_f32_dpp v62, v62, v62 quad_perm:[2,3,0,1] row_mask:0xf bank_mask:0xf
	s_waitcnt lgkmcnt(0)
	s_nop 1
	v_add_f32_dpp v62, v62, v62 row_half_mirror row_mask:0xf bank_mask:0xf
	s_waitcnt lgkmcnt(0)
	s_nop 1
	v_add_f32_dpp v62, v62, v62 row_mirror row_mask:0xf bank_mask:0xf
	s_waitcnt lgkmcnt(0)
	v_mov_b32_e32 v63, v62
	s_nop 1
	v_permlane16_swap_b32_e32 v62, v63
	v_add_f32_e32 v62, v62, v63
	s_waitcnt lgkmcnt(0)
	v_mov_b32_e32 v63, v62
	s_nop 1
	v_permlane32_swap_b32_e32 v62, v63
	v_add_f32_e32 v62, v62, v63
	v_fmamk_f32 v62, v62, 0x3a000000, v23
	v_mul_f32_e32 v63, 0x4b800000, v62
	v_cmp_gt_f32_e32 vcc, s5, v62
	s_nop 1
	v_cndmask_b32_e32 v62, v62, v63, vcc
	v_rsq_f32_e32 v62, v62
	s_nop 0
	v_mul_f32_e32 v63, 0x45800000, v62
	v_cndmask_b32_e32 v62, v62, v63, vcc
	v_pk_mul_f32 v[36:37], v[62:63], v[36:37] op_sel_hi:[0,1]
	v_pk_mul_f32 v[38:39], v[62:63], v[38:39] op_sel_hi:[0,1]
	s_waitcnt vmcnt(0)
	v_pk_mul_f32 v[36:37], v[56:57], v[36:37]
	v_pk_mul_f32 v[38:39], v[58:59], v[38:39]
	global_store_dwordx4 v[60:61], v[36:39], off
	global_load_dwordx4 v[36:39], v[2:3], off offset:1024
	v_pk_mul_f32 v[40:41], v[62:63], v[40:41] op_sel_hi:[0,1]
	v_pk_mul_f32 v[42:43], v[62:63], v[42:43] op_sel_hi:[0,1]
	v_pk_mul_f32 v[24:25], v[62:63], v[24:25] op_sel_hi:[0,1]
	v_pk_mul_f32 v[26:27], v[62:63], v[26:27] op_sel_hi:[0,1]
	v_pk_mul_f32 v[28:29], v[62:63], v[28:29] op_sel_hi:[0,1]
	v_pk_mul_f32 v[30:31], v[62:63], v[30:31] op_sel_hi:[0,1]
	s_waitcnt vmcnt(0)
	v_pk_mul_f32 v[36:37], v[36:37], v[40:41]
	v_pk_mul_f32 v[38:39], v[38:39], v[42:43]
	global_store_dwordx4 v[60:61], v[36:39], off offset:1024
	global_load_dwordx4 v[36:39], v[2:3], off offset:2048
	v_pk_mul_f32 v[40:41], v[62:63], v[44:45] op_sel_hi:[0,1]
	v_pk_mul_f32 v[42:43], v[62:63], v[46:47] op_sel_hi:[0,1]
	s_waitcnt vmcnt(0)
	v_pk_mul_f32 v[36:37], v[36:37], v[40:41]
	v_pk_mul_f32 v[38:39], v[38:39], v[42:43]
	global_store_dwordx4 v[60:61], v[36:39], off offset:2048
	global_load_dwordx4 v[36:39], v[2:3], off offset:3072
	v_pk_mul_f32 v[40:41], v[62:63], v[48:49] op_sel_hi:[0,1]
	v_pk_mul_f32 v[42:43], v[62:63], v[50:51] op_sel_hi:[0,1]
	s_waitcnt vmcnt(0)
	v_pk_mul_f32 v[36:37], v[36:37], v[40:41]
	v_pk_mul_f32 v[38:39], v[38:39], v[42:43]
	global_store_dwordx4 v[60:61], v[36:39], off offset:3072
	global_load_dwordx4 v[36:39], v[4:5], off
	v_add_co_u32_e32 v40, vcc, s6, v60
	s_waitcnt vmcnt(0)
	v_pk_mul_f32 v[24:25], v[36:37], v[24:25]
	v_addc_co_u32_e32 v41, vcc, 0, v61, vcc
	v_pk_mul_f32 v[26:27], v[38:39], v[26:27]
	global_store_dwordx4 v[40:41], v[24:27], off
	global_load_dwordx4 v[24:27], v[6:7], off
	v_cmp_lt_i32_e32 vcc, s7, v16
	s_or_b64 s[2:3], vcc, s[2:3]
	s_waitcnt vmcnt(0)
	v_pk_mul_f32 v[24:25], v[24:25], v[28:29]
	v_pk_mul_f32 v[26:27], v[26:27], v[30:31]
	global_store_dwordx4 v[40:41], v[24:27], off offset:1024
	global_load_dwordx4 v[24:27], v[8:9], off
	v_pk_mul_f32 v[28:29], v[62:63], v[32:33] op_sel_hi:[0,1]
	v_pk_mul_f32 v[30:31], v[62:63], v[34:35] op_sel_hi:[0,1]
	s_waitcnt vmcnt(0)
	v_pk_mul_f32 v[24:25], v[24:25], v[28:29]
	v_pk_mul_f32 v[26:27], v[26:27], v[30:31]
	global_store_dwordx4 v[40:41], v[24:27], off offset:2048
	global_load_dwordx4 v[24:27], v[10:11], off
	v_pk_mul_f32 v[28:29], v[62:63], v[52:53] op_sel_hi:[0,1]
	v_pk_mul_f32 v[30:31], v[62:63], v[54:55] op_sel_hi:[0,1]
	s_waitcnt vmcnt(0)
	v_pk_mul_f32 v[24:25], v[24:25], v[28:29]
	v_pk_mul_f32 v[26:27], v[26:27], v[30:31]
	global_store_dwordx4 v[40:41], v[24:27], off offset:3072
	s_andn2_b64 exec, exec, s[2:3]
	s_cbranch_execnz .LBB0_1367
